# HGRN update as f*(S-v)+v (no 1-f operand), RET decay-normalised state, LDS-buffered output stores flushed in bursts, raised priority for long scan waves
# speedup vs baseline: 1.0065x; 1.0065x over previous
.Lls3_16_entry:
	v_and_b32_e32 v124, 63, v196
	v_and_b32_e32 v125, 15, v124
	v_lshrrev_b32_e32 v126, 4, v124
	s_min_u32 s29, s0, 4
	s_mul_i32 s29, s29, 0x5600
	v_and_b32_e32 v127, 3, v125
	v_cmp_eq_u32_e64 s[6:7], 1, v127
	v_cmp_eq_u32_e64 s[8:9], 2, v127
	v_cmp_eq_u32_e64 s[10:11], 3, v127
	v_lshl_add_u32 v0, v125, 4, s29
	v_lshl_add_u32 v1, v126, 4, s29
	s_lshl_b32 s37, s16, 11
	v_lshrrev_b32_e32 v125, 3, v124
	v_and_b32_e32 v126, 7, v124
	v_add_u32_e32 v127, s37, v125
	s_lshl_b32 s21, s17, 7
	s_add_u32 s21, s21, 0x10800700
	v_mul_u32_u24_e32 v5, 0xd00, v127
	v_lshl_add_u32 v5, v126, 4, v5
	v_add_u32_e32 v5, s21, v5
	v_lshlrev_b32_e32 v2, 8, v125
	v_lshl_add_u32 v2, v126, 5, v2
	v_add_u32_e32 v2, s29, v2
	v_and_b32_e32 v125, 31, v124
	v_lshrrev_b32_e32 v126, 2, v125
	v_and_b32_e32 v125, 3, v125
	v_add_u32_e32 v127, s37, v126
	s_lshl_b32 s22, s14, 2
	s_lshl_b32 s21, s17, 6
	s_add_u32 s21, s21, s22
	s_lshl_b32 s44, s21, 1
	s_add_u32 s44, s44, 0x10800b00
	v_mul_u32_u24_e32 v6, 0xd00, v127
	s_lshl_b32 s24, s17, 2
	s_add_u32 s24, s24, 0x13e00600
	v_mul_u32_u24_e32 v8, 0x630, v127
	v_lshl_add_u32 v8, v125, 4, v8
	v_add_u32_e32 v8, s24, v8
	v_lshlrev_b32_e32 v4, 6, v126
	v_lshl_add_u32 v4, v125, 4, v4
	v_lshl_add_u32 v6, v125, 1, v6
	v_add_u32_e32 v6, s44, v6
	v_add_u32_e32 v4, s29, v4
	v_and_b32_e32 v125, 15, v124
	v_lshrrev_b32_e32 v126, 4, v124
	v_add_u32_e32 v127, s37, v124
	v_lshlrev_b32_e32 v7, 11, v127
	s_lshl_b32 s44, s21, 1
	s_add_u32 s44, s44, 0x6300600
	v_add_u32_e32 v7, s44, v7
	s_lshl_b32 s44, s28, 3
	s_add_u32 s44, s44, s16
	s_lshl_b32 s44, s44, 2
	s_add_u32 s44, s44, s17
	s_mul_i32 s44, s44, 0x4000
	s_add_u32 s44, s44, 0x4480000
	s_lshl_b32 s24, s22, 2
	s_add_u32 s44, s44, s24
	v_lshlrev_b32_e32 v139, 10, v125
	v_lshl_add_u32 v139, v126, 2, v139
	v_add_u32_e32 v139, s44, v139
	v_readlane_b32 s26, v253, 29
	v_readlane_b32 s27, v253, 30
	v_lshlrev_b32_e32 v140, 3, v125
	v_lshl_add_u32 v140, v126, 1, v140
	v_add_u32_e32 v140, s29, v140
	v_lshl_add_u32 v141, v124, 3, s29
	v_mov_b32_e32 v10, 0
	v_mov_b32_e32 v11, 0
	v_mov_b32_e32 v12, 0
	v_mov_b32_e32 v13, 0
	v_mov_b32_e32 v9, 0
	v_mov_b32_e32 v14, 0
	v_mov_b32_e32 v15, 0
	v_mov_b32_e32 v16, 0
	s_setprio 2
	s_movk_i32 s12, 64
	s_nop 0
	global_load_dwordx4 v[70:73], v5, s[94:95]
	global_load_dwordx4 v[74:77], v5, s[94:95] offset:512
	global_load_ushort v78, v6, s[94:95]
	global_load_dword v79, v8, s[94:95]
	v_add_u32_e32 v5, 0x6800, v5
	v_add_u32_e32 v6, 0x6800, v6
	v_add_u32_e32 v8, 0x3180, v8
	s_waitcnt vmcnt(0)
	s_waitcnt vmcnt(2)
	v_lshlrev_b32_e32 v118, 16, v74
	v_and_b32_e32 v119, 0xffff0000, v74
	v_lshlrev_b32_e32 v120, 16, v75
	v_and_b32_e32 v121, 0xffff0000, v75
	ds_write_b128 v2, v[118:121] offset:0
	v_lshlrev_b32_e32 v124, 16, v76
	v_and_b32_e32 v125, 0xffff0000, v76
	v_lshlrev_b32_e32 v126, 16, v77
	v_and_b32_e32 v127, 0xffff0000, v77
	ds_write_b128 v2, v[124:127] offset:16
	v_lshlrev_b32_e32 v118, 16, v70
	v_and_b32_e32 v119, 0xffff0000, v70
	v_lshlrev_b32_e32 v120, 16, v71
	v_and_b32_e32 v121, 0xffff0000, v71
	ds_write_b128 v2, v[118:121] offset:2048
	v_lshlrev_b32_e32 v124, 16, v72
	v_and_b32_e32 v125, 0xffff0000, v72
	v_lshlrev_b32_e32 v126, 16, v73
	v_and_b32_e32 v127, 0xffff0000, v73
	ds_write_b128 v2, v[124:127] offset:2064
	s_waitcnt vmcnt(0)
	v_mov_b32_dpp v80, v79 quad_perm:[1,1,1,1] row_mask:0xf bank_mask:0xf
	v_mov_b32_dpp v81, v79 quad_perm:[2,2,2,2] row_mask:0xf bank_mask:0xf
	v_mov_b32_dpp v79, v79 quad_perm:[0,0,0,0] row_mask:0xf bank_mask:0xf
	v_lshlrev_b32_e32 v78, 16, v78
	s_nop 0
	ds_write_b128 v4, v[78:81] offset:4096
	global_load_dwordx4 v[82:85], v5, s[94:95]
	global_load_dwordx4 v[86:89], v5, s[94:95] offset:512
	global_load_ushort v90, v6, s[94:95]
	global_load_dword v91, v8, s[94:95]
	v_add_u32_e32 v5, 0x6800, v5
	v_add_u32_e32 v6, 0x6800, v6
	v_add_u32_e32 v8, 0x3180, v8
	global_load_dwordx4 v[94:97], v5, s[94:95]
	global_load_dwordx4 v[98:101], v5, s[94:95] offset:512
	global_load_ushort v102, v6, s[94:95]
	global_load_dword v103, v8, s[94:95]
	v_add_u32_e32 v5, 0x6800, v5
	v_add_u32_e32 v6, 0x6800, v6
	v_add_u32_e32 v8, 0x3180, v8
	global_load_dwordx4 v[106:109], v5, s[94:95]
	global_load_dwordx4 v[110:113], v5, s[94:95] offset:512
	global_load_ushort v114, v6, s[94:95]
	global_load_dword v115, v8, s[94:95]
	v_add_u32_e32 v5, 0x6800, v5
	v_add_u32_e32 v6, 0x6800, v6
	v_add_u32_e32 v8, 0x3180, v8
	global_load_dwordx4 v[70:73], v5, s[94:95]
	global_load_dwordx4 v[74:77], v5, s[94:95] offset:512
	global_load_ushort v78, v6, s[94:95]
	global_load_dword v79, v8, s[94:95]
	v_add_u32_e32 v5, 0x6800, v5
	v_add_u32_e32 v6, 0x6800, v6
	v_add_u32_e32 v8, 0x3180, v8
	ds_read_b128 v[20:23], v0 offset:0
	ds_read_b128 v[38:41], v0 offset:2048
	ds_read_b128 v[54:57], v1 offset:4096
	ds_read_b128 v[24:27], v0 offset:256
	ds_read_b128 v[42:45], v0 offset:2304
	ds_read_b128 v[58:61], v1 offset:4160
	ds_read_b128 v[28:31], v0 offset:512
	ds_read_b128 v[46:49], v0 offset:2560
	ds_read_b128 v[62:65], v1 offset:4224
.Lls3_16_loop:
	s_waitcnt lgkmcnt(6)
	v_mul_f32_e32 v19, v20, v10
	v_mul_f32_e32 v36, v38, v10
	v_fmac_f32_e32 v19, v21, v11
	v_fmac_f32_e32 v36, v39, v11
	v_fmac_f32_e32 v19, v22, v12
	v_fmac_f32_e32 v36, v40, v12
	v_fmac_f32_e32 v19, v23, v13
	v_fmac_f32_e32 v36, v41, v13
	v_mul_f32_e32 v10, v56, v10
	v_mul_f32_e32 v11, v56, v11
	v_add_f32_dpp v19, v19, v19 quad_perm:[1,0,3,2] row_mask:0xf bank_mask:0xf bound_ctrl:1
	v_add_f32_dpp v36, v36, v36 quad_perm:[1,0,3,2] row_mask:0xf bank_mask:0xf bound_ctrl:1
	v_mul_f32_e32 v12, v56, v12
	v_add_f32_dpp v19, v19, v19 quad_perm:[2,3,0,1] row_mask:0xf bank_mask:0xf bound_ctrl:1
	v_add_f32_dpp v36, v36, v36 quad_perm:[2,3,0,1] row_mask:0xf bank_mask:0xf bound_ctrl:1
	v_mul_f32_e32 v13, v56, v13
	v_add_f32_dpp v19, v19, v19 row_half_mirror row_mask:0xf bank_mask:0xf bound_ctrl:1
	v_add_f32_dpp v36, v36, v36 row_half_mirror row_mask:0xf bank_mask:0xf bound_ctrl:1
	s_waitcnt vmcnt(14)
	v_add_f32_dpp v19, v19, v19 row_mirror row_mask:0xf bank_mask:0xf bound_ctrl:1
	v_add_f32_dpp v36, v36, v36 row_mirror row_mask:0xf bank_mask:0xf bound_ctrl:1
	v_fma_f32 v122, -v56, v19, v54
	v_mul_f32_e32 v138, v56, v36
	v_mul_f32_e32 v136, v55, v122
	v_lshlrev_b32_e32 v118, 16, v86
	v_fmac_f32_e32 v10, v20, v136
	v_fmac_f32_e32 v11, v21, v136
	v_fmac_f32_e32 v12, v22, v136
	v_fmac_f32_e32 v13, v23, v136
	v_fmac_f32_e32 v138, v57, v136
	ds_read_b128 v[32:35], v0 offset:768
	ds_read_b128 v[50:53], v0 offset:2816
	ds_read_b128 v[66:69], v1 offset:4288
	v_and_b32_e32 v119, 0xffff0000, v86
	v_lshlrev_b32_e32 v120, 16, v87
	v_and_b32_e32 v121, 0xffff0000, v87
	ds_write_b128 v2, v[118:121] offset:4608
	v_lshlrev_b32_e32 v124, 16, v88
	v_mov_b32_dpp v9, v138 quad_perm:[0,1,2,3] row_mask:0xf bank_mask:0x1
	s_waitcnt lgkmcnt(7)
	v_mul_f32_e32 v19, v24, v10
	v_mul_f32_e32 v36, v42, v10
	v_fmac_f32_e32 v19, v25, v11
	v_fmac_f32_e32 v36, v43, v11
	v_fmac_f32_e32 v19, v26, v12
	v_fmac_f32_e32 v36, v44, v12
	v_fmac_f32_e32 v19, v27, v13
	v_fmac_f32_e32 v36, v45, v13
	v_mul_f32_e32 v10, v60, v10
	v_mul_f32_e32 v11, v60, v11
	v_add_f32_dpp v19, v19, v19 quad_perm:[1,0,3,2] row_mask:0xf bank_mask:0xf bound_ctrl:1
	v_add_f32_dpp v36, v36, v36 quad_perm:[1,0,3,2] row_mask:0xf bank_mask:0xf bound_ctrl:1
	v_mul_f32_e32 v12, v60, v12
	v_add_f32_dpp v19, v19, v19 quad_perm:[2,3,0,1] row_mask:0xf bank_mask:0xf bound_ctrl:1
	v_add_f32_dpp v36, v36, v36 quad_perm:[2,3,0,1] row_mask:0xf bank_mask:0xf bound_ctrl:1
	v_mul_f32_e32 v13, v60, v13
	v_add_f32_dpp v19, v19, v19 row_half_mirror row_mask:0xf bank_mask:0xf bound_ctrl:1
	v_add_f32_dpp v36, v36, v36 row_half_mirror row_mask:0xf bank_mask:0xf bound_ctrl:1
	v_and_b32_e32 v125, 0xffff0000, v88
	v_add_f32_dpp v19, v19, v19 row_mirror row_mask:0xf bank_mask:0xf bound_ctrl:1
	v_add_f32_dpp v36, v36, v36 row_mirror row_mask:0xf bank_mask:0xf bound_ctrl:1
	v_fma_f32 v122, -v60, v19, v58
	v_mul_f32_e32 v138, v60, v36
	v_mul_f32_e32 v136, v59, v122
	v_lshlrev_b32_e32 v126, 16, v89
	v_fmac_f32_e32 v10, v24, v136
	v_fmac_f32_e32 v11, v25, v136
	v_fmac_f32_e32 v12, v26, v136
	v_fmac_f32_e32 v13, v27, v136
	v_fmac_f32_e32 v138, v61, v136
	ds_read_b128 v[20:23], v0 offset:1024
	ds_read_b128 v[38:41], v0 offset:3072
	ds_read_b128 v[54:57], v1 offset:4352
	v_and_b32_e32 v127, 0xffff0000, v89
	ds_write_b128 v2, v[124:127] offset:4624
	v_lshlrev_b32_e32 v118, 16, v82
	v_and_b32_e32 v119, 0xffff0000, v82
	v_lshlrev_b32_e32 v120, 16, v83
	v_mov_b32_dpp v14, v138 quad_perm:[0,1,2,3] row_mask:0xf bank_mask:0x1
	s_waitcnt lgkmcnt(8)
	v_mul_f32_e32 v19, v28, v10
	v_mul_f32_e32 v36, v46, v10
	v_fmac_f32_e32 v19, v29, v11
	v_fmac_f32_e32 v36, v47, v11
	v_fmac_f32_e32 v19, v30, v12
	v_fmac_f32_e32 v36, v48, v12
	v_fmac_f32_e32 v19, v31, v13
	v_fmac_f32_e32 v36, v49, v13
	v_mul_f32_e32 v10, v64, v10
	v_mul_f32_e32 v11, v64, v11
	v_add_f32_dpp v19, v19, v19 quad_perm:[1,0,3,2] row_mask:0xf bank_mask:0xf bound_ctrl:1
	v_add_f32_dpp v36, v36, v36 quad_perm:[1,0,3,2] row_mask:0xf bank_mask:0xf bound_ctrl:1
	v_mul_f32_e32 v12, v64, v12
	v_add_f32_dpp v19, v19, v19 quad_perm:[2,3,0,1] row_mask:0xf bank_mask:0xf bound_ctrl:1
	v_add_f32_dpp v36, v36, v36 quad_perm:[2,3,0,1] row_mask:0xf bank_mask:0xf bound_ctrl:1
	v_mul_f32_e32 v13, v64, v13
	v_add_f32_dpp v19, v19, v19 row_half_mirror row_mask:0xf bank_mask:0xf bound_ctrl:1
	v_add_f32_dpp v36, v36, v36 row_half_mirror row_mask:0xf bank_mask:0xf bound_ctrl:1
	v_and_b32_e32 v121, 0xffff0000, v83
	v_add_f32_dpp v19, v19, v19 row_mirror row_mask:0xf bank_mask:0xf bound_ctrl:1
	v_add_f32_dpp v36, v36, v36 row_mirror row_mask:0xf bank_mask:0xf bound_ctrl:1
	v_fma_f32 v122, -v64, v19, v62
	v_mul_f32_e32 v138, v64, v36
	v_mul_f32_e32 v136, v63, v122
	ds_write_b128 v2, v[118:121] offset:6656
	v_fmac_f32_e32 v10, v28, v136
	v_fmac_f32_e32 v11, v29, v136
	v_fmac_f32_e32 v12, v30, v136
	v_fmac_f32_e32 v13, v31, v136
	v_fmac_f32_e32 v138, v65, v136
	ds_read_b128 v[24:27], v0 offset:1280
	ds_read_b128 v[42:45], v0 offset:3328
	ds_read_b128 v[58:61], v1 offset:4416
	v_lshlrev_b32_e32 v124, 16, v84
	v_and_b32_e32 v125, 0xffff0000, v84
	v_lshlrev_b32_e32 v126, 16, v85
	v_and_b32_e32 v127, 0xffff0000, v85
	ds_write_b128 v2, v[124:127] offset:6672
	v_mov_b32_dpp v15, v138 quad_perm:[0,1,2,3] row_mask:0xf bank_mask:0x1
	s_waitcnt lgkmcnt(10)
	v_mul_f32_e32 v19, v32, v10
	v_mul_f32_e32 v36, v50, v10
	v_fmac_f32_e32 v19, v33, v11
	v_fmac_f32_e32 v36, v51, v11
	v_fmac_f32_e32 v19, v34, v12
	v_fmac_f32_e32 v36, v52, v12
	v_fmac_f32_e32 v19, v35, v13
	v_fmac_f32_e32 v36, v53, v13
	v_mul_f32_e32 v10, v68, v10
	v_mul_f32_e32 v11, v68, v11
	v_add_f32_dpp v19, v19, v19 quad_perm:[1,0,3,2] row_mask:0xf bank_mask:0xf bound_ctrl:1
	v_add_f32_dpp v36, v36, v36 quad_perm:[1,0,3,2] row_mask:0xf bank_mask:0xf bound_ctrl:1
	v_mul_f32_e32 v12, v68, v12
	v_add_f32_dpp v19, v19, v19 quad_perm:[2,3,0,1] row_mask:0xf bank_mask:0xf bound_ctrl:1
	v_add_f32_dpp v36, v36, v36 quad_perm:[2,3,0,1] row_mask:0xf bank_mask:0xf bound_ctrl:1
	v_mul_f32_e32 v13, v68, v13
	v_add_f32_dpp v19, v19, v19 row_half_mirror row_mask:0xf bank_mask:0xf bound_ctrl:1
	v_add_f32_dpp v36, v36, v36 row_half_mirror row_mask:0xf bank_mask:0xf bound_ctrl:1
	s_waitcnt vmcnt(12)
	v_add_f32_dpp v19, v19, v19 row_mirror row_mask:0xf bank_mask:0xf bound_ctrl:1
	v_add_f32_dpp v36, v36, v36 row_mirror row_mask:0xf bank_mask:0xf bound_ctrl:1
	v_fma_f32 v122, -v68, v19, v66
	v_mul_f32_e32 v138, v68, v36
	v_mul_f32_e32 v136, v67, v122
	v_mov_b32_dpp v92, v91 quad_perm:[1,1,1,1] row_mask:0xf bank_mask:0xf
	v_fmac_f32_e32 v10, v32, v136
	v_fmac_f32_e32 v11, v33, v136
	v_fmac_f32_e32 v12, v34, v136
	v_fmac_f32_e32 v13, v35, v136
	v_fmac_f32_e32 v138, v69, v136
	ds_read_b128 v[28:31], v0 offset:1536
	ds_read_b128 v[46:49], v0 offset:3584
	ds_read_b128 v[62:65], v1 offset:4480
	v_mov_b32_dpp v93, v91 quad_perm:[2,2,2,2] row_mask:0xf bank_mask:0xf
	v_mov_b32_dpp v91, v91 quad_perm:[0,0,0,0] row_mask:0xf bank_mask:0xf
	v_lshlrev_b32_e32 v90, 16, v90
	s_nop 0
	ds_write_b128 v4, v[90:93] offset:8704
	v_mov_b32_dpp v16, v138 quad_perm:[0,1,2,3] row_mask:0xf bank_mask:0x1
	s_waitcnt lgkmcnt(10)
	v_mul_f32_e32 v19, v20, v10
	v_mul_f32_e32 v36, v38, v10
	v_fmac_f32_e32 v19, v21, v11
	v_fmac_f32_e32 v36, v39, v11
	v_fmac_f32_e32 v19, v22, v12
	v_fmac_f32_e32 v36, v40, v12
	v_fmac_f32_e32 v19, v23, v13
	v_fmac_f32_e32 v36, v41, v13
	v_mul_f32_e32 v10, v56, v10
	v_mul_f32_e32 v11, v56, v11
	v_add_f32_dpp v19, v19, v19 quad_perm:[1,0,3,2] row_mask:0xf bank_mask:0xf bound_ctrl:1
	v_add_f32_dpp v36, v36, v36 quad_perm:[1,0,3,2] row_mask:0xf bank_mask:0xf bound_ctrl:1
	v_mul_f32_e32 v12, v56, v12
	v_add_f32_dpp v19, v19, v19 quad_perm:[2,3,0,1] row_mask:0xf bank_mask:0xf bound_ctrl:1
	v_add_f32_dpp v36, v36, v36 quad_perm:[2,3,0,1] row_mask:0xf bank_mask:0xf bound_ctrl:1
	v_mul_f32_e32 v13, v56, v13
	v_add_f32_dpp v19, v19, v19 row_half_mirror row_mask:0xf bank_mask:0xf bound_ctrl:1
	v_add_f32_dpp v36, v36, v36 row_half_mirror row_mask:0xf bank_mask:0xf bound_ctrl:1
	global_load_dwordx4 v[82:85], v5, s[94:95]
	global_load_dwordx4 v[86:89], v5, s[94:95] offset:512
	global_load_ushort v90, v6, s[94:95]
	global_load_dword v91, v8, s[94:95]
	v_add_u32_e32 v5, 0x6800, v5
	v_add_u32_e32 v6, 0x6800, v6
	v_add_u32_e32 v8, 0x3180, v8
	v_add_f32_dpp v19, v19, v19 row_mirror row_mask:0xf bank_mask:0xf bound_ctrl:1
	v_add_f32_dpp v36, v36, v36 row_mirror row_mask:0xf bank_mask:0xf bound_ctrl:1
	v_fma_f32 v122, -v56, v19, v54
	v_mul_f32_e32 v138, v56, v36
	v_mul_f32_e32 v136, v55, v122
	ds_read_b128 v[32:35], v0 offset:1792
	v_fmac_f32_e32 v10, v20, v136
	v_fmac_f32_e32 v11, v21, v136
	v_fmac_f32_e32 v12, v22, v136
	v_fmac_f32_e32 v13, v23, v136
	v_fmac_f32_e32 v138, v57, v136
	ds_read_b128 v[50:53], v0 offset:3840
	ds_read_b128 v[66:69], v1 offset:4544
	v_mov_b32_dpp v9, v138 quad_perm:[0,1,2,3] row_mask:0xf bank_mask:0x2
	s_waitcnt lgkmcnt(8)
	v_mul_f32_e32 v19, v24, v10
	v_mul_f32_e32 v36, v42, v10
	v_fmac_f32_e32 v19, v25, v11
	v_fmac_f32_e32 v36, v43, v11
	v_fmac_f32_e32 v19, v26, v12
	v_fmac_f32_e32 v36, v44, v12
	v_fmac_f32_e32 v19, v27, v13
	v_fmac_f32_e32 v36, v45, v13
	v_mul_f32_e32 v10, v60, v10
	v_mul_f32_e32 v11, v60, v11
	v_add_f32_dpp v19, v19, v19 quad_perm:[1,0,3,2] row_mask:0xf bank_mask:0xf bound_ctrl:1
	v_add_f32_dpp v36, v36, v36 quad_perm:[1,0,3,2] row_mask:0xf bank_mask:0xf bound_ctrl:1
	v_mul_f32_e32 v12, v60, v12
	v_add_f32_dpp v19, v19, v19 quad_perm:[2,3,0,1] row_mask:0xf bank_mask:0xf bound_ctrl:1
	v_add_f32_dpp v36, v36, v36 quad_perm:[2,3,0,1] row_mask:0xf bank_mask:0xf bound_ctrl:1
	v_mul_f32_e32 v13, v60, v13
	v_add_f32_dpp v19, v19, v19 row_half_mirror row_mask:0xf bank_mask:0xf bound_ctrl:1
	v_add_f32_dpp v36, v36, v36 row_half_mirror row_mask:0xf bank_mask:0xf bound_ctrl:1
	ds_read_b128 v[20:23], v0 offset:4608
	v_add_f32_dpp v19, v19, v19 row_mirror row_mask:0xf bank_mask:0xf bound_ctrl:1
	v_add_f32_dpp v36, v36, v36 row_mirror row_mask:0xf bank_mask:0xf bound_ctrl:1
	v_fma_f32 v122, -v60, v19, v58
	v_mul_f32_e32 v138, v60, v36
	v_mul_f32_e32 v136, v59, v122
	ds_read_b128 v[38:41], v0 offset:6656
	v_fmac_f32_e32 v10, v24, v136
	v_fmac_f32_e32 v11, v25, v136
	v_fmac_f32_e32 v12, v26, v136
	v_fmac_f32_e32 v13, v27, v136
	v_fmac_f32_e32 v138, v61, v136
	ds_read_b128 v[54:57], v1 offset:8704
	s_nop 0
	v_mov_b32_dpp v14, v138 quad_perm:[0,1,2,3] row_mask:0xf bank_mask:0x2
	s_waitcnt lgkmcnt(7)
	v_mul_f32_e32 v19, v28, v10
	v_mul_f32_e32 v36, v46, v10
	v_fmac_f32_e32 v19, v29, v11
	v_fmac_f32_e32 v36, v47, v11
	v_fmac_f32_e32 v19, v30, v12
	v_fmac_f32_e32 v36, v48, v12
	v_fmac_f32_e32 v19, v31, v13
	v_fmac_f32_e32 v36, v49, v13
	v_mul_f32_e32 v10, v64, v10
	v_mul_f32_e32 v11, v64, v11
	v_add_f32_dpp v19, v19, v19 quad_perm:[1,0,3,2] row_mask:0xf bank_mask:0xf bound_ctrl:1
	v_add_f32_dpp v36, v36, v36 quad_perm:[1,0,3,2] row_mask:0xf bank_mask:0xf bound_ctrl:1
	v_mul_f32_e32 v12, v64, v12
	v_add_f32_dpp v19, v19, v19 quad_perm:[2,3,0,1] row_mask:0xf bank_mask:0xf bound_ctrl:1
	v_add_f32_dpp v36, v36, v36 quad_perm:[2,3,0,1] row_mask:0xf bank_mask:0xf bound_ctrl:1
	v_mul_f32_e32 v13, v64, v13
	v_add_f32_dpp v19, v19, v19 row_half_mirror row_mask:0xf bank_mask:0xf bound_ctrl:1
	v_add_f32_dpp v36, v36, v36 row_half_mirror row_mask:0xf bank_mask:0xf bound_ctrl:1
	ds_read_b128 v[24:27], v0 offset:4864
	v_add_f32_dpp v19, v19, v19 row_mirror row_mask:0xf bank_mask:0xf bound_ctrl:1
	v_add_f32_dpp v36, v36, v36 row_mirror row_mask:0xf bank_mask:0xf bound_ctrl:1
	v_fma_f32 v122, -v64, v19, v62
	v_mul_f32_e32 v138, v64, v36
	v_mul_f32_e32 v136, v63, v122
	ds_read_b128 v[42:45], v0 offset:6912
	v_fmac_f32_e32 v10, v28, v136
	v_fmac_f32_e32 v11, v29, v136
	v_fmac_f32_e32 v12, v30, v136
	v_fmac_f32_e32 v13, v31, v136
	v_fmac_f32_e32 v138, v65, v136
	ds_read_b128 v[58:61], v1 offset:8768
	s_nop 0
	v_mov_b32_dpp v15, v138 quad_perm:[0,1,2,3] row_mask:0xf bank_mask:0x2
	s_waitcnt lgkmcnt(6)
	v_mul_f32_e32 v19, v32, v10
	v_mul_f32_e32 v36, v50, v10
	v_fmac_f32_e32 v19, v33, v11
	v_fmac_f32_e32 v36, v51, v11
	v_fmac_f32_e32 v19, v34, v12
	v_fmac_f32_e32 v36, v52, v12
	v_fmac_f32_e32 v19, v35, v13
	v_fmac_f32_e32 v36, v53, v13
	v_mul_f32_e32 v10, v68, v10
	v_mul_f32_e32 v11, v68, v11
	v_add_f32_dpp v19, v19, v19 quad_perm:[1,0,3,2] row_mask:0xf bank_mask:0xf bound_ctrl:1
	v_add_f32_dpp v36, v36, v36 quad_perm:[1,0,3,2] row_mask:0xf bank_mask:0xf bound_ctrl:1
	v_mul_f32_e32 v12, v68, v12
	v_add_f32_dpp v19, v19, v19 quad_perm:[2,3,0,1] row_mask:0xf bank_mask:0xf bound_ctrl:1
	v_add_f32_dpp v36, v36, v36 quad_perm:[2,3,0,1] row_mask:0xf bank_mask:0xf bound_ctrl:1
	v_mul_f32_e32 v13, v68, v13
	v_add_f32_dpp v19, v19, v19 row_half_mirror row_mask:0xf bank_mask:0xf bound_ctrl:1
	v_add_f32_dpp v36, v36, v36 row_half_mirror row_mask:0xf bank_mask:0xf bound_ctrl:1
	ds_read_b128 v[28:31], v0 offset:5120
	v_add_f32_dpp v19, v19, v19 row_mirror row_mask:0xf bank_mask:0xf bound_ctrl:1
	v_add_f32_dpp v36, v36, v36 row_mirror row_mask:0xf bank_mask:0xf bound_ctrl:1
	v_fma_f32 v122, -v68, v19, v66
	v_mul_f32_e32 v138, v68, v36
	v_mul_f32_e32 v136, v67, v122
	ds_read_b128 v[46:49], v0 offset:7168
	v_fmac_f32_e32 v10, v32, v136
	v_fmac_f32_e32 v11, v33, v136
	v_fmac_f32_e32 v12, v34, v136
	v_fmac_f32_e32 v13, v35, v136
	v_fmac_f32_e32 v138, v69, v136
	ds_read_b128 v[62:65], v1 offset:8832
	s_nop 0
	v_mov_b32_dpp v16, v138 quad_perm:[0,1,2,3] row_mask:0xf bank_mask:0x2
	s_waitcnt lgkmcnt(6)
	v_mul_f32_e32 v19, v20, v10
	v_mul_f32_e32 v36, v38, v10
	v_fmac_f32_e32 v19, v21, v11
	v_fmac_f32_e32 v36, v39, v11
	v_fmac_f32_e32 v19, v22, v12
	v_fmac_f32_e32 v36, v40, v12
	v_fmac_f32_e32 v19, v23, v13
	v_fmac_f32_e32 v36, v41, v13
	v_mul_f32_e32 v10, v56, v10
	v_mul_f32_e32 v11, v56, v11
	v_add_f32_dpp v19, v19, v19 quad_perm:[1,0,3,2] row_mask:0xf bank_mask:0xf bound_ctrl:1
	v_add_f32_dpp v36, v36, v36 quad_perm:[1,0,3,2] row_mask:0xf bank_mask:0xf bound_ctrl:1
	v_mul_f32_e32 v12, v56, v12
	v_add_f32_dpp v19, v19, v19 quad_perm:[2,3,0,1] row_mask:0xf bank_mask:0xf bound_ctrl:1
	v_add_f32_dpp v36, v36, v36 quad_perm:[2,3,0,1] row_mask:0xf bank_mask:0xf bound_ctrl:1
	v_mul_f32_e32 v13, v56, v13
	v_add_f32_dpp v19, v19, v19 row_half_mirror row_mask:0xf bank_mask:0xf bound_ctrl:1
	v_add_f32_dpp v36, v36, v36 row_half_mirror row_mask:0xf bank_mask:0xf bound_ctrl:1
	s_waitcnt vmcnt(14)
	v_add_f32_dpp v19, v19, v19 row_mirror row_mask:0xf bank_mask:0xf bound_ctrl:1
	v_add_f32_dpp v36, v36, v36 row_mirror row_mask:0xf bank_mask:0xf bound_ctrl:1
	v_fma_f32 v122, -v56, v19, v54
	v_mul_f32_e32 v138, v56, v36
	v_mul_f32_e32 v136, v55, v122
	v_lshlrev_b32_e32 v118, 16, v98
	v_fmac_f32_e32 v10, v20, v136
	v_fmac_f32_e32 v11, v21, v136
	v_fmac_f32_e32 v12, v22, v136
	v_fmac_f32_e32 v13, v23, v136
	v_fmac_f32_e32 v138, v57, v136
	ds_read_b128 v[32:35], v0 offset:5376
	ds_read_b128 v[50:53], v0 offset:7424
	ds_read_b128 v[66:69], v1 offset:8896
	v_and_b32_e32 v119, 0xffff0000, v98
	v_lshlrev_b32_e32 v120, 16, v99
	v_and_b32_e32 v121, 0xffff0000, v99
	ds_write_b128 v2, v[118:121] offset:0
	v_lshlrev_b32_e32 v124, 16, v100
	v_mov_b32_dpp v9, v138 quad_perm:[0,1,2,3] row_mask:0xf bank_mask:0x4
	s_waitcnt lgkmcnt(7)
	v_mul_f32_e32 v19, v24, v10
	v_mul_f32_e32 v36, v42, v10
	v_fmac_f32_e32 v19, v25, v11
	v_fmac_f32_e32 v36, v43, v11
	v_fmac_f32_e32 v19, v26, v12
	v_fmac_f32_e32 v36, v44, v12
	v_fmac_f32_e32 v19, v27, v13
	v_fmac_f32_e32 v36, v45, v13
	v_mul_f32_e32 v10, v60, v10
	v_mul_f32_e32 v11, v60, v11
	v_add_f32_dpp v19, v19, v19 quad_perm:[1,0,3,2] row_mask:0xf bank_mask:0xf bound_ctrl:1
	v_add_f32_dpp v36, v36, v36 quad_perm:[1,0,3,2] row_mask:0xf bank_mask:0xf bound_ctrl:1
	v_mul_f32_e32 v12, v60, v12
	v_add_f32_dpp v19, v19, v19 quad_perm:[2,3,0,1] row_mask:0xf bank_mask:0xf bound_ctrl:1
	v_add_f32_dpp v36, v36, v36 quad_perm:[2,3,0,1] row_mask:0xf bank_mask:0xf bound_ctrl:1
	v_mul_f32_e32 v13, v60, v13
	v_add_f32_dpp v19, v19, v19 row_half_mirror row_mask:0xf bank_mask:0xf bound_ctrl:1
	v_add_f32_dpp v36, v36, v36 row_half_mirror row_mask:0xf bank_mask:0xf bound_ctrl:1
	v_and_b32_e32 v125, 0xffff0000, v100
	v_add_f32_dpp v19, v19, v19 row_mirror row_mask:0xf bank_mask:0xf bound_ctrl:1
	v_add_f32_dpp v36, v36, v36 row_mirror row_mask:0xf bank_mask:0xf bound_ctrl:1
	v_fma_f32 v122, -v60, v19, v58
	v_mul_f32_e32 v138, v60, v36
	v_mul_f32_e32 v136, v59, v122
	v_lshlrev_b32_e32 v126, 16, v101
	v_fmac_f32_e32 v10, v24, v136
	v_fmac_f32_e32 v11, v25, v136
	v_fmac_f32_e32 v12, v26, v136
	v_fmac_f32_e32 v13, v27, v136
	v_fmac_f32_e32 v138, v61, v136
	ds_read_b128 v[20:23], v0 offset:5632
	ds_read_b128 v[38:41], v0 offset:7680
	ds_read_b128 v[54:57], v1 offset:8960
	v_and_b32_e32 v127, 0xffff0000, v101
	ds_write_b128 v2, v[124:127] offset:16
	v_lshlrev_b32_e32 v118, 16, v94
	v_and_b32_e32 v119, 0xffff0000, v94
	v_lshlrev_b32_e32 v120, 16, v95
	v_mov_b32_dpp v14, v138 quad_perm:[0,1,2,3] row_mask:0xf bank_mask:0x4
	s_waitcnt lgkmcnt(8)
	v_mul_f32_e32 v19, v28, v10
	v_mul_f32_e32 v36, v46, v10
	v_fmac_f32_e32 v19, v29, v11
	v_fmac_f32_e32 v36, v47, v11
	v_fmac_f32_e32 v19, v30, v12
	v_fmac_f32_e32 v36, v48, v12
	v_fmac_f32_e32 v19, v31, v13
	v_fmac_f32_e32 v36, v49, v13
	v_mul_f32_e32 v10, v64, v10
	v_mul_f32_e32 v11, v64, v11
	v_add_f32_dpp v19, v19, v19 quad_perm:[1,0,3,2] row_mask:0xf bank_mask:0xf bound_ctrl:1
	v_add_f32_dpp v36, v36, v36 quad_perm:[1,0,3,2] row_mask:0xf bank_mask:0xf bound_ctrl:1
	v_mul_f32_e32 v12, v64, v12
	v_add_f32_dpp v19, v19, v19 quad_perm:[2,3,0,1] row_mask:0xf bank_mask:0xf bound_ctrl:1
	v_add_f32_dpp v36, v36, v36 quad_perm:[2,3,0,1] row_mask:0xf bank_mask:0xf bound_ctrl:1
	v_mul_f32_e32 v13, v64, v13
	v_add_f32_dpp v19, v19, v19 row_half_mirror row_mask:0xf bank_mask:0xf bound_ctrl:1
	v_add_f32_dpp v36, v36, v36 row_half_mirror row_mask:0xf bank_mask:0xf bound_ctrl:1
	v_and_b32_e32 v121, 0xffff0000, v95
	v_add_f32_dpp v19, v19, v19 row_mirror row_mask:0xf bank_mask:0xf bound_ctrl:1
	v_add_f32_dpp v36, v36, v36 row_mirror row_mask:0xf bank_mask:0xf bound_ctrl:1
	v_fma_f32 v122, -v64, v19, v62
	v_mul_f32_e32 v138, v64, v36
	v_mul_f32_e32 v136, v63, v122
	ds_write_b128 v2, v[118:121] offset:2048
	v_fmac_f32_e32 v10, v28, v136
	v_fmac_f32_e32 v11, v29, v136
	v_fmac_f32_e32 v12, v30, v136
	v_fmac_f32_e32 v13, v31, v136
	v_fmac_f32_e32 v138, v65, v136
	ds_read_b128 v[24:27], v0 offset:5888
	ds_read_b128 v[42:45], v0 offset:7936
	ds_read_b128 v[58:61], v1 offset:9024
	v_lshlrev_b32_e32 v124, 16, v96
	v_and_b32_e32 v125, 0xffff0000, v96
	v_lshlrev_b32_e32 v126, 16, v97
	v_and_b32_e32 v127, 0xffff0000, v97
	ds_write_b128 v2, v[124:127] offset:2064
	v_mov_b32_dpp v15, v138 quad_perm:[0,1,2,3] row_mask:0xf bank_mask:0x4
	s_waitcnt lgkmcnt(10)
	v_mul_f32_e32 v19, v32, v10
	v_mul_f32_e32 v36, v50, v10
	v_fmac_f32_e32 v19, v33, v11
	v_fmac_f32_e32 v36, v51, v11
	v_fmac_f32_e32 v19, v34, v12
	v_fmac_f32_e32 v36, v52, v12
	v_fmac_f32_e32 v19, v35, v13
	v_fmac_f32_e32 v36, v53, v13
	v_mul_f32_e32 v10, v68, v10
	v_mul_f32_e32 v11, v68, v11
	v_add_f32_dpp v19, v19, v19 quad_perm:[1,0,3,2] row_mask:0xf bank_mask:0xf bound_ctrl:1
	v_add_f32_dpp v36, v36, v36 quad_perm:[1,0,3,2] row_mask:0xf bank_mask:0xf bound_ctrl:1
	v_mul_f32_e32 v12, v68, v12
	v_add_f32_dpp v19, v19, v19 quad_perm:[2,3,0,1] row_mask:0xf bank_mask:0xf bound_ctrl:1
	v_add_f32_dpp v36, v36, v36 quad_perm:[2,3,0,1] row_mask:0xf bank_mask:0xf bound_ctrl:1
	v_mul_f32_e32 v13, v68, v13
	v_add_f32_dpp v19, v19, v19 row_half_mirror row_mask:0xf bank_mask:0xf bound_ctrl:1
	v_add_f32_dpp v36, v36, v36 row_half_mirror row_mask:0xf bank_mask:0xf bound_ctrl:1
	s_waitcnt vmcnt(12)
	v_add_f32_dpp v19, v19, v19 row_mirror row_mask:0xf bank_mask:0xf bound_ctrl:1
	v_add_f32_dpp v36, v36, v36 row_mirror row_mask:0xf bank_mask:0xf bound_ctrl:1
	v_fma_f32 v122, -v68, v19, v66
	v_mul_f32_e32 v138, v68, v36
	v_mul_f32_e32 v136, v67, v122
	v_mov_b32_dpp v104, v103 quad_perm:[1,1,1,1] row_mask:0xf bank_mask:0xf
	v_fmac_f32_e32 v10, v32, v136
	v_fmac_f32_e32 v11, v33, v136
	v_fmac_f32_e32 v12, v34, v136
	v_fmac_f32_e32 v13, v35, v136
	v_fmac_f32_e32 v138, v69, v136
	ds_read_b128 v[28:31], v0 offset:6144
	ds_read_b128 v[46:49], v0 offset:8192
	ds_read_b128 v[62:65], v1 offset:9088
	v_mov_b32_dpp v105, v103 quad_perm:[2,2,2,2] row_mask:0xf bank_mask:0xf
	v_mov_b32_dpp v103, v103 quad_perm:[0,0,0,0] row_mask:0xf bank_mask:0xf
	v_lshlrev_b32_e32 v102, 16, v102
	s_nop 0
	ds_write_b128 v4, v[102:105] offset:4096
	v_mov_b32_dpp v16, v138 quad_perm:[0,1,2,3] row_mask:0xf bank_mask:0x4
	s_waitcnt lgkmcnt(10)
	v_mul_f32_e32 v19, v20, v10
	v_mul_f32_e32 v36, v38, v10
	v_fmac_f32_e32 v19, v21, v11
	v_fmac_f32_e32 v36, v39, v11
	v_fmac_f32_e32 v19, v22, v12
	v_fmac_f32_e32 v36, v40, v12
	v_fmac_f32_e32 v19, v23, v13
	v_fmac_f32_e32 v36, v41, v13
	v_mul_f32_e32 v10, v56, v10
	v_mul_f32_e32 v11, v56, v11
	v_add_f32_dpp v19, v19, v19 quad_perm:[1,0,3,2] row_mask:0xf bank_mask:0xf bound_ctrl:1
	v_add_f32_dpp v36, v36, v36 quad_perm:[1,0,3,2] row_mask:0xf bank_mask:0xf bound_ctrl:1
	v_mul_f32_e32 v12, v56, v12
	v_add_f32_dpp v19, v19, v19 quad_perm:[2,3,0,1] row_mask:0xf bank_mask:0xf bound_ctrl:1
	v_add_f32_dpp v36, v36, v36 quad_perm:[2,3,0,1] row_mask:0xf bank_mask:0xf bound_ctrl:1
	v_mul_f32_e32 v13, v56, v13
	v_add_f32_dpp v19, v19, v19 row_half_mirror row_mask:0xf bank_mask:0xf bound_ctrl:1
	v_add_f32_dpp v36, v36, v36 row_half_mirror row_mask:0xf bank_mask:0xf bound_ctrl:1
	global_load_dwordx4 v[94:97], v5, s[94:95]
	global_load_dwordx4 v[98:101], v5, s[94:95] offset:512
	global_load_ushort v102, v6, s[94:95]
	global_load_dword v103, v8, s[94:95]
	v_add_u32_e32 v5, 0x6800, v5
	v_add_u32_e32 v6, 0x6800, v6
	v_add_u32_e32 v8, 0x3180, v8
	v_add_f32_dpp v19, v19, v19 row_mirror row_mask:0xf bank_mask:0xf bound_ctrl:1
	v_add_f32_dpp v36, v36, v36 row_mirror row_mask:0xf bank_mask:0xf bound_ctrl:1
	v_fma_f32 v122, -v56, v19, v54
	v_mul_f32_e32 v138, v56, v36
	v_mul_f32_e32 v136, v55, v122
	ds_read_b128 v[32:35], v0 offset:6400
	v_fmac_f32_e32 v10, v20, v136
	v_fmac_f32_e32 v11, v21, v136
	v_fmac_f32_e32 v12, v22, v136
	v_fmac_f32_e32 v13, v23, v136
	v_fmac_f32_e32 v138, v57, v136
	ds_read_b128 v[50:53], v0 offset:8448
	ds_read_b128 v[66:69], v1 offset:9152
	v_mov_b32_dpp v9, v138 quad_perm:[0,1,2,3] row_mask:0xf bank_mask:0x8
	s_waitcnt lgkmcnt(8)
	v_mul_f32_e32 v19, v24, v10
	v_mul_f32_e32 v36, v42, v10
	v_fmac_f32_e32 v19, v25, v11
	v_fmac_f32_e32 v36, v43, v11
	v_fmac_f32_e32 v19, v26, v12
	v_fmac_f32_e32 v36, v44, v12
	v_fmac_f32_e32 v19, v27, v13
	v_fmac_f32_e32 v36, v45, v13
	v_mul_f32_e32 v10, v60, v10
	v_mul_f32_e32 v11, v60, v11
	v_add_f32_dpp v19, v19, v19 quad_perm:[1,0,3,2] row_mask:0xf bank_mask:0xf bound_ctrl:1
	v_add_f32_dpp v36, v36, v36 quad_perm:[1,0,3,2] row_mask:0xf bank_mask:0xf bound_ctrl:1
	v_mul_f32_e32 v12, v60, v12
	v_add_f32_dpp v19, v19, v19 quad_perm:[2,3,0,1] row_mask:0xf bank_mask:0xf bound_ctrl:1
	v_add_f32_dpp v36, v36, v36 quad_perm:[2,3,0,1] row_mask:0xf bank_mask:0xf bound_ctrl:1
	v_mul_f32_e32 v13, v60, v13
	v_add_f32_dpp v19, v19, v19 row_half_mirror row_mask:0xf bank_mask:0xf bound_ctrl:1
	v_add_f32_dpp v36, v36, v36 row_half_mirror row_mask:0xf bank_mask:0xf bound_ctrl:1
	ds_read_b128 v[20:23], v0 offset:0
	v_add_f32_dpp v19, v19, v19 row_mirror row_mask:0xf bank_mask:0xf bound_ctrl:1
	v_add_f32_dpp v36, v36, v36 row_mirror row_mask:0xf bank_mask:0xf bound_ctrl:1
	v_fma_f32 v122, -v60, v19, v58
	v_mul_f32_e32 v138, v60, v36
	v_mul_f32_e32 v136, v59, v122
	ds_read_b128 v[38:41], v0 offset:2048
	v_fmac_f32_e32 v10, v24, v136
	v_fmac_f32_e32 v11, v25, v136
	v_fmac_f32_e32 v12, v26, v136
	v_fmac_f32_e32 v13, v27, v136
	v_fmac_f32_e32 v138, v61, v136
	ds_read_b128 v[54:57], v1 offset:4096
	s_nop 0
	v_mov_b32_dpp v14, v138 quad_perm:[0,1,2,3] row_mask:0xf bank_mask:0x8
	s_waitcnt lgkmcnt(7)
	v_mul_f32_e32 v19, v28, v10
	v_mul_f32_e32 v36, v46, v10
	v_fmac_f32_e32 v19, v29, v11
	v_fmac_f32_e32 v36, v47, v11
	v_fmac_f32_e32 v19, v30, v12
	v_fmac_f32_e32 v36, v48, v12
	v_fmac_f32_e32 v19, v31, v13
	v_fmac_f32_e32 v36, v49, v13
	v_mul_f32_e32 v10, v64, v10
	v_mul_f32_e32 v11, v64, v11
	v_add_f32_dpp v19, v19, v19 quad_perm:[1,0,3,2] row_mask:0xf bank_mask:0xf bound_ctrl:1
	v_add_f32_dpp v36, v36, v36 quad_perm:[1,0,3,2] row_mask:0xf bank_mask:0xf bound_ctrl:1
	v_mul_f32_e32 v12, v64, v12
	v_add_f32_dpp v19, v19, v19 quad_perm:[2,3,0,1] row_mask:0xf bank_mask:0xf bound_ctrl:1
	v_add_f32_dpp v36, v36, v36 quad_perm:[2,3,0,1] row_mask:0xf bank_mask:0xf bound_ctrl:1
	v_mul_f32_e32 v13, v64, v13
	v_add_f32_dpp v19, v19, v19 row_half_mirror row_mask:0xf bank_mask:0xf bound_ctrl:1
	v_add_f32_dpp v36, v36, v36 row_half_mirror row_mask:0xf bank_mask:0xf bound_ctrl:1
	ds_read_b128 v[24:27], v0 offset:256
	v_add_f32_dpp v19, v19, v19 row_mirror row_mask:0xf bank_mask:0xf bound_ctrl:1
	v_add_f32_dpp v36, v36, v36 row_mirror row_mask:0xf bank_mask:0xf bound_ctrl:1
	v_fma_f32 v122, -v64, v19, v62
	v_mul_f32_e32 v138, v64, v36
	v_mul_f32_e32 v136, v63, v122
	ds_read_b128 v[42:45], v0 offset:2304
	v_fmac_f32_e32 v10, v28, v136
	v_fmac_f32_e32 v11, v29, v136
	v_fmac_f32_e32 v12, v30, v136
	v_fmac_f32_e32 v13, v31, v136
	v_fmac_f32_e32 v138, v65, v136
	ds_read_b128 v[58:61], v1 offset:4160
	s_nop 0
	v_mov_b32_dpp v15, v138 quad_perm:[0,1,2,3] row_mask:0xf bank_mask:0x8
	s_waitcnt lgkmcnt(6)
	v_mul_f32_e32 v19, v32, v10
	v_mul_f32_e32 v36, v50, v10
	v_fmac_f32_e32 v19, v33, v11
	v_fmac_f32_e32 v36, v51, v11
	v_fmac_f32_e32 v19, v34, v12
	v_fmac_f32_e32 v36, v52, v12
	v_fmac_f32_e32 v19, v35, v13
	v_fmac_f32_e32 v36, v53, v13
	v_mul_f32_e32 v10, v68, v10
	v_mul_f32_e32 v11, v68, v11
	v_add_f32_dpp v19, v19, v19 quad_perm:[1,0,3,2] row_mask:0xf bank_mask:0xf bound_ctrl:1
	v_add_f32_dpp v36, v36, v36 quad_perm:[1,0,3,2] row_mask:0xf bank_mask:0xf bound_ctrl:1
	v_mul_f32_e32 v12, v68, v12
	v_add_f32_dpp v19, v19, v19 quad_perm:[2,3,0,1] row_mask:0xf bank_mask:0xf bound_ctrl:1
	v_add_f32_dpp v36, v36, v36 quad_perm:[2,3,0,1] row_mask:0xf bank_mask:0xf bound_ctrl:1
	v_mul_f32_e32 v13, v68, v13
	v_add_f32_dpp v19, v19, v19 row_half_mirror row_mask:0xf bank_mask:0xf bound_ctrl:1
	v_add_f32_dpp v36, v36, v36 row_half_mirror row_mask:0xf bank_mask:0xf bound_ctrl:1
	ds_read_b128 v[28:31], v0 offset:512
	v_add_f32_dpp v19, v19, v19 row_mirror row_mask:0xf bank_mask:0xf bound_ctrl:1
	v_add_f32_dpp v36, v36, v36 row_mirror row_mask:0xf bank_mask:0xf bound_ctrl:1
	v_fma_f32 v122, -v68, v19, v66
	v_mul_f32_e32 v138, v68, v36
	v_mul_f32_e32 v136, v67, v122
	ds_read_b128 v[46:49], v0 offset:2560
	v_fmac_f32_e32 v10, v32, v136
	v_fmac_f32_e32 v11, v33, v136
	v_fmac_f32_e32 v12, v34, v136
	v_fmac_f32_e32 v13, v35, v136
	v_fmac_f32_e32 v138, v69, v136
	ds_read_b128 v[62:65], v1 offset:4224
	s_nop 0
	v_mov_b32_dpp v16, v138 quad_perm:[0,1,2,3] row_mask:0xf bank_mask:0x8
	v_cndmask_b32_e64 v17, v9, v14, s[6:7]
	v_cndmask_b32_e64 v17, v17, v15, s[8:9]
	v_cndmask_b32_e64 v17, v17, v16, s[10:11]
	v_cvt_pk_bf16_f32 v18, v17, v17
	ds_write_b16 v140, v18 offset:9216
	s_waitcnt lgkmcnt(7)
	v_mul_f32_e32 v19, v20, v10
	v_mul_f32_e32 v36, v38, v10
	v_fmac_f32_e32 v19, v21, v11
	v_fmac_f32_e32 v36, v39, v11
	v_fmac_f32_e32 v19, v22, v12
	v_fmac_f32_e32 v36, v40, v12
	v_fmac_f32_e32 v19, v23, v13
	v_fmac_f32_e32 v36, v41, v13
	v_mul_f32_e32 v10, v56, v10
	v_mul_f32_e32 v11, v56, v11
	v_add_f32_dpp v19, v19, v19 quad_perm:[1,0,3,2] row_mask:0xf bank_mask:0xf bound_ctrl:1
	v_add_f32_dpp v36, v36, v36 quad_perm:[1,0,3,2] row_mask:0xf bank_mask:0xf bound_ctrl:1
	v_mul_f32_e32 v12, v56, v12
	v_add_f32_dpp v19, v19, v19 quad_perm:[2,3,0,1] row_mask:0xf bank_mask:0xf bound_ctrl:1
	v_add_f32_dpp v36, v36, v36 quad_perm:[2,3,0,1] row_mask:0xf bank_mask:0xf bound_ctrl:1
	v_mul_f32_e32 v13, v56, v13
	v_add_f32_dpp v19, v19, v19 row_half_mirror row_mask:0xf bank_mask:0xf bound_ctrl:1
	v_add_f32_dpp v36, v36, v36 row_half_mirror row_mask:0xf bank_mask:0xf bound_ctrl:1
	s_waitcnt vmcnt(14)
	v_add_f32_dpp v19, v19, v19 row_mirror row_mask:0xf bank_mask:0xf bound_ctrl:1
	v_add_f32_dpp v36, v36, v36 row_mirror row_mask:0xf bank_mask:0xf bound_ctrl:1
	v_fma_f32 v122, -v56, v19, v54
	v_mul_f32_e32 v138, v56, v36
	v_mul_f32_e32 v136, v55, v122
	v_lshlrev_b32_e32 v118, 16, v110
	v_fmac_f32_e32 v10, v20, v136
	v_fmac_f32_e32 v11, v21, v136
	v_fmac_f32_e32 v12, v22, v136
	v_fmac_f32_e32 v13, v23, v136
	v_fmac_f32_e32 v138, v57, v136
	ds_read_b128 v[32:35], v0 offset:768
	ds_read_b128 v[50:53], v0 offset:2816
	ds_read_b128 v[66:69], v1 offset:4288
	v_and_b32_e32 v119, 0xffff0000, v110
	v_lshlrev_b32_e32 v120, 16, v111
	v_and_b32_e32 v121, 0xffff0000, v111
	ds_write_b128 v2, v[118:121] offset:4608
	v_lshlrev_b32_e32 v124, 16, v112
	v_mov_b32_dpp v9, v138 quad_perm:[0,1,2,3] row_mask:0xf bank_mask:0x1
	s_waitcnt lgkmcnt(8)
	v_mul_f32_e32 v19, v24, v10
	v_mul_f32_e32 v36, v42, v10
	v_fmac_f32_e32 v19, v25, v11
	v_fmac_f32_e32 v36, v43, v11
	v_fmac_f32_e32 v19, v26, v12
	v_fmac_f32_e32 v36, v44, v12
	v_fmac_f32_e32 v19, v27, v13
	v_fmac_f32_e32 v36, v45, v13
	v_mul_f32_e32 v10, v60, v10
	v_mul_f32_e32 v11, v60, v11
	v_add_f32_dpp v19, v19, v19 quad_perm:[1,0,3,2] row_mask:0xf bank_mask:0xf bound_ctrl:1
	v_add_f32_dpp v36, v36, v36 quad_perm:[1,0,3,2] row_mask:0xf bank_mask:0xf bound_ctrl:1
	v_mul_f32_e32 v12, v60, v12
	v_add_f32_dpp v19, v19, v19 quad_perm:[2,3,0,1] row_mask:0xf bank_mask:0xf bound_ctrl:1
	v_add_f32_dpp v36, v36, v36 quad_perm:[2,3,0,1] row_mask:0xf bank_mask:0xf bound_ctrl:1
	v_mul_f32_e32 v13, v60, v13
	v_add_f32_dpp v19, v19, v19 row_half_mirror row_mask:0xf bank_mask:0xf bound_ctrl:1
	v_add_f32_dpp v36, v36, v36 row_half_mirror row_mask:0xf bank_mask:0xf bound_ctrl:1
	v_and_b32_e32 v125, 0xffff0000, v112
	v_add_f32_dpp v19, v19, v19 row_mirror row_mask:0xf bank_mask:0xf bound_ctrl:1
	v_add_f32_dpp v36, v36, v36 row_mirror row_mask:0xf bank_mask:0xf bound_ctrl:1
	v_fma_f32 v122, -v60, v19, v58
	v_mul_f32_e32 v138, v60, v36
	v_mul_f32_e32 v136, v59, v122
	v_lshlrev_b32_e32 v126, 16, v113
	v_fmac_f32_e32 v10, v24, v136
	v_fmac_f32_e32 v11, v25, v136
	v_fmac_f32_e32 v12, v26, v136
	v_fmac_f32_e32 v13, v27, v136
	v_fmac_f32_e32 v138, v61, v136
	ds_read_b128 v[20:23], v0 offset:1024
	ds_read_b128 v[38:41], v0 offset:3072
	ds_read_b128 v[54:57], v1 offset:4352
	v_and_b32_e32 v127, 0xffff0000, v113
	ds_write_b128 v2, v[124:127] offset:4624
	v_lshlrev_b32_e32 v118, 16, v106
	v_and_b32_e32 v119, 0xffff0000, v106
	v_lshlrev_b32_e32 v120, 16, v107
	v_mov_b32_dpp v14, v138 quad_perm:[0,1,2,3] row_mask:0xf bank_mask:0x1
	s_waitcnt lgkmcnt(9)
	v_mul_f32_e32 v19, v28, v10
	v_mul_f32_e32 v36, v46, v10
	v_fmac_f32_e32 v19, v29, v11
	v_fmac_f32_e32 v36, v47, v11
	v_fmac_f32_e32 v19, v30, v12
	v_fmac_f32_e32 v36, v48, v12
	v_fmac_f32_e32 v19, v31, v13
	v_fmac_f32_e32 v36, v49, v13
	v_mul_f32_e32 v10, v64, v10
	v_mul_f32_e32 v11, v64, v11
	v_add_f32_dpp v19, v19, v19 quad_perm:[1,0,3,2] row_mask:0xf bank_mask:0xf bound_ctrl:1
	v_add_f32_dpp v36, v36, v36 quad_perm:[1,0,3,2] row_mask:0xf bank_mask:0xf bound_ctrl:1
	v_mul_f32_e32 v12, v64, v12
	v_add_f32_dpp v19, v19, v19 quad_perm:[2,3,0,1] row_mask:0xf bank_mask:0xf bound_ctrl:1
	v_add_f32_dpp v36, v36, v36 quad_perm:[2,3,0,1] row_mask:0xf bank_mask:0xf bound_ctrl:1
	v_mul_f32_e32 v13, v64, v13
	v_add_f32_dpp v19, v19, v19 row_half_mirror row_mask:0xf bank_mask:0xf bound_ctrl:1
	v_add_f32_dpp v36, v36, v36 row_half_mirror row_mask:0xf bank_mask:0xf bound_ctrl:1
	v_and_b32_e32 v121, 0xffff0000, v107
	v_add_f32_dpp v19, v19, v19 row_mirror row_mask:0xf bank_mask:0xf bound_ctrl:1
	v_add_f32_dpp v36, v36, v36 row_mirror row_mask:0xf bank_mask:0xf bound_ctrl:1
	v_fma_f32 v122, -v64, v19, v62
	v_mul_f32_e32 v138, v64, v36
	v_mul_f32_e32 v136, v63, v122
	ds_write_b128 v2, v[118:121] offset:6656
	v_fmac_f32_e32 v10, v28, v136
	v_fmac_f32_e32 v11, v29, v136
	v_fmac_f32_e32 v12, v30, v136
	v_fmac_f32_e32 v13, v31, v136
	v_fmac_f32_e32 v138, v65, v136
	ds_read_b128 v[24:27], v0 offset:1280
	ds_read_b128 v[42:45], v0 offset:3328
	ds_read_b128 v[58:61], v1 offset:4416
	v_lshlrev_b32_e32 v124, 16, v108
	v_and_b32_e32 v125, 0xffff0000, v108
	v_lshlrev_b32_e32 v126, 16, v109
	v_and_b32_e32 v127, 0xffff0000, v109
	ds_write_b128 v2, v[124:127] offset:6672
	v_mov_b32_dpp v15, v138 quad_perm:[0,1,2,3] row_mask:0xf bank_mask:0x1
	s_waitcnt lgkmcnt(10)
	v_mul_f32_e32 v19, v32, v10
	v_mul_f32_e32 v36, v50, v10
	v_fmac_f32_e32 v19, v33, v11
	v_fmac_f32_e32 v36, v51, v11
	v_fmac_f32_e32 v19, v34, v12
	v_fmac_f32_e32 v36, v52, v12
	v_fmac_f32_e32 v19, v35, v13
	v_fmac_f32_e32 v36, v53, v13
	v_mul_f32_e32 v10, v68, v10
	v_mul_f32_e32 v11, v68, v11
	v_add_f32_dpp v19, v19, v19 quad_perm:[1,0,3,2] row_mask:0xf bank_mask:0xf bound_ctrl:1
	v_add_f32_dpp v36, v36, v36 quad_perm:[1,0,3,2] row_mask:0xf bank_mask:0xf bound_ctrl:1
	v_mul_f32_e32 v12, v68, v12
	v_add_f32_dpp v19, v19, v19 quad_perm:[2,3,0,1] row_mask:0xf bank_mask:0xf bound_ctrl:1
	v_add_f32_dpp v36, v36, v36 quad_perm:[2,3,0,1] row_mask:0xf bank_mask:0xf bound_ctrl:1
	v_mul_f32_e32 v13, v68, v13
	v_add_f32_dpp v19, v19, v19 row_half_mirror row_mask:0xf bank_mask:0xf bound_ctrl:1
	v_add_f32_dpp v36, v36, v36 row_half_mirror row_mask:0xf bank_mask:0xf bound_ctrl:1
	s_waitcnt vmcnt(12)
	v_add_f32_dpp v19, v19, v19 row_mirror row_mask:0xf bank_mask:0xf bound_ctrl:1
	v_add_f32_dpp v36, v36, v36 row_mirror row_mask:0xf bank_mask:0xf bound_ctrl:1
	v_fma_f32 v122, -v68, v19, v66
	v_mul_f32_e32 v138, v68, v36
	v_mul_f32_e32 v136, v67, v122
	v_mov_b32_dpp v116, v115 quad_perm:[1,1,1,1] row_mask:0xf bank_mask:0xf
	v_fmac_f32_e32 v10, v32, v136
	v_fmac_f32_e32 v11, v33, v136
	v_fmac_f32_e32 v12, v34, v136
	v_fmac_f32_e32 v13, v35, v136
	v_fmac_f32_e32 v138, v69, v136
	ds_read_b128 v[28:31], v0 offset:1536
	ds_read_b128 v[46:49], v0 offset:3584
	ds_read_b128 v[62:65], v1 offset:4480
	v_mov_b32_dpp v117, v115 quad_perm:[2,2,2,2] row_mask:0xf bank_mask:0xf
	v_mov_b32_dpp v115, v115 quad_perm:[0,0,0,0] row_mask:0xf bank_mask:0xf
	v_lshlrev_b32_e32 v114, 16, v114
	s_nop 0
	ds_write_b128 v4, v[114:117] offset:8704
	v_mov_b32_dpp v16, v138 quad_perm:[0,1,2,3] row_mask:0xf bank_mask:0x1
	s_waitcnt lgkmcnt(10)
	v_mul_f32_e32 v19, v20, v10
	v_mul_f32_e32 v36, v38, v10
	v_fmac_f32_e32 v19, v21, v11
	v_fmac_f32_e32 v36, v39, v11
	v_fmac_f32_e32 v19, v22, v12
	v_fmac_f32_e32 v36, v40, v12
	v_fmac_f32_e32 v19, v23, v13
	v_fmac_f32_e32 v36, v41, v13
	v_mul_f32_e32 v10, v56, v10
	v_mul_f32_e32 v11, v56, v11
	v_add_f32_dpp v19, v19, v19 quad_perm:[1,0,3,2] row_mask:0xf bank_mask:0xf bound_ctrl:1
	v_add_f32_dpp v36, v36, v36 quad_perm:[1,0,3,2] row_mask:0xf bank_mask:0xf bound_ctrl:1
	v_mul_f32_e32 v12, v56, v12
	v_add_f32_dpp v19, v19, v19 quad_perm:[2,3,0,1] row_mask:0xf bank_mask:0xf bound_ctrl:1
	v_add_f32_dpp v36, v36, v36 quad_perm:[2,3,0,1] row_mask:0xf bank_mask:0xf bound_ctrl:1
	v_mul_f32_e32 v13, v56, v13
	v_add_f32_dpp v19, v19, v19 row_half_mirror row_mask:0xf bank_mask:0xf bound_ctrl:1
	v_add_f32_dpp v36, v36, v36 row_half_mirror row_mask:0xf bank_mask:0xf bound_ctrl:1
	global_load_dwordx4 v[106:109], v5, s[94:95]
	global_load_dwordx4 v[110:113], v5, s[94:95] offset:512
	global_load_ushort v114, v6, s[94:95]
	global_load_dword v115, v8, s[94:95]
	v_add_u32_e32 v5, 0x6800, v5
	v_add_u32_e32 v6, 0x6800, v6
	v_add_u32_e32 v8, 0x3180, v8
	v_add_f32_dpp v19, v19, v19 row_mirror row_mask:0xf bank_mask:0xf bound_ctrl:1
	v_add_f32_dpp v36, v36, v36 row_mirror row_mask:0xf bank_mask:0xf bound_ctrl:1
	v_fma_f32 v122, -v56, v19, v54
	v_mul_f32_e32 v138, v56, v36
	v_mul_f32_e32 v136, v55, v122
	ds_read_b128 v[32:35], v0 offset:1792
	v_fmac_f32_e32 v10, v20, v136
	v_fmac_f32_e32 v11, v21, v136
	v_fmac_f32_e32 v12, v22, v136
	v_fmac_f32_e32 v13, v23, v136
	v_fmac_f32_e32 v138, v57, v136
	ds_read_b128 v[50:53], v0 offset:3840
	ds_read_b128 v[66:69], v1 offset:4544
	v_mov_b32_dpp v9, v138 quad_perm:[0,1,2,3] row_mask:0xf bank_mask:0x2
	s_waitcnt lgkmcnt(8)
	v_mul_f32_e32 v19, v24, v10
	v_mul_f32_e32 v36, v42, v10
	v_fmac_f32_e32 v19, v25, v11
	v_fmac_f32_e32 v36, v43, v11
	v_fmac_f32_e32 v19, v26, v12
	v_fmac_f32_e32 v36, v44, v12
	v_fmac_f32_e32 v19, v27, v13
	v_fmac_f32_e32 v36, v45, v13
	v_mul_f32_e32 v10, v60, v10
	v_mul_f32_e32 v11, v60, v11
	v_add_f32_dpp v19, v19, v19 quad_perm:[1,0,3,2] row_mask:0xf bank_mask:0xf bound_ctrl:1
	v_add_f32_dpp v36, v36, v36 quad_perm:[1,0,3,2] row_mask:0xf bank_mask:0xf bound_ctrl:1
	v_mul_f32_e32 v12, v60, v12
	v_add_f32_dpp v19, v19, v19 quad_perm:[2,3,0,1] row_mask:0xf bank_mask:0xf bound_ctrl:1
	v_add_f32_dpp v36, v36, v36 quad_perm:[2,3,0,1] row_mask:0xf bank_mask:0xf bound_ctrl:1
	v_mul_f32_e32 v13, v60, v13
	v_add_f32_dpp v19, v19, v19 row_half_mirror row_mask:0xf bank_mask:0xf bound_ctrl:1
	v_add_f32_dpp v36, v36, v36 row_half_mirror row_mask:0xf bank_mask:0xf bound_ctrl:1
	ds_read_b128 v[20:23], v0 offset:4608
	v_add_f32_dpp v19, v19, v19 row_mirror row_mask:0xf bank_mask:0xf bound_ctrl:1
	v_add_f32_dpp v36, v36, v36 row_mirror row_mask:0xf bank_mask:0xf bound_ctrl:1
	v_fma_f32 v122, -v60, v19, v58
	v_mul_f32_e32 v138, v60, v36
	v_mul_f32_e32 v136, v59, v122
	ds_read_b128 v[38:41], v0 offset:6656
	v_fmac_f32_e32 v10, v24, v136
	v_fmac_f32_e32 v11, v25, v136
	v_fmac_f32_e32 v12, v26, v136
	v_fmac_f32_e32 v13, v27, v136
	v_fmac_f32_e32 v138, v61, v136
	ds_read_b128 v[54:57], v1 offset:8704
	s_nop 0
	v_mov_b32_dpp v14, v138 quad_perm:[0,1,2,3] row_mask:0xf bank_mask:0x2
	s_waitcnt lgkmcnt(7)
	v_mul_f32_e32 v19, v28, v10
	v_mul_f32_e32 v36, v46, v10
	v_fmac_f32_e32 v19, v29, v11
	v_fmac_f32_e32 v36, v47, v11
	v_fmac_f32_e32 v19, v30, v12
	v_fmac_f32_e32 v36, v48, v12
	v_fmac_f32_e32 v19, v31, v13
	v_fmac_f32_e32 v36, v49, v13
	v_mul_f32_e32 v10, v64, v10
	v_mul_f32_e32 v11, v64, v11
	v_add_f32_dpp v19, v19, v19 quad_perm:[1,0,3,2] row_mask:0xf bank_mask:0xf bound_ctrl:1
	v_add_f32_dpp v36, v36, v36 quad_perm:[1,0,3,2] row_mask:0xf bank_mask:0xf bound_ctrl:1
	v_mul_f32_e32 v12, v64, v12
	v_add_f32_dpp v19, v19, v19 quad_perm:[2,3,0,1] row_mask:0xf bank_mask:0xf bound_ctrl:1
	v_add_f32_dpp v36, v36, v36 quad_perm:[2,3,0,1] row_mask:0xf bank_mask:0xf bound_ctrl:1
	v_mul_f32_e32 v13, v64, v13
	v_add_f32_dpp v19, v19, v19 row_half_mirror row_mask:0xf bank_mask:0xf bound_ctrl:1
	v_add_f32_dpp v36, v36, v36 row_half_mirror row_mask:0xf bank_mask:0xf bound_ctrl:1
	ds_read_b128 v[24:27], v0 offset:4864
	v_add_f32_dpp v19, v19, v19 row_mirror row_mask:0xf bank_mask:0xf bound_ctrl:1
	v_add_f32_dpp v36, v36, v36 row_mirror row_mask:0xf bank_mask:0xf bound_ctrl:1
	v_fma_f32 v122, -v64, v19, v62
	v_mul_f32_e32 v138, v64, v36
	v_mul_f32_e32 v136, v63, v122
	ds_read_b128 v[42:45], v0 offset:6912
	v_fmac_f32_e32 v10, v28, v136
	v_fmac_f32_e32 v11, v29, v136
	v_fmac_f32_e32 v12, v30, v136
	v_fmac_f32_e32 v13, v31, v136
	v_fmac_f32_e32 v138, v65, v136
	ds_read_b128 v[58:61], v1 offset:8768
	s_nop 0
	v_mov_b32_dpp v15, v138 quad_perm:[0,1,2,3] row_mask:0xf bank_mask:0x2
	s_waitcnt lgkmcnt(6)
	v_mul_f32_e32 v19, v32, v10
	v_mul_f32_e32 v36, v50, v10
	v_fmac_f32_e32 v19, v33, v11
	v_fmac_f32_e32 v36, v51, v11
	v_fmac_f32_e32 v19, v34, v12
	v_fmac_f32_e32 v36, v52, v12
	v_fmac_f32_e32 v19, v35, v13
	v_fmac_f32_e32 v36, v53, v13
	v_mul_f32_e32 v10, v68, v10
	v_mul_f32_e32 v11, v68, v11
	v_add_f32_dpp v19, v19, v19 quad_perm:[1,0,3,2] row_mask:0xf bank_mask:0xf bound_ctrl:1
	v_add_f32_dpp v36, v36, v36 quad_perm:[1,0,3,2] row_mask:0xf bank_mask:0xf bound_ctrl:1
	v_mul_f32_e32 v12, v68, v12
	v_add_f32_dpp v19, v19, v19 quad_perm:[2,3,0,1] row_mask:0xf bank_mask:0xf bound_ctrl:1
	v_add_f32_dpp v36, v36, v36 quad_perm:[2,3,0,1] row_mask:0xf bank_mask:0xf bound_ctrl:1
	v_mul_f32_e32 v13, v68, v13
	v_add_f32_dpp v19, v19, v19 row_half_mirror row_mask:0xf bank_mask:0xf bound_ctrl:1
	v_add_f32_dpp v36, v36, v36 row_half_mirror row_mask:0xf bank_mask:0xf bound_ctrl:1
	ds_read_b128 v[28:31], v0 offset:5120
	v_add_f32_dpp v19, v19, v19 row_mirror row_mask:0xf bank_mask:0xf bound_ctrl:1
	v_add_f32_dpp v36, v36, v36 row_mirror row_mask:0xf bank_mask:0xf bound_ctrl:1
	v_fma_f32 v122, -v68, v19, v66
	v_mul_f32_e32 v138, v68, v36
	v_mul_f32_e32 v136, v67, v122
	ds_read_b128 v[46:49], v0 offset:7168
	v_fmac_f32_e32 v10, v32, v136
	v_fmac_f32_e32 v11, v33, v136
	v_fmac_f32_e32 v12, v34, v136
	v_fmac_f32_e32 v13, v35, v136
	v_fmac_f32_e32 v138, v69, v136
	ds_read_b128 v[62:65], v1 offset:8832
	s_nop 0
	v_mov_b32_dpp v16, v138 quad_perm:[0,1,2,3] row_mask:0xf bank_mask:0x2
	s_waitcnt lgkmcnt(6)
	v_mul_f32_e32 v19, v20, v10
	v_mul_f32_e32 v36, v38, v10
	v_fmac_f32_e32 v19, v21, v11
	v_fmac_f32_e32 v36, v39, v11
	v_fmac_f32_e32 v19, v22, v12
	v_fmac_f32_e32 v36, v40, v12
	v_fmac_f32_e32 v19, v23, v13
	v_fmac_f32_e32 v36, v41, v13
	v_mul_f32_e32 v10, v56, v10
	v_mul_f32_e32 v11, v56, v11
	v_add_f32_dpp v19, v19, v19 quad_perm:[1,0,3,2] row_mask:0xf bank_mask:0xf bound_ctrl:1
	v_add_f32_dpp v36, v36, v36 quad_perm:[1,0,3,2] row_mask:0xf bank_mask:0xf bound_ctrl:1
	v_mul_f32_e32 v12, v56, v12
	v_add_f32_dpp v19, v19, v19 quad_perm:[2,3,0,1] row_mask:0xf bank_mask:0xf bound_ctrl:1
	v_add_f32_dpp v36, v36, v36 quad_perm:[2,3,0,1] row_mask:0xf bank_mask:0xf bound_ctrl:1
	v_mul_f32_e32 v13, v56, v13
	v_add_f32_dpp v19, v19, v19 row_half_mirror row_mask:0xf bank_mask:0xf bound_ctrl:1
	v_add_f32_dpp v36, v36, v36 row_half_mirror row_mask:0xf bank_mask:0xf bound_ctrl:1
	s_waitcnt vmcnt(14)
	v_add_f32_dpp v19, v19, v19 row_mirror row_mask:0xf bank_mask:0xf bound_ctrl:1
	v_add_f32_dpp v36, v36, v36 row_mirror row_mask:0xf bank_mask:0xf bound_ctrl:1
	v_fma_f32 v122, -v56, v19, v54
	v_mul_f32_e32 v138, v56, v36
	v_mul_f32_e32 v136, v55, v122
	v_lshlrev_b32_e32 v118, 16, v74
	v_fmac_f32_e32 v10, v20, v136
	v_fmac_f32_e32 v11, v21, v136
	v_fmac_f32_e32 v12, v22, v136
	v_fmac_f32_e32 v13, v23, v136
	v_fmac_f32_e32 v138, v57, v136
	ds_read_b128 v[32:35], v0 offset:5376
	ds_read_b128 v[50:53], v0 offset:7424
	ds_read_b128 v[66:69], v1 offset:8896
	v_and_b32_e32 v119, 0xffff0000, v74
	v_lshlrev_b32_e32 v120, 16, v75
	v_and_b32_e32 v121, 0xffff0000, v75
	ds_write_b128 v2, v[118:121] offset:0
	v_lshlrev_b32_e32 v124, 16, v76
	v_mov_b32_dpp v9, v138 quad_perm:[0,1,2,3] row_mask:0xf bank_mask:0x4
	s_waitcnt lgkmcnt(7)
	v_mul_f32_e32 v19, v24, v10
	v_mul_f32_e32 v36, v42, v10
	v_fmac_f32_e32 v19, v25, v11
	v_fmac_f32_e32 v36, v43, v11
	v_fmac_f32_e32 v19, v26, v12
	v_fmac_f32_e32 v36, v44, v12
	v_fmac_f32_e32 v19, v27, v13
	v_fmac_f32_e32 v36, v45, v13
	v_mul_f32_e32 v10, v60, v10
	v_mul_f32_e32 v11, v60, v11
	v_add_f32_dpp v19, v19, v19 quad_perm:[1,0,3,2] row_mask:0xf bank_mask:0xf bound_ctrl:1
	v_add_f32_dpp v36, v36, v36 quad_perm:[1,0,3,2] row_mask:0xf bank_mask:0xf bound_ctrl:1
	v_mul_f32_e32 v12, v60, v12
	v_add_f32_dpp v19, v19, v19 quad_perm:[2,3,0,1] row_mask:0xf bank_mask:0xf bound_ctrl:1
	v_add_f32_dpp v36, v36, v36 quad_perm:[2,3,0,1] row_mask:0xf bank_mask:0xf bound_ctrl:1
	v_mul_f32_e32 v13, v60, v13
	v_add_f32_dpp v19, v19, v19 row_half_mirror row_mask:0xf bank_mask:0xf bound_ctrl:1
	v_add_f32_dpp v36, v36, v36 row_half_mirror row_mask:0xf bank_mask:0xf bound_ctrl:1
	v_and_b32_e32 v125, 0xffff0000, v76
	v_add_f32_dpp v19, v19, v19 row_mirror row_mask:0xf bank_mask:0xf bound_ctrl:1
	v_add_f32_dpp v36, v36, v36 row_mirror row_mask:0xf bank_mask:0xf bound_ctrl:1
	v_fma_f32 v122, -v60, v19, v58
	v_mul_f32_e32 v138, v60, v36
	v_mul_f32_e32 v136, v59, v122
	v_lshlrev_b32_e32 v126, 16, v77
	v_fmac_f32_e32 v10, v24, v136
	v_fmac_f32_e32 v11, v25, v136
	v_fmac_f32_e32 v12, v26, v136
	v_fmac_f32_e32 v13, v27, v136
	v_fmac_f32_e32 v138, v61, v136
	ds_read_b128 v[20:23], v0 offset:5632
	ds_read_b128 v[38:41], v0 offset:7680
	ds_read_b128 v[54:57], v1 offset:8960
	v_and_b32_e32 v127, 0xffff0000, v77
	ds_write_b128 v2, v[124:127] offset:16
	v_lshlrev_b32_e32 v118, 16, v70
	v_and_b32_e32 v119, 0xffff0000, v70
	v_lshlrev_b32_e32 v120, 16, v71
	v_mov_b32_dpp v14, v138 quad_perm:[0,1,2,3] row_mask:0xf bank_mask:0x4
	s_waitcnt lgkmcnt(8)
	v_mul_f32_e32 v19, v28, v10
	v_mul_f32_e32 v36, v46, v10
	v_fmac_f32_e32 v19, v29, v11
	v_fmac_f32_e32 v36, v47, v11
	v_fmac_f32_e32 v19, v30, v12
	v_fmac_f32_e32 v36, v48, v12
	v_fmac_f32_e32 v19, v31, v13
	v_fmac_f32_e32 v36, v49, v13
	v_mul_f32_e32 v10, v64, v10
	v_mul_f32_e32 v11, v64, v11
	v_add_f32_dpp v19, v19, v19 quad_perm:[1,0,3,2] row_mask:0xf bank_mask:0xf bound_ctrl:1
	v_add_f32_dpp v36, v36, v36 quad_perm:[1,0,3,2] row_mask:0xf bank_mask:0xf bound_ctrl:1
	v_mul_f32_e32 v12, v64, v12
	v_add_f32_dpp v19, v19, v19 quad_perm:[2,3,0,1] row_mask:0xf bank_mask:0xf bound_ctrl:1
	v_add_f32_dpp v36, v36, v36 quad_perm:[2,3,0,1] row_mask:0xf bank_mask:0xf bound_ctrl:1
	v_mul_f32_e32 v13, v64, v13
	v_add_f32_dpp v19, v19, v19 row_half_mirror row_mask:0xf bank_mask:0xf bound_ctrl:1
	v_add_f32_dpp v36, v36, v36 row_half_mirror row_mask:0xf bank_mask:0xf bound_ctrl:1
	v_and_b32_e32 v121, 0xffff0000, v71
	v_add_f32_dpp v19, v19, v19 row_mirror row_mask:0xf bank_mask:0xf bound_ctrl:1
	v_add_f32_dpp v36, v36, v36 row_mirror row_mask:0xf bank_mask:0xf bound_ctrl:1
	v_fma_f32 v122, -v64, v19, v62
	v_mul_f32_e32 v138, v64, v36
	v_mul_f32_e32 v136, v63, v122
	ds_write_b128 v2, v[118:121] offset:2048
	v_fmac_f32_e32 v10, v28, v136
	v_fmac_f32_e32 v11, v29, v136
	v_fmac_f32_e32 v12, v30, v136
	v_fmac_f32_e32 v13, v31, v136
	v_fmac_f32_e32 v138, v65, v136
	ds_read_b128 v[24:27], v0 offset:5888
	ds_read_b128 v[42:45], v0 offset:7936
	ds_read_b128 v[58:61], v1 offset:9024
	v_lshlrev_b32_e32 v124, 16, v72
	v_and_b32_e32 v125, 0xffff0000, v72
	v_lshlrev_b32_e32 v126, 16, v73
	v_and_b32_e32 v127, 0xffff0000, v73
	ds_write_b128 v2, v[124:127] offset:2064
	v_mov_b32_dpp v15, v138 quad_perm:[0,1,2,3] row_mask:0xf bank_mask:0x4
	s_waitcnt lgkmcnt(10)
	v_mul_f32_e32 v19, v32, v10
	v_mul_f32_e32 v36, v50, v10
	v_fmac_f32_e32 v19, v33, v11
	v_fmac_f32_e32 v36, v51, v11
	v_fmac_f32_e32 v19, v34, v12
	v_fmac_f32_e32 v36, v52, v12
	v_fmac_f32_e32 v19, v35, v13
	v_fmac_f32_e32 v36, v53, v13
	v_mul_f32_e32 v10, v68, v10
	v_mul_f32_e32 v11, v68, v11
	v_add_f32_dpp v19, v19, v19 quad_perm:[1,0,3,2] row_mask:0xf bank_mask:0xf bound_ctrl:1
	v_add_f32_dpp v36, v36, v36 quad_perm:[1,0,3,2] row_mask:0xf bank_mask:0xf bound_ctrl:1
	v_mul_f32_e32 v12, v68, v12
	v_add_f32_dpp v19, v19, v19 quad_perm:[2,3,0,1] row_mask:0xf bank_mask:0xf bound_ctrl:1
	v_add_f32_dpp v36, v36, v36 quad_perm:[2,3,0,1] row_mask:0xf bank_mask:0xf bound_ctrl:1
	v_mul_f32_e32 v13, v68, v13
	v_add_f32_dpp v19, v19, v19 row_half_mirror row_mask:0xf bank_mask:0xf bound_ctrl:1
	v_add_f32_dpp v36, v36, v36 row_half_mirror row_mask:0xf bank_mask:0xf bound_ctrl:1
	s_waitcnt vmcnt(12)
	v_add_f32_dpp v19, v19, v19 row_mirror row_mask:0xf bank_mask:0xf bound_ctrl:1
	v_add_f32_dpp v36, v36, v36 row_mirror row_mask:0xf bank_mask:0xf bound_ctrl:1
	v_fma_f32 v122, -v68, v19, v66
	v_mul_f32_e32 v138, v68, v36
	v_mul_f32_e32 v136, v67, v122
	v_mov_b32_dpp v80, v79 quad_perm:[1,1,1,1] row_mask:0xf bank_mask:0xf
	v_fmac_f32_e32 v10, v32, v136
	v_fmac_f32_e32 v11, v33, v136
	v_fmac_f32_e32 v12, v34, v136
	v_fmac_f32_e32 v13, v35, v136
	v_fmac_f32_e32 v138, v69, v136
	ds_read_b128 v[28:31], v0 offset:6144
	ds_read_b128 v[46:49], v0 offset:8192
	ds_read_b128 v[62:65], v1 offset:9088
	v_mov_b32_dpp v81, v79 quad_perm:[2,2,2,2] row_mask:0xf bank_mask:0xf
	v_mov_b32_dpp v79, v79 quad_perm:[0,0,0,0] row_mask:0xf bank_mask:0xf
	v_lshlrev_b32_e32 v78, 16, v78
	s_nop 0
	ds_write_b128 v4, v[78:81] offset:4096
	v_mov_b32_dpp v16, v138 quad_perm:[0,1,2,3] row_mask:0xf bank_mask:0x4
	s_waitcnt lgkmcnt(10)
	v_mul_f32_e32 v19, v20, v10
	v_mul_f32_e32 v36, v38, v10
	v_fmac_f32_e32 v19, v21, v11
	v_fmac_f32_e32 v36, v39, v11
	v_fmac_f32_e32 v19, v22, v12
	v_fmac_f32_e32 v36, v40, v12
	v_fmac_f32_e32 v19, v23, v13
	v_fmac_f32_e32 v36, v41, v13
	v_mul_f32_e32 v10, v56, v10
	v_mul_f32_e32 v11, v56, v11
	v_add_f32_dpp v19, v19, v19 quad_perm:[1,0,3,2] row_mask:0xf bank_mask:0xf bound_ctrl:1
	v_add_f32_dpp v36, v36, v36 quad_perm:[1,0,3,2] row_mask:0xf bank_mask:0xf bound_ctrl:1
	v_mul_f32_e32 v12, v56, v12
	v_add_f32_dpp v19, v19, v19 quad_perm:[2,3,0,1] row_mask:0xf bank_mask:0xf bound_ctrl:1
	v_add_f32_dpp v36, v36, v36 quad_perm:[2,3,0,1] row_mask:0xf bank_mask:0xf bound_ctrl:1
	v_mul_f32_e32 v13, v56, v13
	v_add_f32_dpp v19, v19, v19 row_half_mirror row_mask:0xf bank_mask:0xf bound_ctrl:1
	v_add_f32_dpp v36, v36, v36 row_half_mirror row_mask:0xf bank_mask:0xf bound_ctrl:1
	global_load_dwordx4 v[70:73], v5, s[94:95]
	global_load_dwordx4 v[74:77], v5, s[94:95] offset:512
	global_load_ushort v78, v6, s[94:95]
	global_load_dword v79, v8, s[94:95]
	v_add_u32_e32 v5, 0x6800, v5
	v_add_u32_e32 v6, 0x6800, v6
	v_add_u32_e32 v8, 0x3180, v8
	v_add_f32_dpp v19, v19, v19 row_mirror row_mask:0xf bank_mask:0xf bound_ctrl:1
	v_add_f32_dpp v36, v36, v36 row_mirror row_mask:0xf bank_mask:0xf bound_ctrl:1
	v_fma_f32 v122, -v56, v19, v54
	v_mul_f32_e32 v138, v56, v36
	v_mul_f32_e32 v136, v55, v122
	ds_read_b128 v[32:35], v0 offset:6400
	v_fmac_f32_e32 v10, v20, v136
	v_fmac_f32_e32 v11, v21, v136
	v_fmac_f32_e32 v12, v22, v136
	v_fmac_f32_e32 v13, v23, v136
	v_fmac_f32_e32 v138, v57, v136
	ds_read_b128 v[50:53], v0 offset:8448
	ds_read_b128 v[66:69], v1 offset:9152
	v_mov_b32_dpp v9, v138 quad_perm:[0,1,2,3] row_mask:0xf bank_mask:0x8
	s_waitcnt lgkmcnt(8)
	v_mul_f32_e32 v19, v24, v10
	v_mul_f32_e32 v36, v42, v10
	v_fmac_f32_e32 v19, v25, v11
	v_fmac_f32_e32 v36, v43, v11
	v_fmac_f32_e32 v19, v26, v12
	v_fmac_f32_e32 v36, v44, v12
	v_fmac_f32_e32 v19, v27, v13
	v_fmac_f32_e32 v36, v45, v13
	v_mul_f32_e32 v10, v60, v10
	v_mul_f32_e32 v11, v60, v11
	v_add_f32_dpp v19, v19, v19 quad_perm:[1,0,3,2] row_mask:0xf bank_mask:0xf bound_ctrl:1
	v_add_f32_dpp v36, v36, v36 quad_perm:[1,0,3,2] row_mask:0xf bank_mask:0xf bound_ctrl:1
	v_mul_f32_e32 v12, v60, v12
	v_add_f32_dpp v19, v19, v19 quad_perm:[2,3,0,1] row_mask:0xf bank_mask:0xf bound_ctrl:1
	v_add_f32_dpp v36, v36, v36 quad_perm:[2,3,0,1] row_mask:0xf bank_mask:0xf bound_ctrl:1
	v_mul_f32_e32 v13, v60, v13
	v_add_f32_dpp v19, v19, v19 row_half_mirror row_mask:0xf bank_mask:0xf bound_ctrl:1
	v_add_f32_dpp v36, v36, v36 row_half_mirror row_mask:0xf bank_mask:0xf bound_ctrl:1
	ds_read_b128 v[20:23], v0 offset:0
	v_add_f32_dpp v19, v19, v19 row_mirror row_mask:0xf bank_mask:0xf bound_ctrl:1
	v_add_f32_dpp v36, v36, v36 row_mirror row_mask:0xf bank_mask:0xf bound_ctrl:1
	v_fma_f32 v122, -v60, v19, v58
	v_mul_f32_e32 v138, v60, v36
	v_mul_f32_e32 v136, v59, v122
	ds_read_b128 v[38:41], v0 offset:2048
	v_fmac_f32_e32 v10, v24, v136
	v_fmac_f32_e32 v11, v25, v136
	v_fmac_f32_e32 v12, v26, v136
	v_fmac_f32_e32 v13, v27, v136
	v_fmac_f32_e32 v138, v61, v136
	ds_read_b128 v[54:57], v1 offset:4096
	s_nop 0
	v_mov_b32_dpp v14, v138 quad_perm:[0,1,2,3] row_mask:0xf bank_mask:0x8
	s_waitcnt lgkmcnt(7)
	v_mul_f32_e32 v19, v28, v10
	v_mul_f32_e32 v36, v46, v10
	v_fmac_f32_e32 v19, v29, v11
	v_fmac_f32_e32 v36, v47, v11
	v_fmac_f32_e32 v19, v30, v12
	v_fmac_f32_e32 v36, v48, v12
	v_fmac_f32_e32 v19, v31, v13
	v_fmac_f32_e32 v36, v49, v13
	v_mul_f32_e32 v10, v64, v10
	v_mul_f32_e32 v11, v64, v11
	v_add_f32_dpp v19, v19, v19 quad_perm:[1,0,3,2] row_mask:0xf bank_mask:0xf bound_ctrl:1
	v_add_f32_dpp v36, v36, v36 quad_perm:[1,0,3,2] row_mask:0xf bank_mask:0xf bound_ctrl:1
	v_mul_f32_e32 v12, v64, v12
	v_add_f32_dpp v19, v19, v19 quad_perm:[2,3,0,1] row_mask:0xf bank_mask:0xf bound_ctrl:1
	v_add_f32_dpp v36, v36, v36 quad_perm:[2,3,0,1] row_mask:0xf bank_mask:0xf bound_ctrl:1
	v_mul_f32_e32 v13, v64, v13
	v_add_f32_dpp v19, v19, v19 row_half_mirror row_mask:0xf bank_mask:0xf bound_ctrl:1
	v_add_f32_dpp v36, v36, v36 row_half_mirror row_mask:0xf bank_mask:0xf bound_ctrl:1
	ds_read_b128 v[24:27], v0 offset:256
	v_add_f32_dpp v19, v19, v19 row_mirror row_mask:0xf bank_mask:0xf bound_ctrl:1
	v_add_f32_dpp v36, v36, v36 row_mirror row_mask:0xf bank_mask:0xf bound_ctrl:1
	v_fma_f32 v122, -v64, v19, v62
	v_mul_f32_e32 v138, v64, v36
	v_mul_f32_e32 v136, v63, v122
	ds_read_b128 v[42:45], v0 offset:2304
	v_fmac_f32_e32 v10, v28, v136
	v_fmac_f32_e32 v11, v29, v136
	v_fmac_f32_e32 v12, v30, v136
	v_fmac_f32_e32 v13, v31, v136
	v_fmac_f32_e32 v138, v65, v136
	ds_read_b128 v[58:61], v1 offset:4160
	s_nop 0
	v_mov_b32_dpp v15, v138 quad_perm:[0,1,2,3] row_mask:0xf bank_mask:0x8
	s_waitcnt lgkmcnt(6)
	v_mul_f32_e32 v19, v32, v10
	v_mul_f32_e32 v36, v50, v10
	v_fmac_f32_e32 v19, v33, v11
	v_fmac_f32_e32 v36, v51, v11
	v_fmac_f32_e32 v19, v34, v12
	v_fmac_f32_e32 v36, v52, v12
	v_fmac_f32_e32 v19, v35, v13
	v_fmac_f32_e32 v36, v53, v13
	v_mul_f32_e32 v10, v68, v10
	v_mul_f32_e32 v11, v68, v11
	v_add_f32_dpp v19, v19, v19 quad_perm:[1,0,3,2] row_mask:0xf bank_mask:0xf bound_ctrl:1
	v_add_f32_dpp v36, v36, v36 quad_perm:[1,0,3,2] row_mask:0xf bank_mask:0xf bound_ctrl:1
	v_mul_f32_e32 v12, v68, v12
	v_add_f32_dpp v19, v19, v19 quad_perm:[2,3,0,1] row_mask:0xf bank_mask:0xf bound_ctrl:1
	v_add_f32_dpp v36, v36, v36 quad_perm:[2,3,0,1] row_mask:0xf bank_mask:0xf bound_ctrl:1
	v_mul_f32_e32 v13, v68, v13
	v_add_f32_dpp v19, v19, v19 row_half_mirror row_mask:0xf bank_mask:0xf bound_ctrl:1
	v_add_f32_dpp v36, v36, v36 row_half_mirror row_mask:0xf bank_mask:0xf bound_ctrl:1
	ds_read_b128 v[28:31], v0 offset:512
	v_add_f32_dpp v19, v19, v19 row_mirror row_mask:0xf bank_mask:0xf bound_ctrl:1
	v_add_f32_dpp v36, v36, v36 row_mirror row_mask:0xf bank_mask:0xf bound_ctrl:1
	v_fma_f32 v122, -v68, v19, v66
	v_mul_f32_e32 v138, v68, v36
	v_mul_f32_e32 v136, v67, v122
	ds_read_b128 v[46:49], v0 offset:2560
	v_fmac_f32_e32 v10, v32, v136
	v_fmac_f32_e32 v11, v33, v136
	v_fmac_f32_e32 v12, v34, v136
	v_fmac_f32_e32 v13, v35, v136
	v_fmac_f32_e32 v138, v69, v136
	ds_read_b128 v[62:65], v1 offset:4224
	s_nop 0
	v_mov_b32_dpp v16, v138 quad_perm:[0,1,2,3] row_mask:0xf bank_mask:0x8
	v_cndmask_b32_e64 v17, v9, v14, s[6:7]
	v_cndmask_b32_e64 v17, v17, v15, s[8:9]
	v_cndmask_b32_e64 v17, v17, v16, s[10:11]
	v_cvt_pk_bf16_f32 v18, v17, v17
	ds_write_b16 v140, v18 offset:9344
	v_add_u32_e32 v140, 0x100, v140
	s_and_b32 s24, s12, 15
	s_cmp_eq_u32 s24, 1
	s_cbranch_scc0 .Lls3_16_noflush
	ds_read_b64 v[142:143], v141 offset:9216
	s_waitcnt lgkmcnt(0)
	global_store_dwordx2 v7, v[142:143], s[94:95]
	v_add_u32_e32 v7, 0x20000, v7
	s_nop 0
	ds_read_b64 v[142:143], v141 offset:9728
	s_waitcnt lgkmcnt(0)
	global_store_dwordx2 v7, v[142:143], s[94:95]
	v_add_u32_e32 v7, 0x20000, v7
	s_nop 0
	ds_read_b64 v[142:143], v141 offset:10240
	s_waitcnt lgkmcnt(0)
	global_store_dwordx2 v7, v[142:143], s[94:95]
	v_add_u32_e32 v7, 0x20000, v7
	s_nop 0
	ds_read_b64 v[142:143], v141 offset:10752
	s_waitcnt lgkmcnt(0)
	global_store_dwordx2 v7, v[142:143], s[94:95]
	v_add_u32_e32 v7, 0x20000, v7
	s_nop 0
	ds_read_b64 v[142:143], v141 offset:11264
	s_waitcnt lgkmcnt(0)
	global_store_dwordx2 v7, v[142:143], s[94:95]
	v_add_u32_e32 v7, 0x20000, v7
	s_nop 0
	ds_read_b64 v[142:143], v141 offset:11776
	s_waitcnt lgkmcnt(0)
	global_store_dwordx2 v7, v[142:143], s[94:95]
	v_add_u32_e32 v7, 0x20000, v7
	s_nop 0
	ds_read_b64 v[142:143], v141 offset:12288
	s_waitcnt lgkmcnt(0)
	global_store_dwordx2 v7, v[142:143], s[94:95]
	v_add_u32_e32 v7, 0x20000, v7
	s_nop 0
	ds_read_b64 v[142:143], v141 offset:12800
	s_waitcnt lgkmcnt(0)
	global_store_dwordx2 v7, v[142:143], s[94:95]
	v_add_u32_e32 v7, 0x20000, v7
	s_nop 0
	v_subrev_u32_e32 v140, 0x1000, v140
.Lls3_16_noflush:
	s_sub_u32 s12, s12, 1
	s_cmp_lg_u32 s12, 0
	s_cbranch_scc1 .Lls3_16_loop
	global_store_dword v139, v10, s[26:27] offset:0
	global_store_dword v139, v11, s[26:27] offset:256
	global_store_dword v139, v12, s[26:27] offset:512
	global_store_dword v139, v13, s[26:27] offset:768
	s_waitcnt vmcnt(0) lgkmcnt(0)
	s_setprio 0
	s_branch .Lls_done
.Lls0_8_entry:
	v_and_b32_e32 v98, 63, v196
	v_and_b32_e32 v99, 7, v98
	v_lshrrev_b32_e32 v100, 3, v98
	s_min_u32 s29, s0, 4
	s_mul_i32 s29, s29, 0x5600
	v_and_b32_e32 v101, 3, v99
	v_cmp_eq_u32_e64 s[6:7], 1, v101
	v_cmp_eq_u32_e64 s[8:9], 2, v101
	v_cmp_eq_u32_e64 s[10:11], 3, v101
	v_lshl_add_u32 v0, v99, 5, s29
	v_lshl_add_u32 v1, v100, 2, s29
	s_lshl_b32 s37, s16, 11
	v_lshrrev_b32_e32 v99, 3, v98
	v_and_b32_e32 v100, 7, v98
	v_add_u32_e32 v101, s37, v99
	s_lshl_b32 s21, s17, 7
	s_add_u32 s21, s21, 0x10800000
	v_mul_u32_u24_e32 v5, 0xd00, v101
	v_lshl_add_u32 v5, v100, 4, v5
	v_add_u32_e32 v5, s21, v5
	v_lshlrev_b32_e32 v2, 8, v99
	v_lshl_add_u32 v2, v100, 5, v2
	v_add_u32_e32 v2, s29, v2
	v_lshrrev_b32_e32 v100, 3, v98
	v_and_b32_e32 v99, 7, v98
	v_add_u32_e32 v101, s37, v100
	s_lshl_b32 s22, s14, 3
	s_lshl_b32 s21, s17, 6
	s_add_u32 s21, s21, s22
	s_lshl_b32 s44, s21, 1
	s_add_u32 s44, s44, 0x8400400
	v_lshlrev_b32_e32 v6, 13, v101
	v_lshlrev_b32_e32 v4, 5, v100
	v_lshl_add_u32 v4, v99, 2, v4
	v_lshl_add_u32 v6, v99, 1, v6
	v_add_u32_e32 v6, s44, v6
	v_add_u32_e32 v4, s29, v4
	v_and_b32_e32 v99, 7, v98
	v_lshrrev_b32_e32 v100, 3, v98
	v_add_u32_e32 v101, s37, v98
	v_lshlrev_b32_e32 v7, 11, v101
	s_lshl_b32 s44, s21, 1
	s_add_u32 s44, s44, 0x6300000
	v_add_u32_e32 v7, s44, v7
	s_lshl_b32 s44, s28, 3
	s_add_u32 s44, s44, s16
	s_lshl_b32 s44, s44, 2
	s_add_u32 s44, s44, s17
	s_mul_i32 s44, s44, 0x4000
	s_add_u32 s44, s44, 0x4200000
	s_lshl_b32 s24, s22, 2
	s_add_u32 s44, s44, s24
	v_lshlrev_b32_e32 v111, 11, v99
	v_lshl_add_u32 v111, v100, 2, v111
	v_add_u32_e32 v111, s44, v111
	v_readlane_b32 s26, v253, 29
	v_readlane_b32 s27, v253, 30
	v_lshlrev_b32_e32 v112, 4, v99
	v_lshl_add_u32 v112, v100, 1, v112
	v_add_u32_e32 v112, s29, v112
	v_lshl_add_u32 v113, v98, 4, s29
	s_lshr_b32 s44, 0x80000, s17
	s_sub_u32 s44, 0x3f800000, s44
	s_mov_b32 s45, s44
	v_mov_b32_e32 v98, s45
	v_log_f32_e32 v98, v98
	v_lshrrev_b32_e32 v99, 3, v196
	v_and_b32_e32 v99, 7, v99
	v_add_u32_e32 v100, 1, v99
	v_cvt_f32_u32_e32 v100, v100
	v_mul_f32_e32 v100, v98, v100
	v_exp_f32_e32 v107, v100
	v_sub_f32_e32 v101, 0, v100
	v_exp_f32_e32 v103, v101
	v_add_u32_e32 v100, 9, v99
	v_cvt_f32_u32_e32 v100, v100
	v_mul_f32_e32 v100, v98, v100
	v_exp_f32_e32 v108, v100
	v_sub_f32_e32 v101, 0, v100
	v_exp_f32_e32 v104, v101
	v_add_u32_e32 v100, 17, v99
	v_cvt_f32_u32_e32 v100, v100
	v_mul_f32_e32 v100, v98, v100
	v_exp_f32_e32 v109, v100
	v_sub_f32_e32 v101, 0, v100
	v_exp_f32_e32 v105, v101
	v_add_u32_e32 v100, 25, v99
	v_cvt_f32_u32_e32 v100, v100
	v_mul_f32_e32 v100, v98, v100
	v_exp_f32_e32 v110, v100
	v_sub_f32_e32 v101, 0, v100
	v_exp_f32_e32 v106, v101
	v_mul_f32_e32 v100, 0x42000000, v98
	v_exp_f32_e32 v100, v100
	s_nop 1
	v_readfirstlane_b32 s44, v100
	v_mov_b32_e32 v8, 0
	v_mov_b32_e32 v9, 0
	v_mov_b32_e32 v10, 0
	v_mov_b32_e32 v11, 0
	v_mov_b32_e32 v12, 0
	v_mov_b32_e32 v13, 0
	v_mov_b32_e32 v14, 0
	v_mov_b32_e32 v15, 0
	v_mov_b32_e32 v16, 0
	v_mov_b32_e32 v17, 0
	v_mov_b32_e32 v18, 0
	v_mov_b32_e32 v19, 0
	v_mov_b32_e32 v36, 0
	v_mov_b32_e32 v102, 0
	s_setprio 2
	s_movk_i32 s12, 64
	s_nop 0
	global_load_dwordx4 v[62:65], v5, s[94:95]
	global_load_dwordx4 v[66:69], v5, s[94:95] offset:512
	global_load_ushort v31, v6, s[94:95]
	v_add_u32_e32 v5, 0x6800, v5
	v_add_u32_e32 v6, 0x10000, v6
	s_waitcnt vmcnt(0)
	s_waitcnt vmcnt(1)
	v_lshlrev_b32_e32 v94, 16, v66
	v_and_b32_e32 v95, 0xffff0000, v66
	v_lshlrev_b32_e32 v96, 16, v67
	v_and_b32_e32 v97, 0xffff0000, v67
	v_mul_f32_e32 v94, v103, v94
	v_mul_f32_e32 v95, v103, v95
	v_mul_f32_e32 v96, v103, v96
	v_mul_f32_e32 v97, v103, v97
	ds_write_b128 v2, v[94:97] offset:0
	v_lshlrev_b32_e32 v98, 16, v68
	v_and_b32_e32 v99, 0xffff0000, v68
	v_lshlrev_b32_e32 v100, 16, v69
	v_and_b32_e32 v101, 0xffff0000, v69
	v_mul_f32_e32 v98, v103, v98
	v_mul_f32_e32 v99, v103, v99
	v_mul_f32_e32 v100, v103, v100
	v_mul_f32_e32 v101, v103, v101
	ds_write_b128 v2, v[98:101] offset:16
	v_lshlrev_b32_e32 v94, 16, v62
	v_and_b32_e32 v95, 0xffff0000, v62
	v_lshlrev_b32_e32 v96, 16, v63
	v_and_b32_e32 v97, 0xffff0000, v63
	v_mul_f32_e32 v94, v107, v94
	v_mul_f32_e32 v95, v107, v95
	v_mul_f32_e32 v96, v107, v96
	v_mul_f32_e32 v97, v107, v97
	ds_write_b128 v2, v[94:97] offset:2048
	v_lshlrev_b32_e32 v98, 16, v64
	v_and_b32_e32 v99, 0xffff0000, v64
	v_lshlrev_b32_e32 v100, 16, v65
	v_and_b32_e32 v101, 0xffff0000, v65
	v_mul_f32_e32 v98, v107, v98
	v_mul_f32_e32 v99, v107, v99
	v_mul_f32_e32 v100, v107, v100
	v_mul_f32_e32 v101, v107, v101
	ds_write_b128 v2, v[98:101] offset:2064
	s_waitcnt vmcnt(0)
	v_lshlrev_b32_e32 v31, 16, v31
	s_nop 0
	ds_write_b32 v4, v31 offset:4096
	global_load_dwordx4 v[70:73], v5, s[94:95]
	global_load_dwordx4 v[74:77], v5, s[94:95] offset:512
	global_load_ushort v33, v6, s[94:95]
	v_add_u32_e32 v5, 0x6800, v5
	v_add_u32_e32 v6, 0x10000, v6
	global_load_dwordx4 v[78:81], v5, s[94:95]
	global_load_dwordx4 v[82:85], v5, s[94:95] offset:512
	global_load_ushort v34, v6, s[94:95]
	v_add_u32_e32 v5, 0x6800, v5
	v_add_u32_e32 v6, 0x10000, v6
	global_load_dwordx4 v[86:89], v5, s[94:95]
	global_load_dwordx4 v[90:93], v5, s[94:95] offset:512
	global_load_ushort v35, v6, s[94:95]
	v_add_u32_e32 v5, 0x6800, v5
	v_add_u32_e32 v6, 0x10000, v6
	global_load_dwordx4 v[62:65], v5, s[94:95]
	global_load_dwordx4 v[66:69], v5, s[94:95] offset:512
	global_load_ushort v31, v6, s[94:95]
	v_add_u32_e32 v5, 0x6800, v5
	v_add_u32_e32 v6, 0x10000, v6
	ds_read_b128 v[22:25], v0 offset:0
	ds_read_b128 v[26:29], v0 offset:16
	ds_read_b128 v[46:49], v0 offset:2048
	ds_read_b128 v[50:53], v0 offset:2064
	ds_read_b32 v30, v1 offset:4096
.Lls0_8_loop:
	s_waitcnt lgkmcnt(0)
	ds_read_b128 v[38:41], v0 offset:256
	ds_read_b128 v[42:45], v0 offset:272
	ds_read_b128 v[54:57], v0 offset:2304
	ds_read_b128 v[58:61], v0 offset:2320
	ds_read_b32 v32, v1 offset:4128
	v_fmac_f32_e32 v8, v22, v30
	v_add_f32_dpp v102, v102, v102 quad_perm:[1,0,3,2] row_mask:0xf bank_mask:0xf bound_ctrl:1
	v_fmac_f32_e32 v9, v23, v30
	v_mul_f32_e32 v36, v46, v8
	v_add_f32_dpp v102, v102, v102 quad_perm:[2,3,0,1] row_mask:0xf bank_mask:0xf bound_ctrl:1
	v_fmac_f32_e32 v10, v24, v30
	v_fmac_f32_e32 v36, v47, v9
	v_add_f32_dpp v19, v102, v102 row_half_mirror row_mask:0xf bank_mask:0xa bound_ctrl:1
	v_fmac_f32_e32 v11, v25, v30
	v_fmac_f32_e32 v36, v48, v10
	v_fmac_f32_e32 v12, v26, v30
	v_fmac_f32_e32 v36, v49, v11
	v_fmac_f32_e32 v13, v27, v30
	v_fmac_f32_e32 v36, v50, v12
	v_fmac_f32_e32 v14, v28, v30
	v_fmac_f32_e32 v36, v51, v13
	v_fmac_f32_e32 v15, v29, v30
	v_fmac_f32_e32 v36, v52, v14
	v_fmac_f32_e32 v36, v53, v15
	s_waitcnt vmcnt(10)
	v_lshlrev_b32_e32 v94, 16, v74
	v_and_b32_e32 v95, 0xffff0000, v74
	v_lshlrev_b32_e32 v96, 16, v75
	v_and_b32_e32 v97, 0xffff0000, v75
	v_mul_f32_e32 v94, v104, v94
	v_mul_f32_e32 v95, v104, v95
	v_mul_f32_e32 v96, v104, v96
	v_mul_f32_e32 v97, v104, v97
	ds_write_b128 v2, v[94:97] offset:4352
	v_lshlrev_b32_e32 v98, 16, v76
	s_waitcnt lgkmcnt(1)
	ds_read_b128 v[22:25], v0 offset:512
	ds_read_b128 v[26:29], v0 offset:528
	ds_read_b128 v[46:49], v0 offset:2560
	ds_read_b128 v[50:53], v0 offset:2576
	ds_read_b32 v30, v1 offset:4160
	v_fmac_f32_e32 v8, v38, v32
	v_add_f32_dpp v36, v36, v36 quad_perm:[1,0,3,2] row_mask:0xf bank_mask:0xf bound_ctrl:1
	v_fmac_f32_e32 v9, v39, v32
	v_mul_f32_e32 v102, v54, v8
	v_add_f32_dpp v36, v36, v36 quad_perm:[2,3,0,1] row_mask:0xf bank_mask:0xf bound_ctrl:1
	v_fmac_f32_e32 v10, v40, v32
	v_fmac_f32_e32 v102, v55, v9
	v_add_f32_dpp v16, v36, v36 row_half_mirror row_mask:0xf bank_mask:0x5 bound_ctrl:1
	v_fmac_f32_e32 v11, v41, v32
	v_fmac_f32_e32 v102, v56, v10
	v_fmac_f32_e32 v12, v42, v32
	v_fmac_f32_e32 v102, v57, v11
	v_fmac_f32_e32 v13, v43, v32
	v_fmac_f32_e32 v102, v58, v12
	v_fmac_f32_e32 v14, v44, v32
	v_fmac_f32_e32 v102, v59, v13
	v_fmac_f32_e32 v15, v45, v32
	v_fmac_f32_e32 v102, v60, v14
	v_fmac_f32_e32 v102, v61, v15
	v_and_b32_e32 v99, 0xffff0000, v76
	v_lshlrev_b32_e32 v100, 16, v77
	v_and_b32_e32 v101, 0xffff0000, v77
	v_mul_f32_e32 v98, v104, v98
	v_mul_f32_e32 v99, v104, v99
	v_mul_f32_e32 v100, v104, v100
	v_mul_f32_e32 v101, v104, v101
	ds_write_b128 v2, v[98:101] offset:4368
	v_lshlrev_b32_e32 v94, 16, v70
	v_and_b32_e32 v95, 0xffff0000, v70
	v_lshlrev_b32_e32 v96, 16, v71
	s_waitcnt lgkmcnt(1)
	ds_read_b128 v[38:41], v0 offset:768
	ds_read_b128 v[42:45], v0 offset:784
	ds_read_b128 v[54:57], v0 offset:2816
	ds_read_b128 v[58:61], v0 offset:2832
	ds_read_b32 v32, v1 offset:4192
	v_fmac_f32_e32 v8, v22, v30
	v_add_f32_dpp v102, v102, v102 quad_perm:[1,0,3,2] row_mask:0xf bank_mask:0xf bound_ctrl:1
	v_fmac_f32_e32 v9, v23, v30
	v_mul_f32_e32 v36, v46, v8
	v_add_f32_dpp v102, v102, v102 quad_perm:[2,3,0,1] row_mask:0xf bank_mask:0xf bound_ctrl:1
	v_fmac_f32_e32 v10, v24, v30
	v_fmac_f32_e32 v36, v47, v9
	v_add_f32_dpp v17, v102, v102 row_half_mirror row_mask:0xf bank_mask:0x5 bound_ctrl:1
	v_fmac_f32_e32 v11, v25, v30
	v_fmac_f32_e32 v36, v48, v10
	v_fmac_f32_e32 v12, v26, v30
	v_fmac_f32_e32 v36, v49, v11
	v_fmac_f32_e32 v13, v27, v30
	v_fmac_f32_e32 v36, v50, v12
	v_fmac_f32_e32 v14, v28, v30
	v_fmac_f32_e32 v36, v51, v13
	v_fmac_f32_e32 v15, v29, v30
	v_fmac_f32_e32 v36, v52, v14
	v_fmac_f32_e32 v36, v53, v15
	v_and_b32_e32 v97, 0xffff0000, v71
	v_mul_f32_e32 v94, v108, v94
	v_mul_f32_e32 v95, v108, v95
	v_mul_f32_e32 v96, v108, v96
	v_mul_f32_e32 v97, v108, v97
	ds_write_b128 v2, v[94:97] offset:6400
	v_lshlrev_b32_e32 v98, 16, v72
	v_and_b32_e32 v99, 0xffff0000, v72
	v_lshlrev_b32_e32 v100, 16, v73
	v_and_b32_e32 v101, 0xffff0000, v73
	v_mul_f32_e32 v98, v108, v98
	s_waitcnt lgkmcnt(1)
	ds_read_b128 v[22:25], v0 offset:1024
	ds_read_b128 v[26:29], v0 offset:1040
	ds_read_b128 v[46:49], v0 offset:3072
	ds_read_b128 v[50:53], v0 offset:3088
	ds_read_b32 v30, v1 offset:4224
	v_fmac_f32_e32 v8, v38, v32
	v_add_f32_dpp v36, v36, v36 quad_perm:[1,0,3,2] row_mask:0xf bank_mask:0xf bound_ctrl:1
	v_fmac_f32_e32 v9, v39, v32
	v_mul_f32_e32 v102, v54, v8
	v_add_f32_dpp v36, v36, v36 quad_perm:[2,3,0,1] row_mask:0xf bank_mask:0xf bound_ctrl:1
	v_fmac_f32_e32 v10, v40, v32
	v_fmac_f32_e32 v102, v55, v9
	v_add_f32_dpp v18, v36, v36 row_half_mirror row_mask:0xf bank_mask:0x5 bound_ctrl:1
	v_fmac_f32_e32 v11, v41, v32
	v_fmac_f32_e32 v102, v56, v10
	v_fmac_f32_e32 v12, v42, v32
	v_fmac_f32_e32 v102, v57, v11
	v_fmac_f32_e32 v13, v43, v32
	v_fmac_f32_e32 v102, v58, v12
	v_fmac_f32_e32 v14, v44, v32
	v_fmac_f32_e32 v102, v59, v13
	v_fmac_f32_e32 v15, v45, v32
	v_fmac_f32_e32 v102, v60, v14
	v_fmac_f32_e32 v102, v61, v15
	v_mul_f32_e32 v99, v108, v99
	v_mul_f32_e32 v100, v108, v100
	v_mul_f32_e32 v101, v108, v101
	ds_write_b128 v2, v[98:101] offset:6416
	s_waitcnt vmcnt(9)
	v_lshlrev_b32_e32 v33, 16, v33
	s_nop 0
	ds_write_b32 v4, v33 offset:8448
	s_waitcnt lgkmcnt(2)
	ds_read_b128 v[38:41], v0 offset:1280
	ds_read_b128 v[42:45], v0 offset:1296
	ds_read_b128 v[54:57], v0 offset:3328
	ds_read_b128 v[58:61], v0 offset:3344
	ds_read_b32 v32, v1 offset:4256
	v_fmac_f32_e32 v8, v22, v30
	v_add_f32_dpp v102, v102, v102 quad_perm:[1,0,3,2] row_mask:0xf bank_mask:0xf bound_ctrl:1
	v_fmac_f32_e32 v9, v23, v30
	v_mul_f32_e32 v36, v46, v8
	v_add_f32_dpp v102, v102, v102 quad_perm:[2,3,0,1] row_mask:0xf bank_mask:0xf bound_ctrl:1
	v_fmac_f32_e32 v10, v24, v30
	v_fmac_f32_e32 v36, v47, v9
	v_add_f32_dpp v19, v102, v102 row_half_mirror row_mask:0xf bank_mask:0x5 bound_ctrl:1
	v_fmac_f32_e32 v11, v25, v30
	v_fmac_f32_e32 v36, v48, v10
	v_fmac_f32_e32 v12, v26, v30
	v_fmac_f32_e32 v36, v49, v11
	v_fmac_f32_e32 v13, v27, v30
	v_fmac_f32_e32 v36, v50, v12
	v_fmac_f32_e32 v14, v28, v30
	v_fmac_f32_e32 v36, v51, v13
	v_fmac_f32_e32 v15, v29, v30
	v_fmac_f32_e32 v36, v52, v14
	v_fmac_f32_e32 v36, v53, v15
	global_load_dwordx4 v[70:73], v5, s[94:95]
	global_load_dwordx4 v[74:77], v5, s[94:95] offset:512
	global_load_ushort v33, v6, s[94:95]
	v_add_u32_e32 v5, 0x6800, v5
	v_add_u32_e32 v6, 0x10000, v6
	s_waitcnt lgkmcnt(0)
	ds_read_b128 v[22:25], v0 offset:1536
	ds_read_b128 v[26:29], v0 offset:1552
	ds_read_b128 v[46:49], v0 offset:3584
	ds_read_b128 v[50:53], v0 offset:3600
	ds_read_b32 v30, v1 offset:4288
	v_fmac_f32_e32 v8, v38, v32
	v_add_f32_dpp v36, v36, v36 quad_perm:[1,0,3,2] row_mask:0xf bank_mask:0xf bound_ctrl:1
	v_fmac_f32_e32 v9, v39, v32
	v_mul_f32_e32 v102, v54, v8
	v_add_f32_dpp v36, v36, v36 quad_perm:[2,3,0,1] row_mask:0xf bank_mask:0xf bound_ctrl:1
	v_fmac_f32_e32 v10, v40, v32
	v_fmac_f32_e32 v102, v55, v9
	v_add_f32_dpp v16, v36, v36 row_half_mirror row_mask:0xf bank_mask:0xa bound_ctrl:1
	v_fmac_f32_e32 v11, v41, v32
	v_fmac_f32_e32 v102, v56, v10
	v_fmac_f32_e32 v12, v42, v32
	v_fmac_f32_e32 v102, v57, v11
	v_fmac_f32_e32 v13, v43, v32
	v_fmac_f32_e32 v102, v58, v12
	v_fmac_f32_e32 v14, v44, v32
	v_fmac_f32_e32 v102, v59, v13
	v_fmac_f32_e32 v15, v45, v32
	v_fmac_f32_e32 v102, v60, v14
	v_fmac_f32_e32 v102, v61, v15
	s_waitcnt lgkmcnt(0)
	ds_read_b128 v[38:41], v0 offset:1792
	ds_read_b128 v[42:45], v0 offset:1808
	ds_read_b128 v[54:57], v0 offset:3840
	ds_read_b128 v[58:61], v0 offset:3856
	ds_read_b32 v32, v1 offset:4320
	v_fmac_f32_e32 v8, v22, v30
	v_add_f32_dpp v102, v102, v102 quad_perm:[1,0,3,2] row_mask:0xf bank_mask:0xf bound_ctrl:1
	v_fmac_f32_e32 v9, v23, v30
	v_mul_f32_e32 v36, v46, v8
	v_add_f32_dpp v102, v102, v102 quad_perm:[2,3,0,1] row_mask:0xf bank_mask:0xf bound_ctrl:1
	v_fmac_f32_e32 v10, v24, v30
	v_fmac_f32_e32 v36, v47, v9
	v_add_f32_dpp v17, v102, v102 row_half_mirror row_mask:0xf bank_mask:0xa bound_ctrl:1
	v_fmac_f32_e32 v11, v25, v30
	v_fmac_f32_e32 v36, v48, v10
	v_fmac_f32_e32 v12, v26, v30
	v_fmac_f32_e32 v36, v49, v11
	v_fmac_f32_e32 v13, v27, v30
	v_fmac_f32_e32 v36, v50, v12
	v_fmac_f32_e32 v14, v28, v30
	v_fmac_f32_e32 v36, v51, v13
	v_fmac_f32_e32 v15, v29, v30
	v_fmac_f32_e32 v36, v52, v14
	v_fmac_f32_e32 v36, v53, v15
	s_waitcnt lgkmcnt(0)
	ds_read_b128 v[22:25], v0 offset:4352
	ds_read_b128 v[26:29], v0 offset:4368
	ds_read_b128 v[46:49], v0 offset:6400
	ds_read_b128 v[50:53], v0 offset:6416
	ds_read_b32 v30, v1 offset:8448
	v_fmac_f32_e32 v8, v38, v32
	v_add_f32_dpp v36, v36, v36 quad_perm:[1,0,3,2] row_mask:0xf bank_mask:0xf bound_ctrl:1
	v_fmac_f32_e32 v9, v39, v32
	v_mul_f32_e32 v102, v54, v8
	v_add_f32_dpp v36, v36, v36 quad_perm:[2,3,0,1] row_mask:0xf bank_mask:0xf bound_ctrl:1
	v_fmac_f32_e32 v10, v40, v32
	v_fmac_f32_e32 v102, v55, v9
	v_add_f32_dpp v18, v36, v36 row_half_mirror row_mask:0xf bank_mask:0xa bound_ctrl:1
	v_fmac_f32_e32 v11, v41, v32
	v_fmac_f32_e32 v102, v56, v10
	v_fmac_f32_e32 v12, v42, v32
	v_fmac_f32_e32 v102, v57, v11
	v_fmac_f32_e32 v13, v43, v32
	v_fmac_f32_e32 v102, v58, v12
	v_fmac_f32_e32 v14, v44, v32
	v_fmac_f32_e32 v102, v59, v13
	v_fmac_f32_e32 v15, v45, v32
	v_fmac_f32_e32 v102, v60, v14
	v_fmac_f32_e32 v102, v61, v15
	s_nop 1
	v_add_f32_dpp v102, v102, v102 quad_perm:[1,0,3,2] row_mask:0xf bank_mask:0xf bound_ctrl:1
	s_nop 1
	v_add_f32_dpp v102, v102, v102 quad_perm:[2,3,0,1] row_mask:0xf bank_mask:0xf bound_ctrl:1
	s_nop 1
	v_add_f32_dpp v19, v102, v102 row_half_mirror row_mask:0xf bank_mask:0xa bound_ctrl:1
	v_mov_b32_e32 v102, 0
	v_cndmask_b32_e64 v20, v16, v17, s[6:7]
	v_cndmask_b32_e64 v20, v20, v18, s[8:9]
	v_cndmask_b32_e64 v20, v20, v19, s[10:11]
	v_cvt_pk_bf16_f32 v21, v20, v20
	ds_write_b16 v112, v21 offset:8704
	s_waitcnt lgkmcnt(1)
	ds_read_b128 v[38:41], v0 offset:4608
	ds_read_b128 v[42:45], v0 offset:4624
	ds_read_b128 v[54:57], v0 offset:6656
	ds_read_b128 v[58:61], v0 offset:6672
	ds_read_b32 v32, v1 offset:8480
	v_fmac_f32_e32 v8, v22, v30
	v_add_f32_dpp v102, v102, v102 quad_perm:[1,0,3,2] row_mask:0xf bank_mask:0xf bound_ctrl:1
	v_fmac_f32_e32 v9, v23, v30
	v_mul_f32_e32 v36, v46, v8
	v_add_f32_dpp v102, v102, v102 quad_perm:[2,3,0,1] row_mask:0xf bank_mask:0xf bound_ctrl:1
	v_fmac_f32_e32 v10, v24, v30
	v_fmac_f32_e32 v36, v47, v9
	v_add_f32_dpp v19, v102, v102 row_half_mirror row_mask:0xf bank_mask:0xa bound_ctrl:1
	v_fmac_f32_e32 v11, v25, v30
	v_fmac_f32_e32 v36, v48, v10
	v_fmac_f32_e32 v12, v26, v30
	v_fmac_f32_e32 v36, v49, v11
	v_fmac_f32_e32 v13, v27, v30
	v_fmac_f32_e32 v36, v50, v12
	v_fmac_f32_e32 v14, v28, v30
	v_fmac_f32_e32 v36, v51, v13
	v_fmac_f32_e32 v15, v29, v30
	v_fmac_f32_e32 v36, v52, v14
	v_fmac_f32_e32 v36, v53, v15
	s_waitcnt vmcnt(10)
	v_lshlrev_b32_e32 v94, 16, v82
	v_and_b32_e32 v95, 0xffff0000, v82
	v_lshlrev_b32_e32 v96, 16, v83
	v_and_b32_e32 v97, 0xffff0000, v83
	v_mul_f32_e32 v94, v105, v94
	v_mul_f32_e32 v95, v105, v95
	v_mul_f32_e32 v96, v105, v96
	v_mul_f32_e32 v97, v105, v97
	ds_write_b128 v2, v[94:97] offset:0
	v_lshlrev_b32_e32 v98, 16, v84
	s_waitcnt lgkmcnt(1)
	ds_read_b128 v[22:25], v0 offset:4864
	ds_read_b128 v[26:29], v0 offset:4880
	ds_read_b128 v[46:49], v0 offset:6912
	ds_read_b128 v[50:53], v0 offset:6928
	ds_read_b32 v30, v1 offset:8512
	v_fmac_f32_e32 v8, v38, v32
	v_add_f32_dpp v36, v36, v36 quad_perm:[1,0,3,2] row_mask:0xf bank_mask:0xf bound_ctrl:1
	v_fmac_f32_e32 v9, v39, v32
	v_mul_f32_e32 v102, v54, v8
	v_add_f32_dpp v36, v36, v36 quad_perm:[2,3,0,1] row_mask:0xf bank_mask:0xf bound_ctrl:1
	v_fmac_f32_e32 v10, v40, v32
	v_fmac_f32_e32 v102, v55, v9
	v_add_f32_dpp v16, v36, v36 row_half_mirror row_mask:0xf bank_mask:0x5 bound_ctrl:1
	v_fmac_f32_e32 v11, v41, v32
	v_fmac_f32_e32 v102, v56, v10
	v_fmac_f32_e32 v12, v42, v32
	v_fmac_f32_e32 v102, v57, v11
	v_fmac_f32_e32 v13, v43, v32
	v_fmac_f32_e32 v102, v58, v12
	v_fmac_f32_e32 v14, v44, v32
	v_fmac_f32_e32 v102, v59, v13
	v_fmac_f32_e32 v15, v45, v32
	v_fmac_f32_e32 v102, v60, v14
	v_fmac_f32_e32 v102, v61, v15
	v_and_b32_e32 v99, 0xffff0000, v84
	v_lshlrev_b32_e32 v100, 16, v85
	v_and_b32_e32 v101, 0xffff0000, v85
	v_mul_f32_e32 v98, v105, v98
	v_mul_f32_e32 v99, v105, v99
	v_mul_f32_e32 v100, v105, v100
	v_mul_f32_e32 v101, v105, v101
	ds_write_b128 v2, v[98:101] offset:16
	v_lshlrev_b32_e32 v94, 16, v78
	v_and_b32_e32 v95, 0xffff0000, v78
	v_lshlrev_b32_e32 v96, 16, v79
	s_waitcnt lgkmcnt(1)
	ds_read_b128 v[38:41], v0 offset:5120
	ds_read_b128 v[42:45], v0 offset:5136
	ds_read_b128 v[54:57], v0 offset:7168
	ds_read_b128 v[58:61], v0 offset:7184
	ds_read_b32 v32, v1 offset:8544
	v_fmac_f32_e32 v8, v22, v30
	v_add_f32_dpp v102, v102, v102 quad_perm:[1,0,3,2] row_mask:0xf bank_mask:0xf bound_ctrl:1
	v_fmac_f32_e32 v9, v23, v30
	v_mul_f32_e32 v36, v46, v8
	v_add_f32_dpp v102, v102, v102 quad_perm:[2,3,0,1] row_mask:0xf bank_mask:0xf bound_ctrl:1
	v_fmac_f32_e32 v10, v24, v30
	v_fmac_f32_e32 v36, v47, v9
	v_add_f32_dpp v17, v102, v102 row_half_mirror row_mask:0xf bank_mask:0x5 bound_ctrl:1
	v_fmac_f32_e32 v11, v25, v30
	v_fmac_f32_e32 v36, v48, v10
	v_fmac_f32_e32 v12, v26, v30
	v_fmac_f32_e32 v36, v49, v11
	v_fmac_f32_e32 v13, v27, v30
	v_fmac_f32_e32 v36, v50, v12
	v_fmac_f32_e32 v14, v28, v30
	v_fmac_f32_e32 v36, v51, v13
	v_fmac_f32_e32 v15, v29, v30
	v_fmac_f32_e32 v36, v52, v14
	v_fmac_f32_e32 v36, v53, v15
	v_and_b32_e32 v97, 0xffff0000, v79
	v_mul_f32_e32 v94, v109, v94
	v_mul_f32_e32 v95, v109, v95
	v_mul_f32_e32 v96, v109, v96
	v_mul_f32_e32 v97, v109, v97
	ds_write_b128 v2, v[94:97] offset:2048
	v_lshlrev_b32_e32 v98, 16, v80
	v_and_b32_e32 v99, 0xffff0000, v80
	v_lshlrev_b32_e32 v100, 16, v81
	v_and_b32_e32 v101, 0xffff0000, v81
	v_mul_f32_e32 v98, v109, v98
	s_waitcnt lgkmcnt(1)
	ds_read_b128 v[22:25], v0 offset:5376
	ds_read_b128 v[26:29], v0 offset:5392
	ds_read_b128 v[46:49], v0 offset:7424
	ds_read_b128 v[50:53], v0 offset:7440
	ds_read_b32 v30, v1 offset:8576
	v_fmac_f32_e32 v8, v38, v32
	v_add_f32_dpp v36, v36, v36 quad_perm:[1,0,3,2] row_mask:0xf bank_mask:0xf bound_ctrl:1
	v_fmac_f32_e32 v9, v39, v32
	v_mul_f32_e32 v102, v54, v8
	v_add_f32_dpp v36, v36, v36 quad_perm:[2,3,0,1] row_mask:0xf bank_mask:0xf bound_ctrl:1
	v_fmac_f32_e32 v10, v40, v32
	v_fmac_f32_e32 v102, v55, v9
	v_add_f32_dpp v18, v36, v36 row_half_mirror row_mask:0xf bank_mask:0x5 bound_ctrl:1
	v_fmac_f32_e32 v11, v41, v32
	v_fmac_f32_e32 v102, v56, v10
	v_fmac_f32_e32 v12, v42, v32
	v_fmac_f32_e32 v102, v57, v11
	v_fmac_f32_e32 v13, v43, v32
	v_fmac_f32_e32 v102, v58, v12
	v_fmac_f32_e32 v14, v44, v32
	v_fmac_f32_e32 v102, v59, v13
	v_fmac_f32_e32 v15, v45, v32
	v_fmac_f32_e32 v102, v60, v14
	v_fmac_f32_e32 v102, v61, v15
	v_mul_f32_e32 v99, v109, v99
	v_mul_f32_e32 v100, v109, v100
	v_mul_f32_e32 v101, v109, v101
	ds_write_b128 v2, v[98:101] offset:2064
	s_waitcnt vmcnt(9)
	v_lshlrev_b32_e32 v34, 16, v34
	s_nop 0
	ds_write_b32 v4, v34 offset:4096
	s_waitcnt lgkmcnt(2)
	ds_read_b128 v[38:41], v0 offset:5632
	ds_read_b128 v[42:45], v0 offset:5648
	ds_read_b128 v[54:57], v0 offset:7680
	ds_read_b128 v[58:61], v0 offset:7696
	ds_read_b32 v32, v1 offset:8608
	v_fmac_f32_e32 v8, v22, v30
	v_add_f32_dpp v102, v102, v102 quad_perm:[1,0,3,2] row_mask:0xf bank_mask:0xf bound_ctrl:1
	v_fmac_f32_e32 v9, v23, v30
	v_mul_f32_e32 v36, v46, v8
	v_add_f32_dpp v102, v102, v102 quad_perm:[2,3,0,1] row_mask:0xf bank_mask:0xf bound_ctrl:1
	v_fmac_f32_e32 v10, v24, v30
	v_fmac_f32_e32 v36, v47, v9
	v_add_f32_dpp v19, v102, v102 row_half_mirror row_mask:0xf bank_mask:0x5 bound_ctrl:1
	v_fmac_f32_e32 v11, v25, v30
	v_fmac_f32_e32 v36, v48, v10
	v_fmac_f32_e32 v12, v26, v30
	v_fmac_f32_e32 v36, v49, v11
	v_fmac_f32_e32 v13, v27, v30
	v_fmac_f32_e32 v36, v50, v12
	v_fmac_f32_e32 v14, v28, v30
	v_fmac_f32_e32 v36, v51, v13
	v_fmac_f32_e32 v15, v29, v30
	v_fmac_f32_e32 v36, v52, v14
	v_fmac_f32_e32 v36, v53, v15
	global_load_dwordx4 v[78:81], v5, s[94:95]
	global_load_dwordx4 v[82:85], v5, s[94:95] offset:512
	global_load_ushort v34, v6, s[94:95]
	v_add_u32_e32 v5, 0x6800, v5
	v_add_u32_e32 v6, 0x10000, v6
	s_waitcnt lgkmcnt(0)
	ds_read_b128 v[22:25], v0 offset:5888
	ds_read_b128 v[26:29], v0 offset:5904
	ds_read_b128 v[46:49], v0 offset:7936
	ds_read_b128 v[50:53], v0 offset:7952
	ds_read_b32 v30, v1 offset:8640
	v_fmac_f32_e32 v8, v38, v32
	v_add_f32_dpp v36, v36, v36 quad_perm:[1,0,3,2] row_mask:0xf bank_mask:0xf bound_ctrl:1
	v_fmac_f32_e32 v9, v39, v32
	v_mul_f32_e32 v102, v54, v8
	v_add_f32_dpp v36, v36, v36 quad_perm:[2,3,0,1] row_mask:0xf bank_mask:0xf bound_ctrl:1
	v_fmac_f32_e32 v10, v40, v32
	v_fmac_f32_e32 v102, v55, v9
	v_add_f32_dpp v16, v36, v36 row_half_mirror row_mask:0xf bank_mask:0xa bound_ctrl:1
	v_fmac_f32_e32 v11, v41, v32
	v_fmac_f32_e32 v102, v56, v10
	v_fmac_f32_e32 v12, v42, v32
	v_fmac_f32_e32 v102, v57, v11
	v_fmac_f32_e32 v13, v43, v32
	v_fmac_f32_e32 v102, v58, v12
	v_fmac_f32_e32 v14, v44, v32
	v_fmac_f32_e32 v102, v59, v13
	v_fmac_f32_e32 v15, v45, v32
	v_fmac_f32_e32 v102, v60, v14
	v_fmac_f32_e32 v102, v61, v15
	s_waitcnt lgkmcnt(0)
	ds_read_b128 v[38:41], v0 offset:6144
	ds_read_b128 v[42:45], v0 offset:6160
	ds_read_b128 v[54:57], v0 offset:8192
	ds_read_b128 v[58:61], v0 offset:8208
	ds_read_b32 v32, v1 offset:8672
	v_fmac_f32_e32 v8, v22, v30
	v_add_f32_dpp v102, v102, v102 quad_perm:[1,0,3,2] row_mask:0xf bank_mask:0xf bound_ctrl:1
	v_fmac_f32_e32 v9, v23, v30
	v_mul_f32_e32 v36, v46, v8
	v_add_f32_dpp v102, v102, v102 quad_perm:[2,3,0,1] row_mask:0xf bank_mask:0xf bound_ctrl:1
	v_fmac_f32_e32 v10, v24, v30
	v_fmac_f32_e32 v36, v47, v9
	v_add_f32_dpp v17, v102, v102 row_half_mirror row_mask:0xf bank_mask:0xa bound_ctrl:1
	v_fmac_f32_e32 v11, v25, v30
	v_fmac_f32_e32 v36, v48, v10
	v_fmac_f32_e32 v12, v26, v30
	v_fmac_f32_e32 v36, v49, v11
	v_fmac_f32_e32 v13, v27, v30
	v_fmac_f32_e32 v36, v50, v12
	v_fmac_f32_e32 v14, v28, v30
	v_fmac_f32_e32 v36, v51, v13
	v_fmac_f32_e32 v15, v29, v30
	v_fmac_f32_e32 v36, v52, v14
	v_fmac_f32_e32 v36, v53, v15
	s_waitcnt lgkmcnt(0)
	ds_read_b128 v[22:25], v0 offset:0
	ds_read_b128 v[26:29], v0 offset:16
	ds_read_b128 v[46:49], v0 offset:2048
	ds_read_b128 v[50:53], v0 offset:2064
	ds_read_b32 v30, v1 offset:4096
	v_fmac_f32_e32 v8, v38, v32
	v_add_f32_dpp v36, v36, v36 quad_perm:[1,0,3,2] row_mask:0xf bank_mask:0xf bound_ctrl:1
	v_fmac_f32_e32 v9, v39, v32
	v_mul_f32_e32 v102, v54, v8
	v_add_f32_dpp v36, v36, v36 quad_perm:[2,3,0,1] row_mask:0xf bank_mask:0xf bound_ctrl:1
	v_fmac_f32_e32 v10, v40, v32
	v_fmac_f32_e32 v102, v55, v9
	v_add_f32_dpp v18, v36, v36 row_half_mirror row_mask:0xf bank_mask:0xa bound_ctrl:1
	v_fmac_f32_e32 v11, v41, v32
	v_fmac_f32_e32 v102, v56, v10
	v_fmac_f32_e32 v12, v42, v32
	v_fmac_f32_e32 v102, v57, v11
	v_fmac_f32_e32 v13, v43, v32
	v_fmac_f32_e32 v102, v58, v12
	v_fmac_f32_e32 v14, v44, v32
	v_fmac_f32_e32 v102, v59, v13
	v_fmac_f32_e32 v15, v45, v32
	v_fmac_f32_e32 v102, v60, v14
	v_fmac_f32_e32 v102, v61, v15
	s_nop 1
	v_add_f32_dpp v102, v102, v102 quad_perm:[1,0,3,2] row_mask:0xf bank_mask:0xf bound_ctrl:1
	s_nop 1
	v_add_f32_dpp v102, v102, v102 quad_perm:[2,3,0,1] row_mask:0xf bank_mask:0xf bound_ctrl:1
	s_nop 1
	v_add_f32_dpp v19, v102, v102 row_half_mirror row_mask:0xf bank_mask:0xa bound_ctrl:1
	v_mov_b32_e32 v102, 0
	v_cndmask_b32_e64 v20, v16, v17, s[6:7]
	v_cndmask_b32_e64 v20, v20, v18, s[8:9]
	v_cndmask_b32_e64 v20, v20, v19, s[10:11]
	v_cvt_pk_bf16_f32 v21, v20, v20
	ds_write_b16 v112, v21 offset:8832
	s_waitcnt lgkmcnt(1)
	ds_read_b128 v[38:41], v0 offset:256
	ds_read_b128 v[42:45], v0 offset:272
	ds_read_b128 v[54:57], v0 offset:2304
	ds_read_b128 v[58:61], v0 offset:2320
	ds_read_b32 v32, v1 offset:4128
	v_fmac_f32_e32 v8, v22, v30
	v_add_f32_dpp v102, v102, v102 quad_perm:[1,0,3,2] row_mask:0xf bank_mask:0xf bound_ctrl:1
	v_fmac_f32_e32 v9, v23, v30
	v_mul_f32_e32 v36, v46, v8
	v_add_f32_dpp v102, v102, v102 quad_perm:[2,3,0,1] row_mask:0xf bank_mask:0xf bound_ctrl:1
	v_fmac_f32_e32 v10, v24, v30
	v_fmac_f32_e32 v36, v47, v9
	v_add_f32_dpp v19, v102, v102 row_half_mirror row_mask:0xf bank_mask:0xa bound_ctrl:1
	v_fmac_f32_e32 v11, v25, v30
	v_fmac_f32_e32 v36, v48, v10
	v_fmac_f32_e32 v12, v26, v30
	v_fmac_f32_e32 v36, v49, v11
	v_fmac_f32_e32 v13, v27, v30
	v_fmac_f32_e32 v36, v50, v12
	v_fmac_f32_e32 v14, v28, v30
	v_fmac_f32_e32 v36, v51, v13
	v_fmac_f32_e32 v15, v29, v30
	v_fmac_f32_e32 v36, v52, v14
	v_fmac_f32_e32 v36, v53, v15
	s_waitcnt vmcnt(10)
	v_lshlrev_b32_e32 v94, 16, v90
	v_and_b32_e32 v95, 0xffff0000, v90
	v_lshlrev_b32_e32 v96, 16, v91
	v_and_b32_e32 v97, 0xffff0000, v91
	v_mul_f32_e32 v94, v106, v94
	v_mul_f32_e32 v95, v106, v95
	v_mul_f32_e32 v96, v106, v96
	v_mul_f32_e32 v97, v106, v97
	ds_write_b128 v2, v[94:97] offset:4352
	v_lshlrev_b32_e32 v98, 16, v92
	s_waitcnt lgkmcnt(1)
	ds_read_b128 v[22:25], v0 offset:512
	ds_read_b128 v[26:29], v0 offset:528
	ds_read_b128 v[46:49], v0 offset:2560
	ds_read_b128 v[50:53], v0 offset:2576
	ds_read_b32 v30, v1 offset:4160
	v_fmac_f32_e32 v8, v38, v32
	v_add_f32_dpp v36, v36, v36 quad_perm:[1,0,3,2] row_mask:0xf bank_mask:0xf bound_ctrl:1
	v_fmac_f32_e32 v9, v39, v32
	v_mul_f32_e32 v102, v54, v8
	v_add_f32_dpp v36, v36, v36 quad_perm:[2,3,0,1] row_mask:0xf bank_mask:0xf bound_ctrl:1
	v_fmac_f32_e32 v10, v40, v32
	v_fmac_f32_e32 v102, v55, v9
	v_add_f32_dpp v16, v36, v36 row_half_mirror row_mask:0xf bank_mask:0x5 bound_ctrl:1
	v_fmac_f32_e32 v11, v41, v32
	v_fmac_f32_e32 v102, v56, v10
	v_fmac_f32_e32 v12, v42, v32
	v_fmac_f32_e32 v102, v57, v11
	v_fmac_f32_e32 v13, v43, v32
	v_fmac_f32_e32 v102, v58, v12
	v_fmac_f32_e32 v14, v44, v32
	v_fmac_f32_e32 v102, v59, v13
	v_fmac_f32_e32 v15, v45, v32
	v_fmac_f32_e32 v102, v60, v14
	v_fmac_f32_e32 v102, v61, v15
	v_and_b32_e32 v99, 0xffff0000, v92
	v_lshlrev_b32_e32 v100, 16, v93
	v_and_b32_e32 v101, 0xffff0000, v93
	v_mul_f32_e32 v98, v106, v98
	v_mul_f32_e32 v99, v106, v99
	v_mul_f32_e32 v100, v106, v100
	v_mul_f32_e32 v101, v106, v101
	ds_write_b128 v2, v[98:101] offset:4368
	v_lshlrev_b32_e32 v94, 16, v86
	v_and_b32_e32 v95, 0xffff0000, v86
	v_lshlrev_b32_e32 v96, 16, v87
	s_waitcnt lgkmcnt(1)
	ds_read_b128 v[38:41], v0 offset:768
	ds_read_b128 v[42:45], v0 offset:784
	ds_read_b128 v[54:57], v0 offset:2816
	ds_read_b128 v[58:61], v0 offset:2832
	ds_read_b32 v32, v1 offset:4192
	v_fmac_f32_e32 v8, v22, v30
	v_add_f32_dpp v102, v102, v102 quad_perm:[1,0,3,2] row_mask:0xf bank_mask:0xf bound_ctrl:1
	v_fmac_f32_e32 v9, v23, v30
	v_mul_f32_e32 v36, v46, v8
	v_add_f32_dpp v102, v102, v102 quad_perm:[2,3,0,1] row_mask:0xf bank_mask:0xf bound_ctrl:1
	v_fmac_f32_e32 v10, v24, v30
	v_fmac_f32_e32 v36, v47, v9
	v_add_f32_dpp v17, v102, v102 row_half_mirror row_mask:0xf bank_mask:0x5 bound_ctrl:1
	v_fmac_f32_e32 v11, v25, v30
	v_fmac_f32_e32 v36, v48, v10
	v_fmac_f32_e32 v12, v26, v30
	v_fmac_f32_e32 v36, v49, v11
	v_fmac_f32_e32 v13, v27, v30
	v_fmac_f32_e32 v36, v50, v12
	v_fmac_f32_e32 v14, v28, v30
	v_fmac_f32_e32 v36, v51, v13
	v_fmac_f32_e32 v15, v29, v30
	v_fmac_f32_e32 v36, v52, v14
	v_fmac_f32_e32 v36, v53, v15
	v_and_b32_e32 v97, 0xffff0000, v87
	v_mul_f32_e32 v94, v110, v94
	v_mul_f32_e32 v95, v110, v95
	v_mul_f32_e32 v96, v110, v96
	v_mul_f32_e32 v97, v110, v97
	ds_write_b128 v2, v[94:97] offset:6400
	v_lshlrev_b32_e32 v98, 16, v88
	v_and_b32_e32 v99, 0xffff0000, v88
	v_lshlrev_b32_e32 v100, 16, v89
	v_and_b32_e32 v101, 0xffff0000, v89
	v_mul_f32_e32 v98, v110, v98
	s_waitcnt lgkmcnt(1)
	ds_read_b128 v[22:25], v0 offset:1024
	ds_read_b128 v[26:29], v0 offset:1040
	ds_read_b128 v[46:49], v0 offset:3072
	ds_read_b128 v[50:53], v0 offset:3088
	ds_read_b32 v30, v1 offset:4224
	v_fmac_f32_e32 v8, v38, v32
	v_add_f32_dpp v36, v36, v36 quad_perm:[1,0,3,2] row_mask:0xf bank_mask:0xf bound_ctrl:1
	v_fmac_f32_e32 v9, v39, v32
	v_mul_f32_e32 v102, v54, v8
	v_add_f32_dpp v36, v36, v36 quad_perm:[2,3,0,1] row_mask:0xf bank_mask:0xf bound_ctrl:1
	v_fmac_f32_e32 v10, v40, v32
	v_fmac_f32_e32 v102, v55, v9
	v_add_f32_dpp v18, v36, v36 row_half_mirror row_mask:0xf bank_mask:0x5 bound_ctrl:1
	v_fmac_f32_e32 v11, v41, v32
	v_fmac_f32_e32 v102, v56, v10
	v_fmac_f32_e32 v12, v42, v32
	v_fmac_f32_e32 v102, v57, v11
	v_fmac_f32_e32 v13, v43, v32
	v_fmac_f32_e32 v102, v58, v12
	v_fmac_f32_e32 v14, v44, v32
	v_fmac_f32_e32 v102, v59, v13
	v_fmac_f32_e32 v15, v45, v32
	v_fmac_f32_e32 v102, v60, v14
	v_fmac_f32_e32 v102, v61, v15
	v_mul_f32_e32 v99, v110, v99
	v_mul_f32_e32 v100, v110, v100
	v_mul_f32_e32 v101, v110, v101
	ds_write_b128 v2, v[98:101] offset:6416
	s_waitcnt vmcnt(9)
	v_lshlrev_b32_e32 v35, 16, v35
	s_nop 0
	ds_write_b32 v4, v35 offset:8448
	s_waitcnt lgkmcnt(2)
	ds_read_b128 v[38:41], v0 offset:1280
	ds_read_b128 v[42:45], v0 offset:1296
	ds_read_b128 v[54:57], v0 offset:3328
	ds_read_b128 v[58:61], v0 offset:3344
	ds_read_b32 v32, v1 offset:4256
	v_fmac_f32_e32 v8, v22, v30
	v_add_f32_dpp v102, v102, v102 quad_perm:[1,0,3,2] row_mask:0xf bank_mask:0xf bound_ctrl:1
	v_fmac_f32_e32 v9, v23, v30
	v_mul_f32_e32 v36, v46, v8
	v_add_f32_dpp v102, v102, v102 quad_perm:[2,3,0,1] row_mask:0xf bank_mask:0xf bound_ctrl:1
	v_fmac_f32_e32 v10, v24, v30
	v_fmac_f32_e32 v36, v47, v9
	v_add_f32_dpp v19, v102, v102 row_half_mirror row_mask:0xf bank_mask:0x5 bound_ctrl:1
	v_fmac_f32_e32 v11, v25, v30
	v_fmac_f32_e32 v36, v48, v10
	v_fmac_f32_e32 v12, v26, v30
	v_fmac_f32_e32 v36, v49, v11
	v_fmac_f32_e32 v13, v27, v30
	v_fmac_f32_e32 v36, v50, v12
	v_fmac_f32_e32 v14, v28, v30
	v_fmac_f32_e32 v36, v51, v13
	v_fmac_f32_e32 v15, v29, v30
	v_fmac_f32_e32 v36, v52, v14
	v_fmac_f32_e32 v36, v53, v15
	global_load_dwordx4 v[86:89], v5, s[94:95]
	global_load_dwordx4 v[90:93], v5, s[94:95] offset:512
	global_load_ushort v35, v6, s[94:95]
	v_add_u32_e32 v5, 0x6800, v5
	v_add_u32_e32 v6, 0x10000, v6
	s_waitcnt lgkmcnt(0)
	ds_read_b128 v[22:25], v0 offset:1536
	ds_read_b128 v[26:29], v0 offset:1552
	ds_read_b128 v[46:49], v0 offset:3584
	ds_read_b128 v[50:53], v0 offset:3600
	ds_read_b32 v30, v1 offset:4288
	v_fmac_f32_e32 v8, v38, v32
	v_add_f32_dpp v36, v36, v36 quad_perm:[1,0,3,2] row_mask:0xf bank_mask:0xf bound_ctrl:1
	v_fmac_f32_e32 v9, v39, v32
	v_mul_f32_e32 v102, v54, v8
	v_add_f32_dpp v36, v36, v36 quad_perm:[2,3,0,1] row_mask:0xf bank_mask:0xf bound_ctrl:1
	v_fmac_f32_e32 v10, v40, v32
	v_fmac_f32_e32 v102, v55, v9
	v_add_f32_dpp v16, v36, v36 row_half_mirror row_mask:0xf bank_mask:0xa bound_ctrl:1
	v_fmac_f32_e32 v11, v41, v32
	v_fmac_f32_e32 v102, v56, v10
	v_fmac_f32_e32 v12, v42, v32
	v_fmac_f32_e32 v102, v57, v11
	v_fmac_f32_e32 v13, v43, v32
	v_fmac_f32_e32 v102, v58, v12
	v_fmac_f32_e32 v14, v44, v32
	v_fmac_f32_e32 v102, v59, v13
	v_fmac_f32_e32 v15, v45, v32
	v_fmac_f32_e32 v102, v60, v14
	v_fmac_f32_e32 v102, v61, v15
	s_waitcnt lgkmcnt(0)
	ds_read_b128 v[38:41], v0 offset:1792
	ds_read_b128 v[42:45], v0 offset:1808
	ds_read_b128 v[54:57], v0 offset:3840
	ds_read_b128 v[58:61], v0 offset:3856
	ds_read_b32 v32, v1 offset:4320
	v_fmac_f32_e32 v8, v22, v30
	v_add_f32_dpp v102, v102, v102 quad_perm:[1,0,3,2] row_mask:0xf bank_mask:0xf bound_ctrl:1
	v_fmac_f32_e32 v9, v23, v30
	v_mul_f32_e32 v36, v46, v8
	v_add_f32_dpp v102, v102, v102 quad_perm:[2,3,0,1] row_mask:0xf bank_mask:0xf bound_ctrl:1
	v_fmac_f32_e32 v10, v24, v30
	v_fmac_f32_e32 v36, v47, v9
	v_add_f32_dpp v17, v102, v102 row_half_mirror row_mask:0xf bank_mask:0xa bound_ctrl:1
	v_fmac_f32_e32 v11, v25, v30
	v_fmac_f32_e32 v36, v48, v10
	v_fmac_f32_e32 v12, v26, v30
	v_fmac_f32_e32 v36, v49, v11
	v_fmac_f32_e32 v13, v27, v30
	v_fmac_f32_e32 v36, v50, v12
	v_fmac_f32_e32 v14, v28, v30
	v_fmac_f32_e32 v36, v51, v13
	v_fmac_f32_e32 v15, v29, v30
	v_fmac_f32_e32 v36, v52, v14
	v_fmac_f32_e32 v36, v53, v15
	s_waitcnt lgkmcnt(0)
	ds_read_b128 v[22:25], v0 offset:4352
	ds_read_b128 v[26:29], v0 offset:4368
	ds_read_b128 v[46:49], v0 offset:6400
	ds_read_b128 v[50:53], v0 offset:6416
	ds_read_b32 v30, v1 offset:8448
	v_fmac_f32_e32 v8, v38, v32
	v_add_f32_dpp v36, v36, v36 quad_perm:[1,0,3,2] row_mask:0xf bank_mask:0xf bound_ctrl:1
	v_fmac_f32_e32 v9, v39, v32
	v_mul_f32_e32 v102, v54, v8
	v_add_f32_dpp v36, v36, v36 quad_perm:[2,3,0,1] row_mask:0xf bank_mask:0xf bound_ctrl:1
	v_fmac_f32_e32 v10, v40, v32
	v_fmac_f32_e32 v102, v55, v9
	v_add_f32_dpp v18, v36, v36 row_half_mirror row_mask:0xf bank_mask:0xa bound_ctrl:1
	v_fmac_f32_e32 v11, v41, v32
	v_fmac_f32_e32 v102, v56, v10
	v_fmac_f32_e32 v12, v42, v32
	v_fmac_f32_e32 v102, v57, v11
	v_fmac_f32_e32 v13, v43, v32
	v_fmac_f32_e32 v102, v58, v12
	v_fmac_f32_e32 v14, v44, v32
	v_fmac_f32_e32 v102, v59, v13
	v_fmac_f32_e32 v15, v45, v32
	v_fmac_f32_e32 v102, v60, v14
	v_fmac_f32_e32 v102, v61, v15
	s_nop 1
	v_add_f32_dpp v102, v102, v102 quad_perm:[1,0,3,2] row_mask:0xf bank_mask:0xf bound_ctrl:1
	s_nop 1
	v_add_f32_dpp v102, v102, v102 quad_perm:[2,3,0,1] row_mask:0xf bank_mask:0xf bound_ctrl:1
	s_nop 1
	v_add_f32_dpp v19, v102, v102 row_half_mirror row_mask:0xf bank_mask:0xa bound_ctrl:1
	v_mov_b32_e32 v102, 0
	v_cndmask_b32_e64 v20, v16, v17, s[6:7]
	v_cndmask_b32_e64 v20, v20, v18, s[8:9]
	v_cndmask_b32_e64 v20, v20, v19, s[10:11]
	v_cvt_pk_bf16_f32 v21, v20, v20
	ds_write_b16 v112, v21 offset:8960
	s_waitcnt lgkmcnt(1)
	ds_read_b128 v[38:41], v0 offset:4608
	ds_read_b128 v[42:45], v0 offset:4624
	ds_read_b128 v[54:57], v0 offset:6656
	ds_read_b128 v[58:61], v0 offset:6672
	ds_read_b32 v32, v1 offset:8480
	v_fmac_f32_e32 v8, v22, v30
	v_add_f32_dpp v102, v102, v102 quad_perm:[1,0,3,2] row_mask:0xf bank_mask:0xf bound_ctrl:1
	v_fmac_f32_e32 v9, v23, v30
	v_mul_f32_e32 v36, v46, v8
	v_add_f32_dpp v102, v102, v102 quad_perm:[2,3,0,1] row_mask:0xf bank_mask:0xf bound_ctrl:1
	v_fmac_f32_e32 v10, v24, v30
	v_fmac_f32_e32 v36, v47, v9
	v_add_f32_dpp v19, v102, v102 row_half_mirror row_mask:0xf bank_mask:0xa bound_ctrl:1
	v_fmac_f32_e32 v11, v25, v30
	v_fmac_f32_e32 v36, v48, v10
	v_fmac_f32_e32 v12, v26, v30
	v_fmac_f32_e32 v36, v49, v11
	v_fmac_f32_e32 v13, v27, v30
	v_fmac_f32_e32 v36, v50, v12
	v_fmac_f32_e32 v14, v28, v30
	v_fmac_f32_e32 v36, v51, v13
	v_fmac_f32_e32 v15, v29, v30
	v_fmac_f32_e32 v36, v52, v14
	v_fmac_f32_e32 v36, v53, v15
	s_waitcnt vmcnt(10)
	v_lshlrev_b32_e32 v94, 16, v66
	v_and_b32_e32 v95, 0xffff0000, v66
	v_lshlrev_b32_e32 v96, 16, v67
	v_and_b32_e32 v97, 0xffff0000, v67
	v_mul_f32_e32 v94, v103, v94
	v_mul_f32_e32 v95, v103, v95
	v_mul_f32_e32 v96, v103, v96
	v_mul_f32_e32 v97, v103, v97
	ds_write_b128 v2, v[94:97] offset:0
	v_lshlrev_b32_e32 v98, 16, v68
	s_waitcnt lgkmcnt(1)
	ds_read_b128 v[22:25], v0 offset:4864
	ds_read_b128 v[26:29], v0 offset:4880
	ds_read_b128 v[46:49], v0 offset:6912
	ds_read_b128 v[50:53], v0 offset:6928
	ds_read_b32 v30, v1 offset:8512
	v_fmac_f32_e32 v8, v38, v32
	v_add_f32_dpp v36, v36, v36 quad_perm:[1,0,3,2] row_mask:0xf bank_mask:0xf bound_ctrl:1
	v_fmac_f32_e32 v9, v39, v32
	v_mul_f32_e32 v102, v54, v8
	v_add_f32_dpp v36, v36, v36 quad_perm:[2,3,0,1] row_mask:0xf bank_mask:0xf bound_ctrl:1
	v_fmac_f32_e32 v10, v40, v32
	v_fmac_f32_e32 v102, v55, v9
	v_add_f32_dpp v16, v36, v36 row_half_mirror row_mask:0xf bank_mask:0x5 bound_ctrl:1
	v_fmac_f32_e32 v11, v41, v32
	v_fmac_f32_e32 v102, v56, v10
	v_fmac_f32_e32 v12, v42, v32
	v_fmac_f32_e32 v102, v57, v11
	v_fmac_f32_e32 v13, v43, v32
	v_fmac_f32_e32 v102, v58, v12
	v_fmac_f32_e32 v14, v44, v32
	v_fmac_f32_e32 v102, v59, v13
	v_fmac_f32_e32 v15, v45, v32
	v_fmac_f32_e32 v102, v60, v14
	v_fmac_f32_e32 v102, v61, v15
	v_and_b32_e32 v99, 0xffff0000, v68
	v_lshlrev_b32_e32 v100, 16, v69
	v_and_b32_e32 v101, 0xffff0000, v69
	v_mul_f32_e32 v98, v103, v98
	v_mul_f32_e32 v99, v103, v99
	v_mul_f32_e32 v100, v103, v100
	v_mul_f32_e32 v101, v103, v101
	ds_write_b128 v2, v[98:101] offset:16
	v_lshlrev_b32_e32 v94, 16, v62
	v_and_b32_e32 v95, 0xffff0000, v62
	v_lshlrev_b32_e32 v96, 16, v63
	s_waitcnt lgkmcnt(1)
	ds_read_b128 v[38:41], v0 offset:5120
	ds_read_b128 v[42:45], v0 offset:5136
	ds_read_b128 v[54:57], v0 offset:7168
	ds_read_b128 v[58:61], v0 offset:7184
	ds_read_b32 v32, v1 offset:8544
	v_fmac_f32_e32 v8, v22, v30
	v_add_f32_dpp v102, v102, v102 quad_perm:[1,0,3,2] row_mask:0xf bank_mask:0xf bound_ctrl:1
	v_fmac_f32_e32 v9, v23, v30
	v_mul_f32_e32 v36, v46, v8
	v_add_f32_dpp v102, v102, v102 quad_perm:[2,3,0,1] row_mask:0xf bank_mask:0xf bound_ctrl:1
	v_fmac_f32_e32 v10, v24, v30
	v_fmac_f32_e32 v36, v47, v9
	v_add_f32_dpp v17, v102, v102 row_half_mirror row_mask:0xf bank_mask:0x5 bound_ctrl:1
	v_fmac_f32_e32 v11, v25, v30
	v_fmac_f32_e32 v36, v48, v10
	v_fmac_f32_e32 v12, v26, v30
	v_fmac_f32_e32 v36, v49, v11
	v_fmac_f32_e32 v13, v27, v30
	v_fmac_f32_e32 v36, v50, v12
	v_fmac_f32_e32 v14, v28, v30
	v_fmac_f32_e32 v36, v51, v13
	v_fmac_f32_e32 v15, v29, v30
	v_fmac_f32_e32 v36, v52, v14
	v_fmac_f32_e32 v36, v53, v15
	v_and_b32_e32 v97, 0xffff0000, v63
	v_mul_f32_e32 v94, v107, v94
	v_mul_f32_e32 v95, v107, v95
	v_mul_f32_e32 v96, v107, v96
	v_mul_f32_e32 v97, v107, v97
	ds_write_b128 v2, v[94:97] offset:2048
	v_lshlrev_b32_e32 v98, 16, v64
	v_and_b32_e32 v99, 0xffff0000, v64
	v_lshlrev_b32_e32 v100, 16, v65
	v_and_b32_e32 v101, 0xffff0000, v65
	v_mul_f32_e32 v98, v107, v98
	s_waitcnt lgkmcnt(1)
	ds_read_b128 v[22:25], v0 offset:5376
	ds_read_b128 v[26:29], v0 offset:5392
	ds_read_b128 v[46:49], v0 offset:7424
	ds_read_b128 v[50:53], v0 offset:7440
	ds_read_b32 v30, v1 offset:8576
	v_fmac_f32_e32 v8, v38, v32
	v_add_f32_dpp v36, v36, v36 quad_perm:[1,0,3,2] row_mask:0xf bank_mask:0xf bound_ctrl:1
	v_fmac_f32_e32 v9, v39, v32
	v_mul_f32_e32 v102, v54, v8
	v_add_f32_dpp v36, v36, v36 quad_perm:[2,3,0,1] row_mask:0xf bank_mask:0xf bound_ctrl:1
	v_fmac_f32_e32 v10, v40, v32
	v_fmac_f32_e32 v102, v55, v9
	v_add_f32_dpp v18, v36, v36 row_half_mirror row_mask:0xf bank_mask:0x5 bound_ctrl:1
	v_fmac_f32_e32 v11, v41, v32
	v_fmac_f32_e32 v102, v56, v10
	v_fmac_f32_e32 v12, v42, v32
	v_fmac_f32_e32 v102, v57, v11
	v_fmac_f32_e32 v13, v43, v32
	v_fmac_f32_e32 v102, v58, v12
	v_fmac_f32_e32 v14, v44, v32
	v_fmac_f32_e32 v102, v59, v13
	v_fmac_f32_e32 v15, v45, v32
	v_fmac_f32_e32 v102, v60, v14
	v_fmac_f32_e32 v102, v61, v15
	v_mul_f32_e32 v99, v107, v99
	v_mul_f32_e32 v100, v107, v100
	v_mul_f32_e32 v101, v107, v101
	ds_write_b128 v2, v[98:101] offset:2064
	s_waitcnt vmcnt(9)
	v_lshlrev_b32_e32 v31, 16, v31
	s_nop 0
	ds_write_b32 v4, v31 offset:4096
	s_waitcnt lgkmcnt(2)
	ds_read_b128 v[38:41], v0 offset:5632
	ds_read_b128 v[42:45], v0 offset:5648
	ds_read_b128 v[54:57], v0 offset:7680
	ds_read_b128 v[58:61], v0 offset:7696
	ds_read_b32 v32, v1 offset:8608
	v_fmac_f32_e32 v8, v22, v30
	v_add_f32_dpp v102, v102, v102 quad_perm:[1,0,3,2] row_mask:0xf bank_mask:0xf bound_ctrl:1
	v_fmac_f32_e32 v9, v23, v30
	v_mul_f32_e32 v36, v46, v8
	v_add_f32_dpp v102, v102, v102 quad_perm:[2,3,0,1] row_mask:0xf bank_mask:0xf bound_ctrl:1
	v_fmac_f32_e32 v10, v24, v30
	v_fmac_f32_e32 v36, v47, v9
	v_add_f32_dpp v19, v102, v102 row_half_mirror row_mask:0xf bank_mask:0x5 bound_ctrl:1
	v_fmac_f32_e32 v11, v25, v30
	v_fmac_f32_e32 v36, v48, v10
	v_fmac_f32_e32 v12, v26, v30
	v_fmac_f32_e32 v36, v49, v11
	v_fmac_f32_e32 v13, v27, v30
	v_fmac_f32_e32 v36, v50, v12
	v_fmac_f32_e32 v14, v28, v30
	v_fmac_f32_e32 v36, v51, v13
	v_fmac_f32_e32 v15, v29, v30
	v_fmac_f32_e32 v36, v52, v14
	v_fmac_f32_e32 v36, v53, v15
	global_load_dwordx4 v[62:65], v5, s[94:95]
	global_load_dwordx4 v[66:69], v5, s[94:95] offset:512
	global_load_ushort v31, v6, s[94:95]
	v_add_u32_e32 v5, 0x6800, v5
	v_add_u32_e32 v6, 0x10000, v6
	s_waitcnt lgkmcnt(0)
	ds_read_b128 v[22:25], v0 offset:5888
	ds_read_b128 v[26:29], v0 offset:5904
	ds_read_b128 v[46:49], v0 offset:7936
	ds_read_b128 v[50:53], v0 offset:7952
	ds_read_b32 v30, v1 offset:8640
	v_fmac_f32_e32 v8, v38, v32
	v_add_f32_dpp v36, v36, v36 quad_perm:[1,0,3,2] row_mask:0xf bank_mask:0xf bound_ctrl:1
	v_fmac_f32_e32 v9, v39, v32
	v_mul_f32_e32 v102, v54, v8
	v_add_f32_dpp v36, v36, v36 quad_perm:[2,3,0,1] row_mask:0xf bank_mask:0xf bound_ctrl:1
	v_fmac_f32_e32 v10, v40, v32
	v_fmac_f32_e32 v102, v55, v9
	v_add_f32_dpp v16, v36, v36 row_half_mirror row_mask:0xf bank_mask:0xa bound_ctrl:1
	v_fmac_f32_e32 v11, v41, v32
	v_fmac_f32_e32 v102, v56, v10
	v_fmac_f32_e32 v12, v42, v32
	v_fmac_f32_e32 v102, v57, v11
	v_fmac_f32_e32 v13, v43, v32
	v_fmac_f32_e32 v102, v58, v12
	v_fmac_f32_e32 v14, v44, v32
	v_fmac_f32_e32 v102, v59, v13
	v_fmac_f32_e32 v15, v45, v32
	v_fmac_f32_e32 v102, v60, v14
	v_fmac_f32_e32 v102, v61, v15
	s_waitcnt lgkmcnt(0)
	ds_read_b128 v[38:41], v0 offset:6144
	ds_read_b128 v[42:45], v0 offset:6160
	ds_read_b128 v[54:57], v0 offset:8192
	ds_read_b128 v[58:61], v0 offset:8208
	ds_read_b32 v32, v1 offset:8672
	v_fmac_f32_e32 v8, v22, v30
	v_add_f32_dpp v102, v102, v102 quad_perm:[1,0,3,2] row_mask:0xf bank_mask:0xf bound_ctrl:1
	v_fmac_f32_e32 v9, v23, v30
	v_mul_f32_e32 v36, v46, v8
	v_add_f32_dpp v102, v102, v102 quad_perm:[2,3,0,1] row_mask:0xf bank_mask:0xf bound_ctrl:1
	v_fmac_f32_e32 v10, v24, v30
	v_fmac_f32_e32 v36, v47, v9
	v_add_f32_dpp v17, v102, v102 row_half_mirror row_mask:0xf bank_mask:0xa bound_ctrl:1
	v_fmac_f32_e32 v11, v25, v30
	v_fmac_f32_e32 v36, v48, v10
	v_fmac_f32_e32 v12, v26, v30
	v_fmac_f32_e32 v36, v49, v11
	v_fmac_f32_e32 v13, v27, v30
	v_fmac_f32_e32 v36, v50, v12
	v_fmac_f32_e32 v14, v28, v30
	v_fmac_f32_e32 v36, v51, v13
	v_fmac_f32_e32 v15, v29, v30
	v_fmac_f32_e32 v36, v52, v14
	v_fmac_f32_e32 v36, v53, v15
	s_waitcnt lgkmcnt(0)
	ds_read_b128 v[22:25], v0 offset:0
	ds_read_b128 v[26:29], v0 offset:16
	ds_read_b128 v[46:49], v0 offset:2048
	ds_read_b128 v[50:53], v0 offset:2064
	ds_read_b32 v30, v1 offset:4096
	v_fmac_f32_e32 v8, v38, v32
	v_add_f32_dpp v36, v36, v36 quad_perm:[1,0,3,2] row_mask:0xf bank_mask:0xf bound_ctrl:1
	v_fmac_f32_e32 v9, v39, v32
	v_mul_f32_e32 v102, v54, v8
	v_add_f32_dpp v36, v36, v36 quad_perm:[2,3,0,1] row_mask:0xf bank_mask:0xf bound_ctrl:1
	v_fmac_f32_e32 v10, v40, v32
	v_fmac_f32_e32 v102, v55, v9
	v_add_f32_dpp v18, v36, v36 row_half_mirror row_mask:0xf bank_mask:0xa bound_ctrl:1
	v_fmac_f32_e32 v11, v41, v32
	v_fmac_f32_e32 v102, v56, v10
	v_fmac_f32_e32 v12, v42, v32
	v_fmac_f32_e32 v102, v57, v11
	v_fmac_f32_e32 v13, v43, v32
	v_fmac_f32_e32 v102, v58, v12
	v_fmac_f32_e32 v14, v44, v32
	v_fmac_f32_e32 v102, v59, v13
	v_fmac_f32_e32 v15, v45, v32
	v_fmac_f32_e32 v102, v60, v14
	v_fmac_f32_e32 v102, v61, v15
	s_nop 1
	v_add_f32_dpp v102, v102, v102 quad_perm:[1,0,3,2] row_mask:0xf bank_mask:0xf bound_ctrl:1
	s_nop 1
	v_add_f32_dpp v102, v102, v102 quad_perm:[2,3,0,1] row_mask:0xf bank_mask:0xf bound_ctrl:1
	s_nop 1
	v_add_f32_dpp v19, v102, v102 row_half_mirror row_mask:0xf bank_mask:0xa bound_ctrl:1
	v_mov_b32_e32 v102, 0
	v_cndmask_b32_e64 v20, v16, v17, s[6:7]
	v_cndmask_b32_e64 v20, v20, v18, s[8:9]
	v_cndmask_b32_e64 v20, v20, v19, s[10:11]
	v_cvt_pk_bf16_f32 v21, v20, v20
	ds_write_b16 v112, v21 offset:9088
	v_add_u32_e32 v112, 0x200, v112
	s_and_b32 s24, s12, 15
	s_cmp_eq_u32 s24, 1
	s_cbranch_scc0 .Lls0_8_noflush
	ds_read_b128 v[114:117], v113 offset:8704
	s_waitcnt lgkmcnt(0)
	global_store_dwordx4 v7, v[114:117], s[94:95]
	v_add_u32_e32 v7, 0x20000, v7
	s_nop 0
	ds_read_b128 v[114:117], v113 offset:9728
	s_waitcnt lgkmcnt(0)
	global_store_dwordx4 v7, v[114:117], s[94:95]
	v_add_u32_e32 v7, 0x20000, v7
	s_nop 0
	ds_read_b128 v[114:117], v113 offset:10752
	s_waitcnt lgkmcnt(0)
	global_store_dwordx4 v7, v[114:117], s[94:95]
	v_add_u32_e32 v7, 0x20000, v7
	s_nop 0
	ds_read_b128 v[114:117], v113 offset:11776
	s_waitcnt lgkmcnt(0)
	global_store_dwordx4 v7, v[114:117], s[94:95]
	v_add_u32_e32 v7, 0x20000, v7
	s_nop 0
	ds_read_b128 v[114:117], v113 offset:12800
	s_waitcnt lgkmcnt(0)
	global_store_dwordx4 v7, v[114:117], s[94:95]
	v_add_u32_e32 v7, 0x20000, v7
	s_nop 0
	ds_read_b128 v[114:117], v113 offset:13824
	s_waitcnt lgkmcnt(0)
	global_store_dwordx4 v7, v[114:117], s[94:95]
	v_add_u32_e32 v7, 0x20000, v7
	s_nop 0
	ds_read_b128 v[114:117], v113 offset:14848
	s_waitcnt lgkmcnt(0)
	global_store_dwordx4 v7, v[114:117], s[94:95]
	v_add_u32_e32 v7, 0x20000, v7
	s_nop 0
	ds_read_b128 v[114:117], v113 offset:15872
	s_waitcnt lgkmcnt(0)
	global_store_dwordx4 v7, v[114:117], s[94:95]
	v_add_u32_e32 v7, 0x20000, v7
	s_nop 0
	v_subrev_u32_e32 v112, 0x2000, v112
.Lls0_8_noflush:
	v_mul_f32_e32 v8, s44, v8
	v_mul_f32_e32 v9, s44, v9
	v_mul_f32_e32 v10, s44, v10
	v_mul_f32_e32 v11, s44, v11
	v_mul_f32_e32 v12, s44, v12
	v_mul_f32_e32 v13, s44, v13
	v_mul_f32_e32 v14, s44, v14
	v_mul_f32_e32 v15, s44, v15
	s_sub_u32 s12, s12, 1
	s_cmp_lg_u32 s12, 0
	s_cbranch_scc1 .Lls0_8_loop
	global_store_dword v111, v8, s[26:27] offset:0
	global_store_dword v111, v9, s[26:27] offset:256
	global_store_dword v111, v10, s[26:27] offset:512
	global_store_dword v111, v11, s[26:27] offset:768
	global_store_dword v111, v12, s[26:27] offset:1024
	global_store_dword v111, v13, s[26:27] offset:1280
	global_store_dword v111, v14, s[26:27] offset:1536
	global_store_dword v111, v15, s[26:27] offset:1792
	s_waitcnt vmcnt(0) lgkmcnt(0)
	s_setprio 0
	s_branch .Lls_done
.Lls2_8_entry:
	v_and_b32_e32 v114, 63, v196
	v_and_b32_e32 v115, 7, v114
	v_lshrrev_b32_e32 v116, 3, v114
	s_min_u32 s29, s0, 4
	s_mul_i32 s29, s29, 0x5600
	v_and_b32_e32 v117, 3, v115
	v_cmp_eq_u32_e64 s[6:7], 1, v117
	v_cmp_eq_u32_e64 s[8:9], 2, v117
	v_cmp_eq_u32_e64 s[10:11], 3, v117
	v_lshl_add_u32 v0, v115, 5, s29
	v_lshl_add_u32 v1, v116, 2, s29
	s_lshl_b32 s37, s16, 11
	v_lshrrev_b32_e32 v115, 3, v114
	v_and_b32_e32 v116, 7, v114
	v_add_u32_e32 v117, s37, v115
	s_lshl_b32 s21, s17, 7
	s_add_u32 s21, s21, 0x10800500
	v_mul_u32_u24_e32 v5, 0xd00, v117
	v_lshl_add_u32 v5, v116, 4, v5
	v_add_u32_e32 v5, s21, v5
	v_lshlrev_b32_e32 v2, 8, v115
	v_lshl_add_u32 v2, v116, 5, v2
	v_add_u32_e32 v2, s29, v2
	s_lshl_b32 s21, s17, 8
	s_add_u32 s21, s21, 0x13e00200
	v_mul_u32_u24_e32 v8, 0x630, v117
	v_lshl_add_u32 v8, v116, 5, v8
	v_add_u32_e32 v8, s21, v8
	v_lshrrev_b32_e32 v116, 3, v114
	v_and_b32_e32 v115, 7, v114
	v_add_u32_e32 v117, s37, v116
	s_lshl_b32 s22, s14, 3
	s_lshl_b32 s21, s17, 6
	s_add_u32 s21, s21, s22
	s_lshl_b32 s44, s21, 1
	s_add_u32 s44, s44, 0x8401220
	v_lshlrev_b32_e32 v6, 13, v117
	v_lshlrev_b32_e32 v4, 5, v116
	v_lshl_add_u32 v4, v115, 2, v4
	v_lshl_add_u32 v6, v115, 1, v6
	v_add_u32_e32 v6, s44, v6
	v_add_u32_e32 v4, s29, v4
	v_and_b32_e32 v115, 7, v114
	v_lshrrev_b32_e32 v116, 3, v114
	v_add_u32_e32 v117, s37, v114
	v_lshlrev_b32_e32 v7, 11, v117
	s_lshl_b32 s44, s21, 1
	s_add_u32 s44, s44, 0x6300400
	v_add_u32_e32 v7, s44, v7
	s_lshl_b32 s44, s28, 3
	s_add_u32 s44, s44, s16
	s_lshl_b32 s44, s44, 2
	s_add_u32 s44, s44, s17
	s_mul_i32 s44, s44, 0x4000
	s_add_u32 s44, s44, 0x4380000
	s_lshl_b32 s24, s22, 2
	s_add_u32 s44, s44, s24
	v_lshlrev_b32_e32 v120, 11, v115
	v_lshl_add_u32 v120, v116, 2, v120
	v_add_u32_e32 v120, s44, v120
	v_readlane_b32 s26, v253, 29
	v_readlane_b32 s27, v253, 30
	v_lshlrev_b32_e32 v121, 4, v115
	v_lshl_add_u32 v121, v116, 1, v121
	v_add_u32_e32 v121, s29, v121
	v_lshl_add_u32 v122, v114, 4, s29
	v_mov_b32_e32 v10, 0
	v_mov_b32_e32 v11, 0
	v_mov_b32_e32 v12, 0
	v_mov_b32_e32 v13, 0
	v_mov_b32_e32 v14, 0
	v_mov_b32_e32 v15, 0
	v_mov_b32_e32 v16, 0
	v_mov_b32_e32 v17, 0
	v_mov_b32_e32 v9, 0
	v_mov_b32_e32 v18, 0
	v_mov_b32_e32 v19, 0
	v_mov_b32_e32 v20, 0
	v_mov_b32_e32 v118, 0
	v_mov_b32_e32 v119, 0
	s_setprio 2
	s_movk_i32 s12, 64
	s_nop 0
	global_load_dwordx4 v[62:65], v5, s[94:95]
	global_load_dwordx4 v[66:69], v8, s[94:95]
	global_load_dwordx4 v[70:73], v8, s[94:95] offset:16
	global_load_ushort v23, v6, s[94:95]
	v_add_u32_e32 v5, 0x6800, v5
	v_add_u32_e32 v8, 0x3180, v8
	v_add_u32_e32 v6, 0x10000, v6
	s_waitcnt vmcnt(0)
	s_waitcnt vmcnt(3)
	v_lshlrev_b32_e32 v110, 16, v62
	v_and_b32_e32 v111, 0xffff0000, v62
	v_lshlrev_b32_e32 v112, 16, v63
	v_and_b32_e32 v113, 0xffff0000, v63
	ds_write_b128 v2, v[110:113] offset:0
	v_lshlrev_b32_e32 v114, 16, v64
	v_and_b32_e32 v115, 0xffff0000, v64
	v_lshlrev_b32_e32 v116, 16, v65
	v_and_b32_e32 v117, 0xffff0000, v65
	ds_write_b128 v2, v[114:117] offset:16
	s_waitcnt vmcnt(1)
	ds_write_b128 v2, v[66:69] offset:2048
	ds_write_b128 v2, v[70:73] offset:2064
	s_waitcnt vmcnt(0)
	v_lshlrev_b32_e32 v23, 16, v23
	s_nop 0
	ds_write_b32 v4, v23 offset:4096
	global_load_dwordx4 v[74:77], v5, s[94:95]
	global_load_dwordx4 v[78:81], v8, s[94:95]
	global_load_dwordx4 v[82:85], v8, s[94:95] offset:16
	global_load_ushort v33, v6, s[94:95]
	v_add_u32_e32 v5, 0x6800, v5
	v_add_u32_e32 v8, 0x3180, v8
	v_add_u32_e32 v6, 0x10000, v6
	global_load_dwordx4 v[86:89], v5, s[94:95]
	global_load_dwordx4 v[90:93], v8, s[94:95]
	global_load_dwordx4 v[94:97], v8, s[94:95] offset:16
	global_load_ushort v35, v6, s[94:95]
	v_add_u32_e32 v5, 0x6800, v5
	v_add_u32_e32 v8, 0x3180, v8
	v_add_u32_e32 v6, 0x10000, v6
	global_load_dwordx4 v[98:101], v5, s[94:95]
	global_load_dwordx4 v[102:105], v8, s[94:95]
	global_load_dwordx4 v[106:109], v8, s[94:95] offset:16
	global_load_ushort v36, v6, s[94:95]
	v_add_u32_e32 v5, 0x6800, v5
	v_add_u32_e32 v8, 0x3180, v8
	v_add_u32_e32 v6, 0x10000, v6
	global_load_dwordx4 v[62:65], v5, s[94:95]
	global_load_dwordx4 v[66:69], v8, s[94:95]
	global_load_dwordx4 v[70:73], v8, s[94:95] offset:16
	global_load_ushort v23, v6, s[94:95]
	v_add_u32_e32 v5, 0x6800, v5
	v_add_u32_e32 v8, 0x3180, v8
	v_add_u32_e32 v6, 0x10000, v6
	ds_read_b128 v[24:27], v0 offset:0
	ds_read_b128 v[28:31], v0 offset:16
	ds_read_b128 v[46:49], v0 offset:2048
	ds_read_b128 v[50:53], v0 offset:2064
	ds_read_b32 v32, v1 offset:4096
.Lls2_8_loop:
	s_waitcnt lgkmcnt(0)
	ds_read_b128 v[38:41], v0 offset:256
	ds_read_b128 v[42:45], v0 offset:272
	ds_read_b128 v[54:57], v0 offset:2304
	ds_read_b128 v[58:61], v0 offset:2320
	ds_read_b32 v34, v1 offset:4128
	v_sub_f32_e32 v10, v10, v32
	v_add_f32_dpp v119, v119, v119 quad_perm:[1,0,3,2] row_mask:0xf bank_mask:0xf bound_ctrl:1
	v_sub_f32_e32 v11, v11, v32
	v_sub_f32_e32 v12, v12, v32
	v_add_f32_dpp v119, v119, v119 quad_perm:[2,3,0,1] row_mask:0xf bank_mask:0xf bound_ctrl:1
	v_sub_f32_e32 v13, v13, v32
	v_sub_f32_e32 v14, v14, v32
	v_add_f32_dpp v20, v119, v119 row_half_mirror row_mask:0xf bank_mask:0xa bound_ctrl:1
	v_sub_f32_e32 v15, v15, v32
	v_sub_f32_e32 v16, v16, v32
	v_sub_f32_e32 v17, v17, v32
	v_fma_f32 v10, v46, v10, v32
	v_fma_f32 v11, v47, v11, v32
	v_mul_f32_e32 v118, v24, v10
	v_fma_f32 v12, v48, v12, v32
	v_fmac_f32_e32 v118, v25, v11
	v_fma_f32 v13, v49, v13, v32
	v_fmac_f32_e32 v118, v26, v12
	v_fma_f32 v14, v50, v14, v32
	v_fmac_f32_e32 v118, v27, v13
	v_fma_f32 v15, v51, v15, v32
	v_fmac_f32_e32 v118, v28, v14
	v_fma_f32 v16, v52, v16, v32
	v_fmac_f32_e32 v118, v29, v15
	v_fma_f32 v17, v53, v17, v32
	v_fmac_f32_e32 v118, v30, v16
	v_fmac_f32_e32 v118, v31, v17
	s_waitcnt vmcnt(15)
	v_lshlrev_b32_e32 v110, 16, v74
	v_and_b32_e32 v111, 0xffff0000, v74
	v_lshlrev_b32_e32 v112, 16, v75
	v_and_b32_e32 v113, 0xffff0000, v75
	s_waitcnt lgkmcnt(0)
	ds_read_b128 v[24:27], v0 offset:512
	ds_read_b128 v[28:31], v0 offset:528
	ds_read_b128 v[46:49], v0 offset:2560
	ds_read_b128 v[50:53], v0 offset:2576
	ds_read_b32 v32, v1 offset:4160
	v_sub_f32_e32 v10, v10, v34
	v_add_f32_dpp v118, v118, v118 quad_perm:[1,0,3,2] row_mask:0xf bank_mask:0xf bound_ctrl:1
	v_sub_f32_e32 v11, v11, v34
	v_sub_f32_e32 v12, v12, v34
	v_add_f32_dpp v118, v118, v118 quad_perm:[2,3,0,1] row_mask:0xf bank_mask:0xf bound_ctrl:1
	v_sub_f32_e32 v13, v13, v34
	v_sub_f32_e32 v14, v14, v34
	v_add_f32_dpp v9, v118, v118 row_half_mirror row_mask:0xf bank_mask:0x5 bound_ctrl:1
	v_sub_f32_e32 v15, v15, v34
	v_sub_f32_e32 v16, v16, v34
	v_sub_f32_e32 v17, v17, v34
	v_fma_f32 v10, v54, v10, v34
	v_fma_f32 v11, v55, v11, v34
	v_mul_f32_e32 v119, v38, v10
	v_fma_f32 v12, v56, v12, v34
	v_fmac_f32_e32 v119, v39, v11
	v_fma_f32 v13, v57, v13, v34
	v_fmac_f32_e32 v119, v40, v12
	v_fma_f32 v14, v58, v14, v34
	v_fmac_f32_e32 v119, v41, v13
	v_fma_f32 v15, v59, v15, v34
	v_fmac_f32_e32 v119, v42, v14
	v_fma_f32 v16, v60, v16, v34
	v_fmac_f32_e32 v119, v43, v15
	v_fma_f32 v17, v61, v17, v34
	v_fmac_f32_e32 v119, v44, v16
	v_fmac_f32_e32 v119, v45, v17
	ds_write_b128 v2, v[110:113] offset:4352
	v_lshlrev_b32_e32 v114, 16, v76
	v_and_b32_e32 v115, 0xffff0000, v76
	v_lshlrev_b32_e32 v116, 16, v77
	v_and_b32_e32 v117, 0xffff0000, v77
	s_waitcnt lgkmcnt(1)
	ds_read_b128 v[38:41], v0 offset:768
	ds_read_b128 v[42:45], v0 offset:784
	ds_read_b128 v[54:57], v0 offset:2816
	ds_read_b128 v[58:61], v0 offset:2832
	ds_read_b32 v34, v1 offset:4192
	v_sub_f32_e32 v10, v10, v32
	v_add_f32_dpp v119, v119, v119 quad_perm:[1,0,3,2] row_mask:0xf bank_mask:0xf bound_ctrl:1
	v_sub_f32_e32 v11, v11, v32
	v_sub_f32_e32 v12, v12, v32
	v_add_f32_dpp v119, v119, v119 quad_perm:[2,3,0,1] row_mask:0xf bank_mask:0xf bound_ctrl:1
	v_sub_f32_e32 v13, v13, v32
	v_sub_f32_e32 v14, v14, v32
	v_add_f32_dpp v18, v119, v119 row_half_mirror row_mask:0xf bank_mask:0x5 bound_ctrl:1
	v_sub_f32_e32 v15, v15, v32
	v_sub_f32_e32 v16, v16, v32
	v_sub_f32_e32 v17, v17, v32
	v_fma_f32 v10, v46, v10, v32
	v_fma_f32 v11, v47, v11, v32
	v_mul_f32_e32 v118, v24, v10
	v_fma_f32 v12, v48, v12, v32
	v_fmac_f32_e32 v118, v25, v11
	v_fma_f32 v13, v49, v13, v32
	v_fmac_f32_e32 v118, v26, v12
	v_fma_f32 v14, v50, v14, v32
	v_fmac_f32_e32 v118, v27, v13
	v_fma_f32 v15, v51, v15, v32
	v_fmac_f32_e32 v118, v28, v14
	v_fma_f32 v16, v52, v16, v32
	v_fmac_f32_e32 v118, v29, v15
	v_fma_f32 v17, v53, v17, v32
	v_fmac_f32_e32 v118, v30, v16
	v_fmac_f32_e32 v118, v31, v17
	ds_write_b128 v2, v[114:117] offset:4368
	s_waitcnt vmcnt(13)
	ds_write_b128 v2, v[78:81] offset:6400
	ds_write_b128 v2, v[82:85] offset:6416
	s_waitcnt vmcnt(12)
	s_waitcnt lgkmcnt(3)
	ds_read_b128 v[24:27], v0 offset:1024
	ds_read_b128 v[28:31], v0 offset:1040
	ds_read_b128 v[46:49], v0 offset:3072
	ds_read_b128 v[50:53], v0 offset:3088
	ds_read_b32 v32, v1 offset:4224
	v_sub_f32_e32 v10, v10, v34
	v_add_f32_dpp v118, v118, v118 quad_perm:[1,0,3,2] row_mask:0xf bank_mask:0xf bound_ctrl:1
	v_sub_f32_e32 v11, v11, v34
	v_sub_f32_e32 v12, v12, v34
	v_add_f32_dpp v118, v118, v118 quad_perm:[2,3,0,1] row_mask:0xf bank_mask:0xf bound_ctrl:1
	v_sub_f32_e32 v13, v13, v34
	v_sub_f32_e32 v14, v14, v34
	v_add_f32_dpp v19, v118, v118 row_half_mirror row_mask:0xf bank_mask:0x5 bound_ctrl:1
	v_sub_f32_e32 v15, v15, v34
	v_sub_f32_e32 v16, v16, v34
	v_sub_f32_e32 v17, v17, v34
	v_fma_f32 v10, v54, v10, v34
	v_fma_f32 v11, v55, v11, v34
	v_mul_f32_e32 v119, v38, v10
	v_fma_f32 v12, v56, v12, v34
	v_fmac_f32_e32 v119, v39, v11
	v_fma_f32 v13, v57, v13, v34
	v_fmac_f32_e32 v119, v40, v12
	v_fma_f32 v14, v58, v14, v34
	v_fmac_f32_e32 v119, v41, v13
	v_fma_f32 v15, v59, v15, v34
	v_fmac_f32_e32 v119, v42, v14
	v_fma_f32 v16, v60, v16, v34
	v_fmac_f32_e32 v119, v43, v15
	v_fma_f32 v17, v61, v17, v34
	v_fmac_f32_e32 v119, v44, v16
	v_fmac_f32_e32 v119, v45, v17
	v_lshlrev_b32_e32 v33, 16, v33
	s_nop 0
	ds_write_b32 v4, v33 offset:8448
	s_waitcnt lgkmcnt(1)
	ds_read_b128 v[38:41], v0 offset:1280
	ds_read_b128 v[42:45], v0 offset:1296
	ds_read_b128 v[54:57], v0 offset:3328
	ds_read_b128 v[58:61], v0 offset:3344
	ds_read_b32 v34, v1 offset:4256
	v_sub_f32_e32 v10, v10, v32
	v_add_f32_dpp v119, v119, v119 quad_perm:[1,0,3,2] row_mask:0xf bank_mask:0xf bound_ctrl:1
	v_sub_f32_e32 v11, v11, v32
	v_sub_f32_e32 v12, v12, v32
	v_add_f32_dpp v119, v119, v119 quad_perm:[2,3,0,1] row_mask:0xf bank_mask:0xf bound_ctrl:1
	v_sub_f32_e32 v13, v13, v32
	v_sub_f32_e32 v14, v14, v32
	v_add_f32_dpp v20, v119, v119 row_half_mirror row_mask:0xf bank_mask:0x5 bound_ctrl:1
	v_sub_f32_e32 v15, v15, v32
	v_sub_f32_e32 v16, v16, v32
	v_sub_f32_e32 v17, v17, v32
	v_fma_f32 v10, v46, v10, v32
	v_fma_f32 v11, v47, v11, v32
	v_mul_f32_e32 v118, v24, v10
	v_fma_f32 v12, v48, v12, v32
	v_fmac_f32_e32 v118, v25, v11
	v_fma_f32 v13, v49, v13, v32
	v_fmac_f32_e32 v118, v26, v12
	v_fma_f32 v14, v50, v14, v32
	v_fmac_f32_e32 v118, v27, v13
	v_fma_f32 v15, v51, v15, v32
	v_fmac_f32_e32 v118, v28, v14
	v_fma_f32 v16, v52, v16, v32
	v_fmac_f32_e32 v118, v29, v15
	v_fma_f32 v17, v53, v17, v32
	v_fmac_f32_e32 v118, v30, v16
	v_fmac_f32_e32 v118, v31, v17
	global_load_dwordx4 v[74:77], v5, s[94:95]
	global_load_dwordx4 v[78:81], v8, s[94:95]
	global_load_dwordx4 v[82:85], v8, s[94:95] offset:16
	global_load_ushort v33, v6, s[94:95]
	v_add_u32_e32 v5, 0x6800, v5
	v_add_u32_e32 v8, 0x3180, v8
	v_add_u32_e32 v6, 0x10000, v6
	s_waitcnt lgkmcnt(0)
	ds_read_b128 v[24:27], v0 offset:1536
	ds_read_b128 v[28:31], v0 offset:1552
	ds_read_b128 v[46:49], v0 offset:3584
	ds_read_b128 v[50:53], v0 offset:3600
	ds_read_b32 v32, v1 offset:4288
	v_sub_f32_e32 v10, v10, v34
	v_add_f32_dpp v118, v118, v118 quad_perm:[1,0,3,2] row_mask:0xf bank_mask:0xf bound_ctrl:1
	v_sub_f32_e32 v11, v11, v34
	v_sub_f32_e32 v12, v12, v34
	v_add_f32_dpp v118, v118, v118 quad_perm:[2,3,0,1] row_mask:0xf bank_mask:0xf bound_ctrl:1
	v_sub_f32_e32 v13, v13, v34
	v_sub_f32_e32 v14, v14, v34
	v_add_f32_dpp v9, v118, v118 row_half_mirror row_mask:0xf bank_mask:0xa bound_ctrl:1
	v_sub_f32_e32 v15, v15, v34
	v_sub_f32_e32 v16, v16, v34
	v_sub_f32_e32 v17, v17, v34
	v_fma_f32 v10, v54, v10, v34
	v_fma_f32 v11, v55, v11, v34
	v_mul_f32_e32 v119, v38, v10
	v_fma_f32 v12, v56, v12, v34
	v_fmac_f32_e32 v119, v39, v11
	v_fma_f32 v13, v57, v13, v34
	v_fmac_f32_e32 v119, v40, v12
	v_fma_f32 v14, v58, v14, v34
	v_fmac_f32_e32 v119, v41, v13
	v_fma_f32 v15, v59, v15, v34
	v_fmac_f32_e32 v119, v42, v14
	v_fma_f32 v16, v60, v16, v34
	v_fmac_f32_e32 v119, v43, v15
	v_fma_f32 v17, v61, v17, v34
	v_fmac_f32_e32 v119, v44, v16
	v_fmac_f32_e32 v119, v45, v17
	s_waitcnt lgkmcnt(0)
	ds_read_b128 v[38:41], v0 offset:1792
	ds_read_b128 v[42:45], v0 offset:1808
	ds_read_b128 v[54:57], v0 offset:3840
	ds_read_b128 v[58:61], v0 offset:3856
	ds_read_b32 v34, v1 offset:4320
	v_sub_f32_e32 v10, v10, v32
	v_add_f32_dpp v119, v119, v119 quad_perm:[1,0,3,2] row_mask:0xf bank_mask:0xf bound_ctrl:1
	v_sub_f32_e32 v11, v11, v32
	v_sub_f32_e32 v12, v12, v32
	v_add_f32_dpp v119, v119, v119 quad_perm:[2,3,0,1] row_mask:0xf bank_mask:0xf bound_ctrl:1
	v_sub_f32_e32 v13, v13, v32
	v_sub_f32_e32 v14, v14, v32
	v_add_f32_dpp v18, v119, v119 row_half_mirror row_mask:0xf bank_mask:0xa bound_ctrl:1
	v_sub_f32_e32 v15, v15, v32
	v_sub_f32_e32 v16, v16, v32
	v_sub_f32_e32 v17, v17, v32
	v_fma_f32 v10, v46, v10, v32
	v_fma_f32 v11, v47, v11, v32
	v_mul_f32_e32 v118, v24, v10
	v_fma_f32 v12, v48, v12, v32
	v_fmac_f32_e32 v118, v25, v11
	v_fma_f32 v13, v49, v13, v32
	v_fmac_f32_e32 v118, v26, v12
	v_fma_f32 v14, v50, v14, v32
	v_fmac_f32_e32 v118, v27, v13
	v_fma_f32 v15, v51, v15, v32
	v_fmac_f32_e32 v118, v28, v14
	v_fma_f32 v16, v52, v16, v32
	v_fmac_f32_e32 v118, v29, v15
	v_fma_f32 v17, v53, v17, v32
	v_fmac_f32_e32 v118, v30, v16
	v_fmac_f32_e32 v118, v31, v17
	s_waitcnt lgkmcnt(0)
	ds_read_b128 v[24:27], v0 offset:4352
	ds_read_b128 v[28:31], v0 offset:4368
	ds_read_b128 v[46:49], v0 offset:6400
	ds_read_b128 v[50:53], v0 offset:6416
	ds_read_b32 v32, v1 offset:8448
	v_sub_f32_e32 v10, v10, v34
	v_add_f32_dpp v118, v118, v118 quad_perm:[1,0,3,2] row_mask:0xf bank_mask:0xf bound_ctrl:1
	v_sub_f32_e32 v11, v11, v34
	v_sub_f32_e32 v12, v12, v34
	v_add_f32_dpp v118, v118, v118 quad_perm:[2,3,0,1] row_mask:0xf bank_mask:0xf bound_ctrl:1
	v_sub_f32_e32 v13, v13, v34
	v_sub_f32_e32 v14, v14, v34
	v_add_f32_dpp v19, v118, v118 row_half_mirror row_mask:0xf bank_mask:0xa bound_ctrl:1
	v_sub_f32_e32 v15, v15, v34
	v_sub_f32_e32 v16, v16, v34
	v_sub_f32_e32 v17, v17, v34
	v_fma_f32 v10, v54, v10, v34
	v_fma_f32 v11, v55, v11, v34
	v_mul_f32_e32 v119, v38, v10
	v_fma_f32 v12, v56, v12, v34
	v_fmac_f32_e32 v119, v39, v11
	v_fma_f32 v13, v57, v13, v34
	v_fmac_f32_e32 v119, v40, v12
	v_fma_f32 v14, v58, v14, v34
	v_fmac_f32_e32 v119, v41, v13
	v_fma_f32 v15, v59, v15, v34
	v_fmac_f32_e32 v119, v42, v14
	v_fma_f32 v16, v60, v16, v34
	v_fmac_f32_e32 v119, v43, v15
	v_fma_f32 v17, v61, v17, v34
	v_fmac_f32_e32 v119, v44, v16
	v_fmac_f32_e32 v119, v45, v17
	s_nop 1
	v_add_f32_dpp v119, v119, v119 quad_perm:[1,0,3,2] row_mask:0xf bank_mask:0xf bound_ctrl:1
	s_nop 1
	v_add_f32_dpp v119, v119, v119 quad_perm:[2,3,0,1] row_mask:0xf bank_mask:0xf bound_ctrl:1
	s_nop 1
	v_add_f32_dpp v20, v119, v119 row_half_mirror row_mask:0xf bank_mask:0xa bound_ctrl:1
	v_mov_b32_e32 v119, 0
	v_cndmask_b32_e64 v21, v9, v18, s[6:7]
	v_cndmask_b32_e64 v21, v21, v19, s[8:9]
	v_cndmask_b32_e64 v21, v21, v20, s[10:11]
	v_cvt_pk_bf16_f32 v22, v21, v21
	ds_write_b16 v121, v22 offset:8704
	s_waitcnt lgkmcnt(1)
	ds_read_b128 v[38:41], v0 offset:4608
	ds_read_b128 v[42:45], v0 offset:4624
	ds_read_b128 v[54:57], v0 offset:6656
	ds_read_b128 v[58:61], v0 offset:6672
	ds_read_b32 v34, v1 offset:8480
	v_sub_f32_e32 v10, v10, v32
	v_add_f32_dpp v119, v119, v119 quad_perm:[1,0,3,2] row_mask:0xf bank_mask:0xf bound_ctrl:1
	v_sub_f32_e32 v11, v11, v32
	v_sub_f32_e32 v12, v12, v32
	v_add_f32_dpp v119, v119, v119 quad_perm:[2,3,0,1] row_mask:0xf bank_mask:0xf bound_ctrl:1
	v_sub_f32_e32 v13, v13, v32
	v_sub_f32_e32 v14, v14, v32
	v_add_f32_dpp v20, v119, v119 row_half_mirror row_mask:0xf bank_mask:0xa bound_ctrl:1
	v_sub_f32_e32 v15, v15, v32
	v_sub_f32_e32 v16, v16, v32
	v_sub_f32_e32 v17, v17, v32
	v_fma_f32 v10, v46, v10, v32
	v_fma_f32 v11, v47, v11, v32
	v_mul_f32_e32 v118, v24, v10
	v_fma_f32 v12, v48, v12, v32
	v_fmac_f32_e32 v118, v25, v11
	v_fma_f32 v13, v49, v13, v32
	v_fmac_f32_e32 v118, v26, v12
	v_fma_f32 v14, v50, v14, v32
	v_fmac_f32_e32 v118, v27, v13
	v_fma_f32 v15, v51, v15, v32
	v_fmac_f32_e32 v118, v28, v14
	v_fma_f32 v16, v52, v16, v32
	v_fmac_f32_e32 v118, v29, v15
	v_fma_f32 v17, v53, v17, v32
	v_fmac_f32_e32 v118, v30, v16
	v_fmac_f32_e32 v118, v31, v17
	s_waitcnt vmcnt(15)
	v_lshlrev_b32_e32 v110, 16, v86
	v_and_b32_e32 v111, 0xffff0000, v86
	v_lshlrev_b32_e32 v112, 16, v87
	v_and_b32_e32 v113, 0xffff0000, v87
	s_waitcnt lgkmcnt(0)
	ds_read_b128 v[24:27], v0 offset:4864
	ds_read_b128 v[28:31], v0 offset:4880
	ds_read_b128 v[46:49], v0 offset:6912
	ds_read_b128 v[50:53], v0 offset:6928
	ds_read_b32 v32, v1 offset:8512
	v_sub_f32_e32 v10, v10, v34
	v_add_f32_dpp v118, v118, v118 quad_perm:[1,0,3,2] row_mask:0xf bank_mask:0xf bound_ctrl:1
	v_sub_f32_e32 v11, v11, v34
	v_sub_f32_e32 v12, v12, v34
	v_add_f32_dpp v118, v118, v118 quad_perm:[2,3,0,1] row_mask:0xf bank_mask:0xf bound_ctrl:1
	v_sub_f32_e32 v13, v13, v34
	v_sub_f32_e32 v14, v14, v34
	v_add_f32_dpp v9, v118, v118 row_half_mirror row_mask:0xf bank_mask:0x5 bound_ctrl:1
	v_sub_f32_e32 v15, v15, v34
	v_sub_f32_e32 v16, v16, v34
	v_sub_f32_e32 v17, v17, v34
	v_fma_f32 v10, v54, v10, v34
	v_fma_f32 v11, v55, v11, v34
	v_mul_f32_e32 v119, v38, v10
	v_fma_f32 v12, v56, v12, v34
	v_fmac_f32_e32 v119, v39, v11
	v_fma_f32 v13, v57, v13, v34
	v_fmac_f32_e32 v119, v40, v12
	v_fma_f32 v14, v58, v14, v34
	v_fmac_f32_e32 v119, v41, v13
	v_fma_f32 v15, v59, v15, v34
	v_fmac_f32_e32 v119, v42, v14
	v_fma_f32 v16, v60, v16, v34
	v_fmac_f32_e32 v119, v43, v15
	v_fma_f32 v17, v61, v17, v34
	v_fmac_f32_e32 v119, v44, v16
	v_fmac_f32_e32 v119, v45, v17
	ds_write_b128 v2, v[110:113] offset:0
	v_lshlrev_b32_e32 v114, 16, v88
	v_and_b32_e32 v115, 0xffff0000, v88
	v_lshlrev_b32_e32 v116, 16, v89
	v_and_b32_e32 v117, 0xffff0000, v89
	s_waitcnt lgkmcnt(1)
	ds_read_b128 v[38:41], v0 offset:5120
	ds_read_b128 v[42:45], v0 offset:5136
	ds_read_b128 v[54:57], v0 offset:7168
	ds_read_b128 v[58:61], v0 offset:7184
	ds_read_b32 v34, v1 offset:8544
	v_sub_f32_e32 v10, v10, v32
	v_add_f32_dpp v119, v119, v119 quad_perm:[1,0,3,2] row_mask:0xf bank_mask:0xf bound_ctrl:1
	v_sub_f32_e32 v11, v11, v32
	v_sub_f32_e32 v12, v12, v32
	v_add_f32_dpp v119, v119, v119 quad_perm:[2,3,0,1] row_mask:0xf bank_mask:0xf bound_ctrl:1
	v_sub_f32_e32 v13, v13, v32
	v_sub_f32_e32 v14, v14, v32
	v_add_f32_dpp v18, v119, v119 row_half_mirror row_mask:0xf bank_mask:0x5 bound_ctrl:1
	v_sub_f32_e32 v15, v15, v32
	v_sub_f32_e32 v16, v16, v32
	v_sub_f32_e32 v17, v17, v32
	v_fma_f32 v10, v46, v10, v32
	v_fma_f32 v11, v47, v11, v32
	v_mul_f32_e32 v118, v24, v10
	v_fma_f32 v12, v48, v12, v32
	v_fmac_f32_e32 v118, v25, v11
	v_fma_f32 v13, v49, v13, v32
	v_fmac_f32_e32 v118, v26, v12
	v_fma_f32 v14, v50, v14, v32
	v_fmac_f32_e32 v118, v27, v13
	v_fma_f32 v15, v51, v15, v32
	v_fmac_f32_e32 v118, v28, v14
	v_fma_f32 v16, v52, v16, v32
	v_fmac_f32_e32 v118, v29, v15
	v_fma_f32 v17, v53, v17, v32
	v_fmac_f32_e32 v118, v30, v16
	v_fmac_f32_e32 v118, v31, v17
	ds_write_b128 v2, v[114:117] offset:16
	s_waitcnt vmcnt(13)
	ds_write_b128 v2, v[90:93] offset:2048
	ds_write_b128 v2, v[94:97] offset:2064
	s_waitcnt vmcnt(12)
	s_waitcnt lgkmcnt(3)
	ds_read_b128 v[24:27], v0 offset:5376
	ds_read_b128 v[28:31], v0 offset:5392
	ds_read_b128 v[46:49], v0 offset:7424
	ds_read_b128 v[50:53], v0 offset:7440
	ds_read_b32 v32, v1 offset:8576
	v_sub_f32_e32 v10, v10, v34
	v_add_f32_dpp v118, v118, v118 quad_perm:[1,0,3,2] row_mask:0xf bank_mask:0xf bound_ctrl:1
	v_sub_f32_e32 v11, v11, v34
	v_sub_f32_e32 v12, v12, v34
	v_add_f32_dpp v118, v118, v118 quad_perm:[2,3,0,1] row_mask:0xf bank_mask:0xf bound_ctrl:1
	v_sub_f32_e32 v13, v13, v34
	v_sub_f32_e32 v14, v14, v34
	v_add_f32_dpp v19, v118, v118 row_half_mirror row_mask:0xf bank_mask:0x5 bound_ctrl:1
	v_sub_f32_e32 v15, v15, v34
	v_sub_f32_e32 v16, v16, v34
	v_sub_f32_e32 v17, v17, v34
	v_fma_f32 v10, v54, v10, v34
	v_fma_f32 v11, v55, v11, v34
	v_mul_f32_e32 v119, v38, v10
	v_fma_f32 v12, v56, v12, v34
	v_fmac_f32_e32 v119, v39, v11
	v_fma_f32 v13, v57, v13, v34
	v_fmac_f32_e32 v119, v40, v12
	v_fma_f32 v14, v58, v14, v34
	v_fmac_f32_e32 v119, v41, v13
	v_fma_f32 v15, v59, v15, v34
	v_fmac_f32_e32 v119, v42, v14
	v_fma_f32 v16, v60, v16, v34
	v_fmac_f32_e32 v119, v43, v15
	v_fma_f32 v17, v61, v17, v34
	v_fmac_f32_e32 v119, v44, v16
	v_fmac_f32_e32 v119, v45, v17
	v_lshlrev_b32_e32 v35, 16, v35
	s_nop 0
	ds_write_b32 v4, v35 offset:4096
	s_waitcnt lgkmcnt(1)
	ds_read_b128 v[38:41], v0 offset:5632
	ds_read_b128 v[42:45], v0 offset:5648
	ds_read_b128 v[54:57], v0 offset:7680
	ds_read_b128 v[58:61], v0 offset:7696
	ds_read_b32 v34, v1 offset:8608
	v_sub_f32_e32 v10, v10, v32
	v_add_f32_dpp v119, v119, v119 quad_perm:[1,0,3,2] row_mask:0xf bank_mask:0xf bound_ctrl:1
	v_sub_f32_e32 v11, v11, v32
	v_sub_f32_e32 v12, v12, v32
	v_add_f32_dpp v119, v119, v119 quad_perm:[2,3,0,1] row_mask:0xf bank_mask:0xf bound_ctrl:1
	v_sub_f32_e32 v13, v13, v32
	v_sub_f32_e32 v14, v14, v32
	v_add_f32_dpp v20, v119, v119 row_half_mirror row_mask:0xf bank_mask:0x5 bound_ctrl:1
	v_sub_f32_e32 v15, v15, v32
	v_sub_f32_e32 v16, v16, v32
	v_sub_f32_e32 v17, v17, v32
	v_fma_f32 v10, v46, v10, v32
	v_fma_f32 v11, v47, v11, v32
	v_mul_f32_e32 v118, v24, v10
	v_fma_f32 v12, v48, v12, v32
	v_fmac_f32_e32 v118, v25, v11
	v_fma_f32 v13, v49, v13, v32
	v_fmac_f32_e32 v118, v26, v12
	v_fma_f32 v14, v50, v14, v32
	v_fmac_f32_e32 v118, v27, v13
	v_fma_f32 v15, v51, v15, v32
	v_fmac_f32_e32 v118, v28, v14
	v_fma_f32 v16, v52, v16, v32
	v_fmac_f32_e32 v118, v29, v15
	v_fma_f32 v17, v53, v17, v32
	v_fmac_f32_e32 v118, v30, v16
	v_fmac_f32_e32 v118, v31, v17
	global_load_dwordx4 v[86:89], v5, s[94:95]
	global_load_dwordx4 v[90:93], v8, s[94:95]
	global_load_dwordx4 v[94:97], v8, s[94:95] offset:16
	global_load_ushort v35, v6, s[94:95]
	v_add_u32_e32 v5, 0x6800, v5
	v_add_u32_e32 v8, 0x3180, v8
	v_add_u32_e32 v6, 0x10000, v6
	s_waitcnt lgkmcnt(0)
	ds_read_b128 v[24:27], v0 offset:5888
	ds_read_b128 v[28:31], v0 offset:5904
	ds_read_b128 v[46:49], v0 offset:7936
	ds_read_b128 v[50:53], v0 offset:7952
	ds_read_b32 v32, v1 offset:8640
	v_sub_f32_e32 v10, v10, v34
	v_add_f32_dpp v118, v118, v118 quad_perm:[1,0,3,2] row_mask:0xf bank_mask:0xf bound_ctrl:1
	v_sub_f32_e32 v11, v11, v34
	v_sub_f32_e32 v12, v12, v34
	v_add_f32_dpp v118, v118, v118 quad_perm:[2,3,0,1] row_mask:0xf bank_mask:0xf bound_ctrl:1
	v_sub_f32_e32 v13, v13, v34
	v_sub_f32_e32 v14, v14, v34
	v_add_f32_dpp v9, v118, v118 row_half_mirror row_mask:0xf bank_mask:0xa bound_ctrl:1
	v_sub_f32_e32 v15, v15, v34
	v_sub_f32_e32 v16, v16, v34
	v_sub_f32_e32 v17, v17, v34
	v_fma_f32 v10, v54, v10, v34
	v_fma_f32 v11, v55, v11, v34
	v_mul_f32_e32 v119, v38, v10
	v_fma_f32 v12, v56, v12, v34
	v_fmac_f32_e32 v119, v39, v11
	v_fma_f32 v13, v57, v13, v34
	v_fmac_f32_e32 v119, v40, v12
	v_fma_f32 v14, v58, v14, v34
	v_fmac_f32_e32 v119, v41, v13
	v_fma_f32 v15, v59, v15, v34
	v_fmac_f32_e32 v119, v42, v14
	v_fma_f32 v16, v60, v16, v34
	v_fmac_f32_e32 v119, v43, v15
	v_fma_f32 v17, v61, v17, v34
	v_fmac_f32_e32 v119, v44, v16
	v_fmac_f32_e32 v119, v45, v17
	s_waitcnt lgkmcnt(0)
	ds_read_b128 v[38:41], v0 offset:6144
	ds_read_b128 v[42:45], v0 offset:6160
	ds_read_b128 v[54:57], v0 offset:8192
	ds_read_b128 v[58:61], v0 offset:8208
	ds_read_b32 v34, v1 offset:8672
	v_sub_f32_e32 v10, v10, v32
	v_add_f32_dpp v119, v119, v119 quad_perm:[1,0,3,2] row_mask:0xf bank_mask:0xf bound_ctrl:1
	v_sub_f32_e32 v11, v11, v32
	v_sub_f32_e32 v12, v12, v32
	v_add_f32_dpp v119, v119, v119 quad_perm:[2,3,0,1] row_mask:0xf bank_mask:0xf bound_ctrl:1
	v_sub_f32_e32 v13, v13, v32
	v_sub_f32_e32 v14, v14, v32
	v_add_f32_dpp v18, v119, v119 row_half_mirror row_mask:0xf bank_mask:0xa bound_ctrl:1
	v_sub_f32_e32 v15, v15, v32
	v_sub_f32_e32 v16, v16, v32
	v_sub_f32_e32 v17, v17, v32
	v_fma_f32 v10, v46, v10, v32
	v_fma_f32 v11, v47, v11, v32
	v_mul_f32_e32 v118, v24, v10
	v_fma_f32 v12, v48, v12, v32
	v_fmac_f32_e32 v118, v25, v11
	v_fma_f32 v13, v49, v13, v32
	v_fmac_f32_e32 v118, v26, v12
	v_fma_f32 v14, v50, v14, v32
	v_fmac_f32_e32 v118, v27, v13
	v_fma_f32 v15, v51, v15, v32
	v_fmac_f32_e32 v118, v28, v14
	v_fma_f32 v16, v52, v16, v32
	v_fmac_f32_e32 v118, v29, v15
	v_fma_f32 v17, v53, v17, v32
	v_fmac_f32_e32 v118, v30, v16
	v_fmac_f32_e32 v118, v31, v17
	s_waitcnt lgkmcnt(0)
	ds_read_b128 v[24:27], v0 offset:0
	ds_read_b128 v[28:31], v0 offset:16
	ds_read_b128 v[46:49], v0 offset:2048
	ds_read_b128 v[50:53], v0 offset:2064
	ds_read_b32 v32, v1 offset:4096
	v_sub_f32_e32 v10, v10, v34
	v_add_f32_dpp v118, v118, v118 quad_perm:[1,0,3,2] row_mask:0xf bank_mask:0xf bound_ctrl:1
	v_sub_f32_e32 v11, v11, v34
	v_sub_f32_e32 v12, v12, v34
	v_add_f32_dpp v118, v118, v118 quad_perm:[2,3,0,1] row_mask:0xf bank_mask:0xf bound_ctrl:1
	v_sub_f32_e32 v13, v13, v34
	v_sub_f32_e32 v14, v14, v34
	v_add_f32_dpp v19, v118, v118 row_half_mirror row_mask:0xf bank_mask:0xa bound_ctrl:1
	v_sub_f32_e32 v15, v15, v34
	v_sub_f32_e32 v16, v16, v34
	v_sub_f32_e32 v17, v17, v34
	v_fma_f32 v10, v54, v10, v34
	v_fma_f32 v11, v55, v11, v34
	v_mul_f32_e32 v119, v38, v10
	v_fma_f32 v12, v56, v12, v34
	v_fmac_f32_e32 v119, v39, v11
	v_fma_f32 v13, v57, v13, v34
	v_fmac_f32_e32 v119, v40, v12
	v_fma_f32 v14, v58, v14, v34
	v_fmac_f32_e32 v119, v41, v13
	v_fma_f32 v15, v59, v15, v34
	v_fmac_f32_e32 v119, v42, v14
	v_fma_f32 v16, v60, v16, v34
	v_fmac_f32_e32 v119, v43, v15
	v_fma_f32 v17, v61, v17, v34
	v_fmac_f32_e32 v119, v44, v16
	v_fmac_f32_e32 v119, v45, v17
	s_nop 1
	v_add_f32_dpp v119, v119, v119 quad_perm:[1,0,3,2] row_mask:0xf bank_mask:0xf bound_ctrl:1
	s_nop 1
	v_add_f32_dpp v119, v119, v119 quad_perm:[2,3,0,1] row_mask:0xf bank_mask:0xf bound_ctrl:1
	s_nop 1
	v_add_f32_dpp v20, v119, v119 row_half_mirror row_mask:0xf bank_mask:0xa bound_ctrl:1
	v_mov_b32_e32 v119, 0
	v_cndmask_b32_e64 v21, v9, v18, s[6:7]
	v_cndmask_b32_e64 v21, v21, v19, s[8:9]
	v_cndmask_b32_e64 v21, v21, v20, s[10:11]
	v_cvt_pk_bf16_f32 v22, v21, v21
	ds_write_b16 v121, v22 offset:8832
	s_waitcnt lgkmcnt(1)
	ds_read_b128 v[38:41], v0 offset:256
	ds_read_b128 v[42:45], v0 offset:272
	ds_read_b128 v[54:57], v0 offset:2304
	ds_read_b128 v[58:61], v0 offset:2320
	ds_read_b32 v34, v1 offset:4128
	v_sub_f32_e32 v10, v10, v32
	v_add_f32_dpp v119, v119, v119 quad_perm:[1,0,3,2] row_mask:0xf bank_mask:0xf bound_ctrl:1
	v_sub_f32_e32 v11, v11, v32
	v_sub_f32_e32 v12, v12, v32
	v_add_f32_dpp v119, v119, v119 quad_perm:[2,3,0,1] row_mask:0xf bank_mask:0xf bound_ctrl:1
	v_sub_f32_e32 v13, v13, v32
	v_sub_f32_e32 v14, v14, v32
	v_add_f32_dpp v20, v119, v119 row_half_mirror row_mask:0xf bank_mask:0xa bound_ctrl:1
	v_sub_f32_e32 v15, v15, v32
	v_sub_f32_e32 v16, v16, v32
	v_sub_f32_e32 v17, v17, v32
	v_fma_f32 v10, v46, v10, v32
	v_fma_f32 v11, v47, v11, v32
	v_mul_f32_e32 v118, v24, v10
	v_fma_f32 v12, v48, v12, v32
	v_fmac_f32_e32 v118, v25, v11
	v_fma_f32 v13, v49, v13, v32
	v_fmac_f32_e32 v118, v26, v12
	v_fma_f32 v14, v50, v14, v32
	v_fmac_f32_e32 v118, v27, v13
	v_fma_f32 v15, v51, v15, v32
	v_fmac_f32_e32 v118, v28, v14
	v_fma_f32 v16, v52, v16, v32
	v_fmac_f32_e32 v118, v29, v15
	v_fma_f32 v17, v53, v17, v32
	v_fmac_f32_e32 v118, v30, v16
	v_fmac_f32_e32 v118, v31, v17
	s_waitcnt vmcnt(15)
	v_lshlrev_b32_e32 v110, 16, v98
	v_and_b32_e32 v111, 0xffff0000, v98
	v_lshlrev_b32_e32 v112, 16, v99
	v_and_b32_e32 v113, 0xffff0000, v99
	s_waitcnt lgkmcnt(0)
	ds_read_b128 v[24:27], v0 offset:512
	ds_read_b128 v[28:31], v0 offset:528
	ds_read_b128 v[46:49], v0 offset:2560
	ds_read_b128 v[50:53], v0 offset:2576
	ds_read_b32 v32, v1 offset:4160
	v_sub_f32_e32 v10, v10, v34
	v_add_f32_dpp v118, v118, v118 quad_perm:[1,0,3,2] row_mask:0xf bank_mask:0xf bound_ctrl:1
	v_sub_f32_e32 v11, v11, v34
	v_sub_f32_e32 v12, v12, v34
	v_add_f32_dpp v118, v118, v118 quad_perm:[2,3,0,1] row_mask:0xf bank_mask:0xf bound_ctrl:1
	v_sub_f32_e32 v13, v13, v34
	v_sub_f32_e32 v14, v14, v34
	v_add_f32_dpp v9, v118, v118 row_half_mirror row_mask:0xf bank_mask:0x5 bound_ctrl:1
	v_sub_f32_e32 v15, v15, v34
	v_sub_f32_e32 v16, v16, v34
	v_sub_f32_e32 v17, v17, v34
	v_fma_f32 v10, v54, v10, v34
	v_fma_f32 v11, v55, v11, v34
	v_mul_f32_e32 v119, v38, v10
	v_fma_f32 v12, v56, v12, v34
	v_fmac_f32_e32 v119, v39, v11
	v_fma_f32 v13, v57, v13, v34
	v_fmac_f32_e32 v119, v40, v12
	v_fma_f32 v14, v58, v14, v34
	v_fmac_f32_e32 v119, v41, v13
	v_fma_f32 v15, v59, v15, v34
	v_fmac_f32_e32 v119, v42, v14
	v_fma_f32 v16, v60, v16, v34
	v_fmac_f32_e32 v119, v43, v15
	v_fma_f32 v17, v61, v17, v34
	v_fmac_f32_e32 v119, v44, v16
	v_fmac_f32_e32 v119, v45, v17
	ds_write_b128 v2, v[110:113] offset:4352
	v_lshlrev_b32_e32 v114, 16, v100
	v_and_b32_e32 v115, 0xffff0000, v100
	v_lshlrev_b32_e32 v116, 16, v101
	v_and_b32_e32 v117, 0xffff0000, v101
	s_waitcnt lgkmcnt(1)
	ds_read_b128 v[38:41], v0 offset:768
	ds_read_b128 v[42:45], v0 offset:784
	ds_read_b128 v[54:57], v0 offset:2816
	ds_read_b128 v[58:61], v0 offset:2832
	ds_read_b32 v34, v1 offset:4192
	v_sub_f32_e32 v10, v10, v32
	v_add_f32_dpp v119, v119, v119 quad_perm:[1,0,3,2] row_mask:0xf bank_mask:0xf bound_ctrl:1
	v_sub_f32_e32 v11, v11, v32
	v_sub_f32_e32 v12, v12, v32
	v_add_f32_dpp v119, v119, v119 quad_perm:[2,3,0,1] row_mask:0xf bank_mask:0xf bound_ctrl:1
	v_sub_f32_e32 v13, v13, v32
	v_sub_f32_e32 v14, v14, v32
	v_add_f32_dpp v18, v119, v119 row_half_mirror row_mask:0xf bank_mask:0x5 bound_ctrl:1
	v_sub_f32_e32 v15, v15, v32
	v_sub_f32_e32 v16, v16, v32
	v_sub_f32_e32 v17, v17, v32
	v_fma_f32 v10, v46, v10, v32
	v_fma_f32 v11, v47, v11, v32
	v_mul_f32_e32 v118, v24, v10
	v_fma_f32 v12, v48, v12, v32
	v_fmac_f32_e32 v118, v25, v11
	v_fma_f32 v13, v49, v13, v32
	v_fmac_f32_e32 v118, v26, v12
	v_fma_f32 v14, v50, v14, v32
	v_fmac_f32_e32 v118, v27, v13
	v_fma_f32 v15, v51, v15, v32
	v_fmac_f32_e32 v118, v28, v14
	v_fma_f32 v16, v52, v16, v32
	v_fmac_f32_e32 v118, v29, v15
	v_fma_f32 v17, v53, v17, v32
	v_fmac_f32_e32 v118, v30, v16
	v_fmac_f32_e32 v118, v31, v17
	ds_write_b128 v2, v[114:117] offset:4368
	s_waitcnt vmcnt(13)
	ds_write_b128 v2, v[102:105] offset:6400
	ds_write_b128 v2, v[106:109] offset:6416
	s_waitcnt vmcnt(12)
	s_waitcnt lgkmcnt(3)
	ds_read_b128 v[24:27], v0 offset:1024
	ds_read_b128 v[28:31], v0 offset:1040
	ds_read_b128 v[46:49], v0 offset:3072
	ds_read_b128 v[50:53], v0 offset:3088
	ds_read_b32 v32, v1 offset:4224
	v_sub_f32_e32 v10, v10, v34
	v_add_f32_dpp v118, v118, v118 quad_perm:[1,0,3,2] row_mask:0xf bank_mask:0xf bound_ctrl:1
	v_sub_f32_e32 v11, v11, v34
	v_sub_f32_e32 v12, v12, v34
	v_add_f32_dpp v118, v118, v118 quad_perm:[2,3,0,1] row_mask:0xf bank_mask:0xf bound_ctrl:1
	v_sub_f32_e32 v13, v13, v34
	v_sub_f32_e32 v14, v14, v34
	v_add_f32_dpp v19, v118, v118 row_half_mirror row_mask:0xf bank_mask:0x5 bound_ctrl:1
	v_sub_f32_e32 v15, v15, v34
	v_sub_f32_e32 v16, v16, v34
	v_sub_f32_e32 v17, v17, v34
	v_fma_f32 v10, v54, v10, v34
	v_fma_f32 v11, v55, v11, v34
	v_mul_f32_e32 v119, v38, v10
	v_fma_f32 v12, v56, v12, v34
	v_fmac_f32_e32 v119, v39, v11
	v_fma_f32 v13, v57, v13, v34
	v_fmac_f32_e32 v119, v40, v12
	v_fma_f32 v14, v58, v14, v34
	v_fmac_f32_e32 v119, v41, v13
	v_fma_f32 v15, v59, v15, v34
	v_fmac_f32_e32 v119, v42, v14
	v_fma_f32 v16, v60, v16, v34
	v_fmac_f32_e32 v119, v43, v15
	v_fma_f32 v17, v61, v17, v34
	v_fmac_f32_e32 v119, v44, v16
	v_fmac_f32_e32 v119, v45, v17
	v_lshlrev_b32_e32 v36, 16, v36
	s_nop 0
	ds_write_b32 v4, v36 offset:8448
	s_waitcnt lgkmcnt(1)
	ds_read_b128 v[38:41], v0 offset:1280
	ds_read_b128 v[42:45], v0 offset:1296
	ds_read_b128 v[54:57], v0 offset:3328
	ds_read_b128 v[58:61], v0 offset:3344
	ds_read_b32 v34, v1 offset:4256
	v_sub_f32_e32 v10, v10, v32
	v_add_f32_dpp v119, v119, v119 quad_perm:[1,0,3,2] row_mask:0xf bank_mask:0xf bound_ctrl:1
	v_sub_f32_e32 v11, v11, v32
	v_sub_f32_e32 v12, v12, v32
	v_add_f32_dpp v119, v119, v119 quad_perm:[2,3,0,1] row_mask:0xf bank_mask:0xf bound_ctrl:1
	v_sub_f32_e32 v13, v13, v32
	v_sub_f32_e32 v14, v14, v32
	v_add_f32_dpp v20, v119, v119 row_half_mirror row_mask:0xf bank_mask:0x5 bound_ctrl:1
	v_sub_f32_e32 v15, v15, v32
	v_sub_f32_e32 v16, v16, v32
	v_sub_f32_e32 v17, v17, v32
	v_fma_f32 v10, v46, v10, v32
	v_fma_f32 v11, v47, v11, v32
	v_mul_f32_e32 v118, v24, v10
	v_fma_f32 v12, v48, v12, v32
	v_fmac_f32_e32 v118, v25, v11
	v_fma_f32 v13, v49, v13, v32
	v_fmac_f32_e32 v118, v26, v12
	v_fma_f32 v14, v50, v14, v32
	v_fmac_f32_e32 v118, v27, v13
	v_fma_f32 v15, v51, v15, v32
	v_fmac_f32_e32 v118, v28, v14
	v_fma_f32 v16, v52, v16, v32
	v_fmac_f32_e32 v118, v29, v15
	v_fma_f32 v17, v53, v17, v32
	v_fmac_f32_e32 v118, v30, v16
	v_fmac_f32_e32 v118, v31, v17
	global_load_dwordx4 v[98:101], v5, s[94:95]
	global_load_dwordx4 v[102:105], v8, s[94:95]
	global_load_dwordx4 v[106:109], v8, s[94:95] offset:16
	global_load_ushort v36, v6, s[94:95]
	v_add_u32_e32 v5, 0x6800, v5
	v_add_u32_e32 v8, 0x3180, v8
	v_add_u32_e32 v6, 0x10000, v6
	s_waitcnt lgkmcnt(0)
	ds_read_b128 v[24:27], v0 offset:1536
	ds_read_b128 v[28:31], v0 offset:1552
	ds_read_b128 v[46:49], v0 offset:3584
	ds_read_b128 v[50:53], v0 offset:3600
	ds_read_b32 v32, v1 offset:4288
	v_sub_f32_e32 v10, v10, v34
	v_add_f32_dpp v118, v118, v118 quad_perm:[1,0,3,2] row_mask:0xf bank_mask:0xf bound_ctrl:1
	v_sub_f32_e32 v11, v11, v34
	v_sub_f32_e32 v12, v12, v34
	v_add_f32_dpp v118, v118, v118 quad_perm:[2,3,0,1] row_mask:0xf bank_mask:0xf bound_ctrl:1
	v_sub_f32_e32 v13, v13, v34
	v_sub_f32_e32 v14, v14, v34
	v_add_f32_dpp v9, v118, v118 row_half_mirror row_mask:0xf bank_mask:0xa bound_ctrl:1
	v_sub_f32_e32 v15, v15, v34
	v_sub_f32_e32 v16, v16, v34
	v_sub_f32_e32 v17, v17, v34
	v_fma_f32 v10, v54, v10, v34
	v_fma_f32 v11, v55, v11, v34
	v_mul_f32_e32 v119, v38, v10
	v_fma_f32 v12, v56, v12, v34
	v_fmac_f32_e32 v119, v39, v11
	v_fma_f32 v13, v57, v13, v34
	v_fmac_f32_e32 v119, v40, v12
	v_fma_f32 v14, v58, v14, v34
	v_fmac_f32_e32 v119, v41, v13
	v_fma_f32 v15, v59, v15, v34
	v_fmac_f32_e32 v119, v42, v14
	v_fma_f32 v16, v60, v16, v34
	v_fmac_f32_e32 v119, v43, v15
	v_fma_f32 v17, v61, v17, v34
	v_fmac_f32_e32 v119, v44, v16
	v_fmac_f32_e32 v119, v45, v17
	s_waitcnt lgkmcnt(0)
	ds_read_b128 v[38:41], v0 offset:1792
	ds_read_b128 v[42:45], v0 offset:1808
	ds_read_b128 v[54:57], v0 offset:3840
	ds_read_b128 v[58:61], v0 offset:3856
	ds_read_b32 v34, v1 offset:4320
	v_sub_f32_e32 v10, v10, v32
	v_add_f32_dpp v119, v119, v119 quad_perm:[1,0,3,2] row_mask:0xf bank_mask:0xf bound_ctrl:1
	v_sub_f32_e32 v11, v11, v32
	v_sub_f32_e32 v12, v12, v32
	v_add_f32_dpp v119, v119, v119 quad_perm:[2,3,0,1] row_mask:0xf bank_mask:0xf bound_ctrl:1
	v_sub_f32_e32 v13, v13, v32
	v_sub_f32_e32 v14, v14, v32
	v_add_f32_dpp v18, v119, v119 row_half_mirror row_mask:0xf bank_mask:0xa bound_ctrl:1
	v_sub_f32_e32 v15, v15, v32
	v_sub_f32_e32 v16, v16, v32
	v_sub_f32_e32 v17, v17, v32
	v_fma_f32 v10, v46, v10, v32
	v_fma_f32 v11, v47, v11, v32
	v_mul_f32_e32 v118, v24, v10
	v_fma_f32 v12, v48, v12, v32
	v_fmac_f32_e32 v118, v25, v11
	v_fma_f32 v13, v49, v13, v32
	v_fmac_f32_e32 v118, v26, v12
	v_fma_f32 v14, v50, v14, v32
	v_fmac_f32_e32 v118, v27, v13
	v_fma_f32 v15, v51, v15, v32
	v_fmac_f32_e32 v118, v28, v14
	v_fma_f32 v16, v52, v16, v32
	v_fmac_f32_e32 v118, v29, v15
	v_fma_f32 v17, v53, v17, v32
	v_fmac_f32_e32 v118, v30, v16
	v_fmac_f32_e32 v118, v31, v17
	s_waitcnt lgkmcnt(0)
	ds_read_b128 v[24:27], v0 offset:4352
	ds_read_b128 v[28:31], v0 offset:4368
	ds_read_b128 v[46:49], v0 offset:6400
	ds_read_b128 v[50:53], v0 offset:6416
	ds_read_b32 v32, v1 offset:8448
	v_sub_f32_e32 v10, v10, v34
	v_add_f32_dpp v118, v118, v118 quad_perm:[1,0,3,2] row_mask:0xf bank_mask:0xf bound_ctrl:1
	v_sub_f32_e32 v11, v11, v34
	v_sub_f32_e32 v12, v12, v34
	v_add_f32_dpp v118, v118, v118 quad_perm:[2,3,0,1] row_mask:0xf bank_mask:0xf bound_ctrl:1
	v_sub_f32_e32 v13, v13, v34
	v_sub_f32_e32 v14, v14, v34
	v_add_f32_dpp v19, v118, v118 row_half_mirror row_mask:0xf bank_mask:0xa bound_ctrl:1
	v_sub_f32_e32 v15, v15, v34
	v_sub_f32_e32 v16, v16, v34
	v_sub_f32_e32 v17, v17, v34
	v_fma_f32 v10, v54, v10, v34
	v_fma_f32 v11, v55, v11, v34
	v_mul_f32_e32 v119, v38, v10
	v_fma_f32 v12, v56, v12, v34
	v_fmac_f32_e32 v119, v39, v11
	v_fma_f32 v13, v57, v13, v34
	v_fmac_f32_e32 v119, v40, v12
	v_fma_f32 v14, v58, v14, v34
	v_fmac_f32_e32 v119, v41, v13
	v_fma_f32 v15, v59, v15, v34
	v_fmac_f32_e32 v119, v42, v14
	v_fma_f32 v16, v60, v16, v34
	v_fmac_f32_e32 v119, v43, v15
	v_fma_f32 v17, v61, v17, v34
	v_fmac_f32_e32 v119, v44, v16
	v_fmac_f32_e32 v119, v45, v17
	s_nop 1
	v_add_f32_dpp v119, v119, v119 quad_perm:[1,0,3,2] row_mask:0xf bank_mask:0xf bound_ctrl:1
	s_nop 1
	v_add_f32_dpp v119, v119, v119 quad_perm:[2,3,0,1] row_mask:0xf bank_mask:0xf bound_ctrl:1
	s_nop 1
	v_add_f32_dpp v20, v119, v119 row_half_mirror row_mask:0xf bank_mask:0xa bound_ctrl:1
	v_mov_b32_e32 v119, 0
	v_cndmask_b32_e64 v21, v9, v18, s[6:7]
	v_cndmask_b32_e64 v21, v21, v19, s[8:9]
	v_cndmask_b32_e64 v21, v21, v20, s[10:11]
	v_cvt_pk_bf16_f32 v22, v21, v21
	ds_write_b16 v121, v22 offset:8960
	s_waitcnt lgkmcnt(1)
	ds_read_b128 v[38:41], v0 offset:4608
	ds_read_b128 v[42:45], v0 offset:4624
	ds_read_b128 v[54:57], v0 offset:6656
	ds_read_b128 v[58:61], v0 offset:6672
	ds_read_b32 v34, v1 offset:8480
	v_sub_f32_e32 v10, v10, v32
	v_add_f32_dpp v119, v119, v119 quad_perm:[1,0,3,2] row_mask:0xf bank_mask:0xf bound_ctrl:1
	v_sub_f32_e32 v11, v11, v32
	v_sub_f32_e32 v12, v12, v32
	v_add_f32_dpp v119, v119, v119 quad_perm:[2,3,0,1] row_mask:0xf bank_mask:0xf bound_ctrl:1
	v_sub_f32_e32 v13, v13, v32
	v_sub_f32_e32 v14, v14, v32
	v_add_f32_dpp v20, v119, v119 row_half_mirror row_mask:0xf bank_mask:0xa bound_ctrl:1
	v_sub_f32_e32 v15, v15, v32
	v_sub_f32_e32 v16, v16, v32
	v_sub_f32_e32 v17, v17, v32
	v_fma_f32 v10, v46, v10, v32
	v_fma_f32 v11, v47, v11, v32
	v_mul_f32_e32 v118, v24, v10
	v_fma_f32 v12, v48, v12, v32
	v_fmac_f32_e32 v118, v25, v11
	v_fma_f32 v13, v49, v13, v32
	v_fmac_f32_e32 v118, v26, v12
	v_fma_f32 v14, v50, v14, v32
	v_fmac_f32_e32 v118, v27, v13
	v_fma_f32 v15, v51, v15, v32
	v_fmac_f32_e32 v118, v28, v14
	v_fma_f32 v16, v52, v16, v32
	v_fmac_f32_e32 v118, v29, v15
	v_fma_f32 v17, v53, v17, v32
	v_fmac_f32_e32 v118, v30, v16
	v_fmac_f32_e32 v118, v31, v17
	s_waitcnt vmcnt(15)
	v_lshlrev_b32_e32 v110, 16, v62
	v_and_b32_e32 v111, 0xffff0000, v62
	v_lshlrev_b32_e32 v112, 16, v63
	v_and_b32_e32 v113, 0xffff0000, v63
	s_waitcnt lgkmcnt(0)
	ds_read_b128 v[24:27], v0 offset:4864
	ds_read_b128 v[28:31], v0 offset:4880
	ds_read_b128 v[46:49], v0 offset:6912
	ds_read_b128 v[50:53], v0 offset:6928
	ds_read_b32 v32, v1 offset:8512
	v_sub_f32_e32 v10, v10, v34
	v_add_f32_dpp v118, v118, v118 quad_perm:[1,0,3,2] row_mask:0xf bank_mask:0xf bound_ctrl:1
	v_sub_f32_e32 v11, v11, v34
	v_sub_f32_e32 v12, v12, v34
	v_add_f32_dpp v118, v118, v118 quad_perm:[2,3,0,1] row_mask:0xf bank_mask:0xf bound_ctrl:1
	v_sub_f32_e32 v13, v13, v34
	v_sub_f32_e32 v14, v14, v34
	v_add_f32_dpp v9, v118, v118 row_half_mirror row_mask:0xf bank_mask:0x5 bound_ctrl:1
	v_sub_f32_e32 v15, v15, v34
	v_sub_f32_e32 v16, v16, v34
	v_sub_f32_e32 v17, v17, v34
	v_fma_f32 v10, v54, v10, v34
	v_fma_f32 v11, v55, v11, v34
	v_mul_f32_e32 v119, v38, v10
	v_fma_f32 v12, v56, v12, v34
	v_fmac_f32_e32 v119, v39, v11
	v_fma_f32 v13, v57, v13, v34
	v_fmac_f32_e32 v119, v40, v12
	v_fma_f32 v14, v58, v14, v34
	v_fmac_f32_e32 v119, v41, v13
	v_fma_f32 v15, v59, v15, v34
	v_fmac_f32_e32 v119, v42, v14
	v_fma_f32 v16, v60, v16, v34
	v_fmac_f32_e32 v119, v43, v15
	v_fma_f32 v17, v61, v17, v34
	v_fmac_f32_e32 v119, v44, v16
	v_fmac_f32_e32 v119, v45, v17
	ds_write_b128 v2, v[110:113] offset:0
	v_lshlrev_b32_e32 v114, 16, v64
	v_and_b32_e32 v115, 0xffff0000, v64
	v_lshlrev_b32_e32 v116, 16, v65
	v_and_b32_e32 v117, 0xffff0000, v65
	s_waitcnt lgkmcnt(1)
	ds_read_b128 v[38:41], v0 offset:5120
	ds_read_b128 v[42:45], v0 offset:5136
	ds_read_b128 v[54:57], v0 offset:7168
	ds_read_b128 v[58:61], v0 offset:7184
	ds_read_b32 v34, v1 offset:8544
	v_sub_f32_e32 v10, v10, v32
	v_add_f32_dpp v119, v119, v119 quad_perm:[1,0,3,2] row_mask:0xf bank_mask:0xf bound_ctrl:1
	v_sub_f32_e32 v11, v11, v32
	v_sub_f32_e32 v12, v12, v32
	v_add_f32_dpp v119, v119, v119 quad_perm:[2,3,0,1] row_mask:0xf bank_mask:0xf bound_ctrl:1
	v_sub_f32_e32 v13, v13, v32
	v_sub_f32_e32 v14, v14, v32
	v_add_f32_dpp v18, v119, v119 row_half_mirror row_mask:0xf bank_mask:0x5 bound_ctrl:1
	v_sub_f32_e32 v15, v15, v32
	v_sub_f32_e32 v16, v16, v32
	v_sub_f32_e32 v17, v17, v32
	v_fma_f32 v10, v46, v10, v32
	v_fma_f32 v11, v47, v11, v32
	v_mul_f32_e32 v118, v24, v10
	v_fma_f32 v12, v48, v12, v32
	v_fmac_f32_e32 v118, v25, v11
	v_fma_f32 v13, v49, v13, v32
	v_fmac_f32_e32 v118, v26, v12
	v_fma_f32 v14, v50, v14, v32
	v_fmac_f32_e32 v118, v27, v13
	v_fma_f32 v15, v51, v15, v32
	v_fmac_f32_e32 v118, v28, v14
	v_fma_f32 v16, v52, v16, v32
	v_fmac_f32_e32 v118, v29, v15
	v_fma_f32 v17, v53, v17, v32
	v_fmac_f32_e32 v118, v30, v16
	v_fmac_f32_e32 v118, v31, v17
	ds_write_b128 v2, v[114:117] offset:16
	s_waitcnt vmcnt(13)
	ds_write_b128 v2, v[66:69] offset:2048
	ds_write_b128 v2, v[70:73] offset:2064
	s_waitcnt vmcnt(12)
	s_waitcnt lgkmcnt(3)
	ds_read_b128 v[24:27], v0 offset:5376
	ds_read_b128 v[28:31], v0 offset:5392
	ds_read_b128 v[46:49], v0 offset:7424
	ds_read_b128 v[50:53], v0 offset:7440
	ds_read_b32 v32, v1 offset:8576
	v_sub_f32_e32 v10, v10, v34
	v_add_f32_dpp v118, v118, v118 quad_perm:[1,0,3,2] row_mask:0xf bank_mask:0xf bound_ctrl:1
	v_sub_f32_e32 v11, v11, v34
	v_sub_f32_e32 v12, v12, v34
	v_add_f32_dpp v118, v118, v118 quad_perm:[2,3,0,1] row_mask:0xf bank_mask:0xf bound_ctrl:1
	v_sub_f32_e32 v13, v13, v34
	v_sub_f32_e32 v14, v14, v34
	v_add_f32_dpp v19, v118, v118 row_half_mirror row_mask:0xf bank_mask:0x5 bound_ctrl:1
	v_sub_f32_e32 v15, v15, v34
	v_sub_f32_e32 v16, v16, v34
	v_sub_f32_e32 v17, v17, v34
	v_fma_f32 v10, v54, v10, v34
	v_fma_f32 v11, v55, v11, v34
	v_mul_f32_e32 v119, v38, v10
	v_fma_f32 v12, v56, v12, v34
	v_fmac_f32_e32 v119, v39, v11
	v_fma_f32 v13, v57, v13, v34
	v_fmac_f32_e32 v119, v40, v12
	v_fma_f32 v14, v58, v14, v34
	v_fmac_f32_e32 v119, v41, v13
	v_fma_f32 v15, v59, v15, v34
	v_fmac_f32_e32 v119, v42, v14
	v_fma_f32 v16, v60, v16, v34
	v_fmac_f32_e32 v119, v43, v15
	v_fma_f32 v17, v61, v17, v34
	v_fmac_f32_e32 v119, v44, v16
	v_fmac_f32_e32 v119, v45, v17
	v_lshlrev_b32_e32 v23, 16, v23
	s_nop 0
	ds_write_b32 v4, v23 offset:4096
	s_waitcnt lgkmcnt(1)
	ds_read_b128 v[38:41], v0 offset:5632
	ds_read_b128 v[42:45], v0 offset:5648
	ds_read_b128 v[54:57], v0 offset:7680
	ds_read_b128 v[58:61], v0 offset:7696
	ds_read_b32 v34, v1 offset:8608
	v_sub_f32_e32 v10, v10, v32
	v_add_f32_dpp v119, v119, v119 quad_perm:[1,0,3,2] row_mask:0xf bank_mask:0xf bound_ctrl:1
	v_sub_f32_e32 v11, v11, v32
	v_sub_f32_e32 v12, v12, v32
	v_add_f32_dpp v119, v119, v119 quad_perm:[2,3,0,1] row_mask:0xf bank_mask:0xf bound_ctrl:1
	v_sub_f32_e32 v13, v13, v32
	v_sub_f32_e32 v14, v14, v32
	v_add_f32_dpp v20, v119, v119 row_half_mirror row_mask:0xf bank_mask:0x5 bound_ctrl:1
	v_sub_f32_e32 v15, v15, v32
	v_sub_f32_e32 v16, v16, v32
	v_sub_f32_e32 v17, v17, v32
	v_fma_f32 v10, v46, v10, v32
	v_fma_f32 v11, v47, v11, v32
	v_mul_f32_e32 v118, v24, v10
	v_fma_f32 v12, v48, v12, v32
	v_fmac_f32_e32 v118, v25, v11
	v_fma_f32 v13, v49, v13, v32
	v_fmac_f32_e32 v118, v26, v12
	v_fma_f32 v14, v50, v14, v32
	v_fmac_f32_e32 v118, v27, v13
	v_fma_f32 v15, v51, v15, v32
	v_fmac_f32_e32 v118, v28, v14
	v_fma_f32 v16, v52, v16, v32
	v_fmac_f32_e32 v118, v29, v15
	v_fma_f32 v17, v53, v17, v32
	v_fmac_f32_e32 v118, v30, v16
	v_fmac_f32_e32 v118, v31, v17
	global_load_dwordx4 v[62:65], v5, s[94:95]
	global_load_dwordx4 v[66:69], v8, s[94:95]
	global_load_dwordx4 v[70:73], v8, s[94:95] offset:16
	global_load_ushort v23, v6, s[94:95]
	v_add_u32_e32 v5, 0x6800, v5
	v_add_u32_e32 v8, 0x3180, v8
	v_add_u32_e32 v6, 0x10000, v6
	s_waitcnt lgkmcnt(0)
	ds_read_b128 v[24:27], v0 offset:5888
	ds_read_b128 v[28:31], v0 offset:5904
	ds_read_b128 v[46:49], v0 offset:7936
	ds_read_b128 v[50:53], v0 offset:7952
	ds_read_b32 v32, v1 offset:8640
	v_sub_f32_e32 v10, v10, v34
	v_add_f32_dpp v118, v118, v118 quad_perm:[1,0,3,2] row_mask:0xf bank_mask:0xf bound_ctrl:1
	v_sub_f32_e32 v11, v11, v34
	v_sub_f32_e32 v12, v12, v34
	v_add_f32_dpp v118, v118, v118 quad_perm:[2,3,0,1] row_mask:0xf bank_mask:0xf bound_ctrl:1
	v_sub_f32_e32 v13, v13, v34
	v_sub_f32_e32 v14, v14, v34
	v_add_f32_dpp v9, v118, v118 row_half_mirror row_mask:0xf bank_mask:0xa bound_ctrl:1
	v_sub_f32_e32 v15, v15, v34
	v_sub_f32_e32 v16, v16, v34
	v_sub_f32_e32 v17, v17, v34
	v_fma_f32 v10, v54, v10, v34
	v_fma_f32 v11, v55, v11, v34
	v_mul_f32_e32 v119, v38, v10
	v_fma_f32 v12, v56, v12, v34
	v_fmac_f32_e32 v119, v39, v11
	v_fma_f32 v13, v57, v13, v34
	v_fmac_f32_e32 v119, v40, v12
	v_fma_f32 v14, v58, v14, v34
	v_fmac_f32_e32 v119, v41, v13
	v_fma_f32 v15, v59, v15, v34
	v_fmac_f32_e32 v119, v42, v14
	v_fma_f32 v16, v60, v16, v34
	v_fmac_f32_e32 v119, v43, v15
	v_fma_f32 v17, v61, v17, v34
	v_fmac_f32_e32 v119, v44, v16
	v_fmac_f32_e32 v119, v45, v17
	s_waitcnt lgkmcnt(0)
	ds_read_b128 v[38:41], v0 offset:6144
	ds_read_b128 v[42:45], v0 offset:6160
	ds_read_b128 v[54:57], v0 offset:8192
	ds_read_b128 v[58:61], v0 offset:8208
	ds_read_b32 v34, v1 offset:8672
	v_sub_f32_e32 v10, v10, v32
	v_add_f32_dpp v119, v119, v119 quad_perm:[1,0,3,2] row_mask:0xf bank_mask:0xf bound_ctrl:1
	v_sub_f32_e32 v11, v11, v32
	v_sub_f32_e32 v12, v12, v32
	v_add_f32_dpp v119, v119, v119 quad_perm:[2,3,0,1] row_mask:0xf bank_mask:0xf bound_ctrl:1
	v_sub_f32_e32 v13, v13, v32
	v_sub_f32_e32 v14, v14, v32
	v_add_f32_dpp v18, v119, v119 row_half_mirror row_mask:0xf bank_mask:0xa bound_ctrl:1
	v_sub_f32_e32 v15, v15, v32
	v_sub_f32_e32 v16, v16, v32
	v_sub_f32_e32 v17, v17, v32
	v_fma_f32 v10, v46, v10, v32
	v_fma_f32 v11, v47, v11, v32
	v_mul_f32_e32 v118, v24, v10
	v_fma_f32 v12, v48, v12, v32
	v_fmac_f32_e32 v118, v25, v11
	v_fma_f32 v13, v49, v13, v32
	v_fmac_f32_e32 v118, v26, v12
	v_fma_f32 v14, v50, v14, v32
	v_fmac_f32_e32 v118, v27, v13
	v_fma_f32 v15, v51, v15, v32
	v_fmac_f32_e32 v118, v28, v14
	v_fma_f32 v16, v52, v16, v32
	v_fmac_f32_e32 v118, v29, v15
	v_fma_f32 v17, v53, v17, v32
	v_fmac_f32_e32 v118, v30, v16
	v_fmac_f32_e32 v118, v31, v17
	s_waitcnt lgkmcnt(0)
	ds_read_b128 v[24:27], v0 offset:0
	ds_read_b128 v[28:31], v0 offset:16
	ds_read_b128 v[46:49], v0 offset:2048
	ds_read_b128 v[50:53], v0 offset:2064
	ds_read_b32 v32, v1 offset:4096
	v_sub_f32_e32 v10, v10, v34
	v_add_f32_dpp v118, v118, v118 quad_perm:[1,0,3,2] row_mask:0xf bank_mask:0xf bound_ctrl:1
	v_sub_f32_e32 v11, v11, v34
	v_sub_f32_e32 v12, v12, v34
	v_add_f32_dpp v118, v118, v118 quad_perm:[2,3,0,1] row_mask:0xf bank_mask:0xf bound_ctrl:1
	v_sub_f32_e32 v13, v13, v34
	v_sub_f32_e32 v14, v14, v34
	v_add_f32_dpp v19, v118, v118 row_half_mirror row_mask:0xf bank_mask:0xa bound_ctrl:1
	v_sub_f32_e32 v15, v15, v34
	v_sub_f32_e32 v16, v16, v34
	v_sub_f32_e32 v17, v17, v34
	v_fma_f32 v10, v54, v10, v34
	v_fma_f32 v11, v55, v11, v34
	v_mul_f32_e32 v119, v38, v10
	v_fma_f32 v12, v56, v12, v34
	v_fmac_f32_e32 v119, v39, v11
	v_fma_f32 v13, v57, v13, v34
	v_fmac_f32_e32 v119, v40, v12
	v_fma_f32 v14, v58, v14, v34
	v_fmac_f32_e32 v119, v41, v13
	v_fma_f32 v15, v59, v15, v34
	v_fmac_f32_e32 v119, v42, v14
	v_fma_f32 v16, v60, v16, v34
	v_fmac_f32_e32 v119, v43, v15
	v_fma_f32 v17, v61, v17, v34
	v_fmac_f32_e32 v119, v44, v16
	v_fmac_f32_e32 v119, v45, v17
	s_nop 1
	v_add_f32_dpp v119, v119, v119 quad_perm:[1,0,3,2] row_mask:0xf bank_mask:0xf bound_ctrl:1
	s_nop 1
	v_add_f32_dpp v119, v119, v119 quad_perm:[2,3,0,1] row_mask:0xf bank_mask:0xf bound_ctrl:1
	s_nop 1
	v_add_f32_dpp v20, v119, v119 row_half_mirror row_mask:0xf bank_mask:0xa bound_ctrl:1
	v_mov_b32_e32 v119, 0
	v_cndmask_b32_e64 v21, v9, v18, s[6:7]
	v_cndmask_b32_e64 v21, v21, v19, s[8:9]
	v_cndmask_b32_e64 v21, v21, v20, s[10:11]
	v_cvt_pk_bf16_f32 v22, v21, v21
	ds_write_b16 v121, v22 offset:9088
	v_add_u32_e32 v121, 0x200, v121
	s_and_b32 s24, s12, 15
	s_cmp_eq_u32 s24, 1
	s_cbranch_scc0 .Lls2_8_noflush
	ds_read_b128 v[124:127], v122 offset:8704
	s_waitcnt lgkmcnt(0)
	global_store_dwordx4 v7, v[124:127], s[94:95]
	v_add_u32_e32 v7, 0x20000, v7
	s_nop 0
	ds_read_b128 v[124:127], v122 offset:9728
	s_waitcnt lgkmcnt(0)
	global_store_dwordx4 v7, v[124:127], s[94:95]
	v_add_u32_e32 v7, 0x20000, v7
	s_nop 0
	ds_read_b128 v[124:127], v122 offset:10752
	s_waitcnt lgkmcnt(0)
	global_store_dwordx4 v7, v[124:127], s[94:95]
	v_add_u32_e32 v7, 0x20000, v7
	s_nop 0
	ds_read_b128 v[124:127], v122 offset:11776
	s_waitcnt lgkmcnt(0)
	global_store_dwordx4 v7, v[124:127], s[94:95]
	v_add_u32_e32 v7, 0x20000, v7
	s_nop 0
	ds_read_b128 v[124:127], v122 offset:12800
	s_waitcnt lgkmcnt(0)
	global_store_dwordx4 v7, v[124:127], s[94:95]
	v_add_u32_e32 v7, 0x20000, v7
	s_nop 0
	ds_read_b128 v[124:127], v122 offset:13824
	s_waitcnt lgkmcnt(0)
	global_store_dwordx4 v7, v[124:127], s[94:95]
	v_add_u32_e32 v7, 0x20000, v7
	s_nop 0
	ds_read_b128 v[124:127], v122 offset:14848
	s_waitcnt lgkmcnt(0)
	global_store_dwordx4 v7, v[124:127], s[94:95]
	v_add_u32_e32 v7, 0x20000, v7
	s_nop 0
	ds_read_b128 v[124:127], v122 offset:15872
	s_waitcnt lgkmcnt(0)
	global_store_dwordx4 v7, v[124:127], s[94:95]
	v_add_u32_e32 v7, 0x20000, v7
	s_nop 0
	v_subrev_u32_e32 v121, 0x2000, v121
.Lls2_8_noflush:
	s_sub_u32 s12, s12, 1
	s_cmp_lg_u32 s12, 0
	s_cbranch_scc1 .Lls2_8_loop
	global_store_dword v120, v10, s[26:27] offset:0
	global_store_dword v120, v11, s[26:27] offset:256
	global_store_dword v120, v12, s[26:27] offset:512
	global_store_dword v120, v13, s[26:27] offset:768
	global_store_dword v120, v14, s[26:27] offset:1024
	global_store_dword v120, v15, s[26:27] offset:1280
	global_store_dword v120, v16, s[26:27] offset:1536
	global_store_dword v120, v17, s[26:27] offset:1792
	s_waitcnt vmcnt(0) lgkmcnt(0)
	s_setprio 0
	s_branch .Lls_done
.Lls1_8_entry:
	v_and_b32_e32 v114, 63, v196
	v_and_b32_e32 v115, 7, v114
	v_lshrrev_b32_e32 v116, 3, v114
	s_min_u32 s29, s0, 4
	s_mul_i32 s29, s29, 0x5600
	v_and_b32_e32 v117, 3, v115
	v_cmp_eq_u32_e64 s[6:7], 1, v117
	v_cmp_eq_u32_e64 s[8:9], 2, v117
	v_cmp_eq_u32_e64 s[10:11], 3, v117
	v_lshl_add_u32 v0, v115, 4, s29
	v_lshl_add_u32 v1, v116, 2, s29
	s_lshl_b32 s37, s16, 11
	v_lshrrev_b32_e32 v115, 3, v114
	v_and_b32_e32 v116, 7, v114
	v_add_u32_e32 v117, s37, v115
	s_lshl_b32 s21, s17, 7
	s_add_u32 s21, s21, 0x13e00000
	v_mul_u32_u24_e32 v8, 0x630, v117
	v_lshl_add_u32 v8, v116, 4, v8
	v_add_u32_e32 v8, s21, v8
	v_lshlrev_b32_e32 v119, 7, v115
	v_lshl_add_u32 v119, v116, 4, v119
	v_add_u32_e32 v119, s29, v119
	v_and_b32_e32 v115, 31, v114
	v_lshrrev_b32_e32 v116, 2, v115
	v_and_b32_e32 v115, 3, v115
	v_add_u32_e32 v117, s37, v116
	v_cmp_gt_u32_e32 vcc, 32, v114
	s_lshl_b32 s21, s17, 6
	s_add_u32 s22, s21, 0x10800400
	s_add_u32 s44, s21, 0x8400900
	v_mov_b32_e32 v9, 0x2000
	v_mov_b32_e32 v18, 0xd00
	v_cndmask_b32_e32 v9, v9, v18, vcc
	v_mov_b32_e32 v5, s44
	v_mov_b32_e32 v18, s22
	v_cndmask_b32_e32 v5, v5, v18, vcc
	v_mul_lo_u32 v18, v117, v9
	v_add_u32_e32 v5, v5, v18
	v_lshl_add_u32 v5, v115, 4, v5
	v_lshlrev_b32_e32 v9, 3, v9
	v_mov_b32_e32 v2, 0
	v_mov_b32_e32 v18, 1024
	v_cndmask_b32_e32 v2, v2, v18, vcc
	v_lshl_add_u32 v2, v116, 7, v2
	v_lshl_add_u32 v2, v115, 5, v2
	v_add_u32_e32 v2, s29, v2
	v_lshrrev_b32_e32 v116, 3, v114
	v_and_b32_e32 v115, 7, v114
	v_add_u32_e32 v117, s37, v116
	s_lshl_b32 s22, s14, 3
	s_lshl_b32 s21, s17, 6
	s_add_u32 s21, s21, s22
	s_lshl_b32 s44, s21, 1
	s_add_u32 s44, s44, 0x8400a00
	v_lshlrev_b32_e32 v6, 13, v117
	v_lshlrev_b32_e32 v4, 5, v116
	v_lshl_add_u32 v4, v115, 2, v4
	v_lshl_add_u32 v6, v115, 1, v6
	v_add_u32_e32 v6, s44, v6
	v_add_u32_e32 v4, s29, v4
	v_and_b32_e32 v115, 7, v114
	v_lshrrev_b32_e32 v116, 3, v114
	v_add_u32_e32 v117, s37, v114
	v_lshlrev_b32_e32 v7, 11, v117
	s_lshl_b32 s44, s21, 1
	s_add_u32 s44, s44, 0x6300200
	v_add_u32_e32 v7, s44, v7
	s_lshl_b32 s44, s28, 3
	s_add_u32 s44, s44, s16
	s_lshl_b32 s44, s44, 2
	s_add_u32 s44, s44, s17
	s_mul_i32 s44, s44, 0x2000
	s_add_u32 s44, s44, 0x4300000
	s_lshl_b32 s24, s22, 2
	s_add_u32 s44, s44, s24
	v_lshlrev_b32_e32 v120, 10, v115
	v_lshl_add_u32 v120, v116, 2, v120
	v_add_u32_e32 v120, s44, v120
	v_readlane_b32 s26, v253, 29
	v_readlane_b32 s27, v253, 30
	v_lshlrev_b32_e32 v121, 4, v115
	v_lshl_add_u32 v121, v116, 1, v121
	v_add_u32_e32 v121, s29, v121
	v_lshl_add_u32 v122, v114, 4, s29
	v_mov_b32_e32 v10, 0
	v_mov_b32_e32 v11, 0
	v_mov_b32_e32 v12, 0
	v_mov_b32_e32 v13, 0
	v_mov_b32_e32 v14, 0
	v_mov_b32_e32 v15, 0
	v_mov_b32_e32 v16, 0
	v_mov_b32_e32 v17, 0
	v_mov_b32_e32 v61, 0
	v_mov_b32_e32 v118, 0
	s_setprio 2
	s_movk_i32 s12, 64
	s_nop 0
	global_load_dwordx4 v[78:81], v5, s[94:95]
	global_load_dwordx4 v[82:85], v8, s[94:95]
	global_load_ushort v36, v6, s[94:95]
	v_add_u32_e32 v5, v5, v9
	v_add_u32_e32 v8, 0x3180, v8
	v_add_u32_e32 v6, 0x10000, v6
	s_waitcnt vmcnt(0)
	s_waitcnt vmcnt(2)
	v_lshlrev_b32_e32 v110, 16, v78
	v_and_b32_e32 v111, 0xffff0000, v78
	v_lshlrev_b32_e32 v112, 16, v79
	v_and_b32_e32 v113, 0xffff0000, v79
	ds_write_b128 v2, v[110:113] offset:0
	v_lshlrev_b32_e32 v114, 16, v80
	v_and_b32_e32 v115, 0xffff0000, v80
	v_lshlrev_b32_e32 v116, 16, v81
	v_and_b32_e32 v117, 0xffff0000, v81
	ds_write_b128 v2, v[114:117] offset:16
	s_waitcnt vmcnt(1)
	ds_write_b128 v119, v[82:85] offset:2048
	s_waitcnt vmcnt(0)
	v_lshlrev_b32_e32 v36, 16, v36
	s_nop 0
	ds_write_b32 v4, v36 offset:3072
	global_load_dwordx4 v[86:89], v5, s[94:95]
	global_load_dwordx4 v[90:93], v8, s[94:95]
	global_load_ushort v55, v6, s[94:95]
	v_add_u32_e32 v5, v5, v9
	v_add_u32_e32 v8, 0x3180, v8
	v_add_u32_e32 v6, 0x10000, v6
	global_load_dwordx4 v[94:97], v5, s[94:95]
	global_load_dwordx4 v[98:101], v8, s[94:95]
	global_load_ushort v57, v6, s[94:95]
	v_add_u32_e32 v5, v5, v9
	v_add_u32_e32 v8, 0x3180, v8
	v_add_u32_e32 v6, 0x10000, v6
	global_load_dwordx4 v[102:105], v5, s[94:95]
	global_load_dwordx4 v[106:109], v8, s[94:95]
	global_load_ushort v59, v6, s[94:95]
	v_add_u32_e32 v5, v5, v9
	v_add_u32_e32 v8, 0x3180, v8
	v_add_u32_e32 v6, 0x10000, v6
	global_load_dwordx4 v[78:81], v5, s[94:95]
	global_load_dwordx4 v[82:85], v8, s[94:95]
	global_load_ushort v36, v6, s[94:95]
	v_add_u32_e32 v5, v5, v9
	v_add_u32_e32 v8, 0x3180, v8
	v_add_u32_e32 v6, 0x10000, v6
	ds_read_b128 v[20:23], v0 offset:0
	ds_read_b128 v[38:41], v0 offset:1024
	ds_read_b128 v[62:65], v0 offset:2048
	ds_read_b32 v54, v1 offset:3072
	ds_read_b128 v[24:27], v0 offset:128
	ds_read_b128 v[42:45], v0 offset:1152
	ds_read_b128 v[66:69], v0 offset:2176
	ds_read_b32 v56, v1 offset:3104
	ds_read_b128 v[28:31], v0 offset:256
	ds_read_b128 v[46:49], v0 offset:1280
	ds_read_b128 v[70:73], v0 offset:2304
	ds_read_b32 v58, v1 offset:3136
.Lls1_8_loop:
	s_waitcnt lgkmcnt(8)
	v_mul_f32_e32 v10, v62, v10
	v_add_f32_dpp v118, v118, v118 quad_perm:[1,0,3,2] row_mask:0xf bank_mask:0xf bound_ctrl:1
	v_mul_f32_e32 v11, v63, v11
	v_mul_f32_e32 v12, v64, v12
	v_add_f32_dpp v118, v118, v118 quad_perm:[2,3,0,1] row_mask:0xf bank_mask:0xf bound_ctrl:1
	v_mul_f32_e32 v13, v65, v13
	v_fmac_f32_e32 v10, v20, v54
	v_add_f32_dpp v17, v118, v118 row_half_mirror row_mask:0xf bank_mask:0xa bound_ctrl:1
	v_fmac_f32_e32 v11, v21, v54
	v_mul_f32_e32 v61, v38, v10
	v_fmac_f32_e32 v12, v22, v54
	v_fmac_f32_e32 v61, v39, v11
	v_fmac_f32_e32 v13, v23, v54
	v_fmac_f32_e32 v61, v40, v12
	v_fmac_f32_e32 v61, v41, v13
	ds_read_b128 v[32:35], v0 offset:384
	ds_read_b128 v[50:53], v0 offset:1408
	ds_read_b128 v[74:77], v0 offset:2432
	ds_read_b32 v60, v1 offset:3168
	s_waitcnt vmcnt(11)
	v_lshlrev_b32_e32 v110, 16, v86
	v_and_b32_e32 v111, 0xffff0000, v86
	v_lshlrev_b32_e32 v112, 16, v87
	v_and_b32_e32 v113, 0xffff0000, v87
	s_waitcnt lgkmcnt(8)
	v_mul_f32_e32 v10, v66, v10
	v_add_f32_dpp v61, v61, v61 quad_perm:[1,0,3,2] row_mask:0xf bank_mask:0xf bound_ctrl:1
	v_mul_f32_e32 v11, v67, v11
	v_mul_f32_e32 v12, v68, v12
	v_add_f32_dpp v61, v61, v61 quad_perm:[2,3,0,1] row_mask:0xf bank_mask:0xf bound_ctrl:1
	v_mul_f32_e32 v13, v69, v13
	v_fmac_f32_e32 v10, v24, v56
	v_add_f32_dpp v14, v61, v61 row_half_mirror row_mask:0xf bank_mask:0x5 bound_ctrl:1
	v_fmac_f32_e32 v11, v25, v56
	v_mul_f32_e32 v118, v42, v10
	v_fmac_f32_e32 v12, v26, v56
	v_fmac_f32_e32 v118, v43, v11
	v_fmac_f32_e32 v13, v27, v56
	v_fmac_f32_e32 v118, v44, v12
	v_fmac_f32_e32 v118, v45, v13
	ds_read_b128 v[20:23], v0 offset:512
	ds_read_b128 v[38:41], v0 offset:1536
	ds_read_b128 v[62:65], v0 offset:2560
	ds_read_b32 v54, v1 offset:3200
	ds_write_b128 v2, v[110:113] offset:3328
	v_lshlrev_b32_e32 v114, 16, v88
	v_and_b32_e32 v115, 0xffff0000, v88
	v_lshlrev_b32_e32 v116, 16, v89
	v_and_b32_e32 v117, 0xffff0000, v89
	s_waitcnt lgkmcnt(9)
	v_mul_f32_e32 v10, v70, v10
	v_add_f32_dpp v118, v118, v118 quad_perm:[1,0,3,2] row_mask:0xf bank_mask:0xf bound_ctrl:1
	v_mul_f32_e32 v11, v71, v11
	v_mul_f32_e32 v12, v72, v12
	v_add_f32_dpp v118, v118, v118 quad_perm:[2,3,0,1] row_mask:0xf bank_mask:0xf bound_ctrl:1
	v_mul_f32_e32 v13, v73, v13
	v_fmac_f32_e32 v10, v28, v58
	v_add_f32_dpp v15, v118, v118 row_half_mirror row_mask:0xf bank_mask:0x5 bound_ctrl:1
	v_fmac_f32_e32 v11, v29, v58
	v_mul_f32_e32 v61, v46, v10
	v_fmac_f32_e32 v12, v30, v58
	v_fmac_f32_e32 v61, v47, v11
	v_fmac_f32_e32 v13, v31, v58
	v_fmac_f32_e32 v61, v48, v12
	v_fmac_f32_e32 v61, v49, v13
	ds_read_b128 v[24:27], v0 offset:640
	ds_read_b128 v[42:45], v0 offset:1664
	ds_read_b128 v[66:69], v0 offset:2688
	ds_read_b32 v56, v1 offset:3232
	ds_write_b128 v2, v[114:117] offset:3344
	s_waitcnt vmcnt(10)
	ds_write_b128 v119, v[90:93] offset:5376
	s_waitcnt vmcnt(9)
	v_lshlrev_b32_e32 v55, 16, v55
	s_waitcnt lgkmcnt(11)
	v_mul_f32_e32 v10, v74, v10
	v_add_f32_dpp v61, v61, v61 quad_perm:[1,0,3,2] row_mask:0xf bank_mask:0xf bound_ctrl:1
	v_mul_f32_e32 v11, v75, v11
	v_mul_f32_e32 v12, v76, v12
	v_add_f32_dpp v61, v61, v61 quad_perm:[2,3,0,1] row_mask:0xf bank_mask:0xf bound_ctrl:1
	v_mul_f32_e32 v13, v77, v13
	v_fmac_f32_e32 v10, v32, v60
	v_add_f32_dpp v16, v61, v61 row_half_mirror row_mask:0xf bank_mask:0x5 bound_ctrl:1
	v_fmac_f32_e32 v11, v33, v60
	v_mul_f32_e32 v118, v50, v10
	v_fmac_f32_e32 v12, v34, v60
	v_fmac_f32_e32 v118, v51, v11
	v_fmac_f32_e32 v13, v35, v60
	v_fmac_f32_e32 v118, v52, v12
	v_fmac_f32_e32 v118, v53, v13
	ds_read_b128 v[28:31], v0 offset:768
	ds_read_b128 v[46:49], v0 offset:1792
	ds_read_b128 v[70:73], v0 offset:2816
	ds_read_b32 v58, v1 offset:3264
	s_nop 0
	ds_write_b32 v4, v55 offset:6400
	s_waitcnt lgkmcnt(12)
	v_mul_f32_e32 v10, v62, v10
	v_add_f32_dpp v118, v118, v118 quad_perm:[1,0,3,2] row_mask:0xf bank_mask:0xf bound_ctrl:1
	v_mul_f32_e32 v11, v63, v11
	v_mul_f32_e32 v12, v64, v12
	v_add_f32_dpp v118, v118, v118 quad_perm:[2,3,0,1] row_mask:0xf bank_mask:0xf bound_ctrl:1
	v_mul_f32_e32 v13, v65, v13
	v_fmac_f32_e32 v10, v20, v54
	v_add_f32_dpp v17, v118, v118 row_half_mirror row_mask:0xf bank_mask:0x5 bound_ctrl:1
	v_fmac_f32_e32 v11, v21, v54
	v_mul_f32_e32 v61, v38, v10
	v_fmac_f32_e32 v12, v22, v54
	v_fmac_f32_e32 v61, v39, v11
	v_fmac_f32_e32 v13, v23, v54
	v_fmac_f32_e32 v61, v40, v12
	v_fmac_f32_e32 v61, v41, v13
	ds_read_b128 v[32:35], v0 offset:896
	ds_read_b128 v[50:53], v0 offset:1920
	ds_read_b128 v[74:77], v0 offset:2944
	ds_read_b32 v60, v1 offset:3296
	global_load_dwordx4 v[86:89], v5, s[94:95]
	global_load_dwordx4 v[90:93], v8, s[94:95]
	global_load_ushort v55, v6, s[94:95]
	v_add_u32_e32 v5, v5, v9
	v_add_u32_e32 v8, 0x3180, v8
	v_add_u32_e32 v6, 0x10000, v6
	s_waitcnt lgkmcnt(11)
	v_mul_f32_e32 v10, v66, v10
	v_add_f32_dpp v61, v61, v61 quad_perm:[1,0,3,2] row_mask:0xf bank_mask:0xf bound_ctrl:1
	v_mul_f32_e32 v11, v67, v11
	v_mul_f32_e32 v12, v68, v12
	v_add_f32_dpp v61, v61, v61 quad_perm:[2,3,0,1] row_mask:0xf bank_mask:0xf bound_ctrl:1
	v_mul_f32_e32 v13, v69, v13
	v_fmac_f32_e32 v10, v24, v56
	v_add_f32_dpp v14, v61, v61 row_half_mirror row_mask:0xf bank_mask:0xa bound_ctrl:1
	v_fmac_f32_e32 v11, v25, v56
	v_mul_f32_e32 v118, v42, v10
	v_fmac_f32_e32 v12, v26, v56
	v_fmac_f32_e32 v118, v43, v11
	v_fmac_f32_e32 v13, v27, v56
	v_fmac_f32_e32 v118, v44, v12
	v_fmac_f32_e32 v118, v45, v13
	ds_read_b128 v[20:23], v0 offset:3328
	ds_read_b128 v[38:41], v0 offset:4352
	ds_read_b128 v[62:65], v0 offset:5376
	ds_read_b32 v54, v1 offset:6400
	s_waitcnt lgkmcnt(9)
	v_mul_f32_e32 v10, v70, v10
	v_add_f32_dpp v118, v118, v118 quad_perm:[1,0,3,2] row_mask:0xf bank_mask:0xf bound_ctrl:1
	v_mul_f32_e32 v11, v71, v11
	v_mul_f32_e32 v12, v72, v12
	v_add_f32_dpp v118, v118, v118 quad_perm:[2,3,0,1] row_mask:0xf bank_mask:0xf bound_ctrl:1
	v_mul_f32_e32 v13, v73, v13
	v_fmac_f32_e32 v10, v28, v58
	v_add_f32_dpp v15, v118, v118 row_half_mirror row_mask:0xf bank_mask:0xa bound_ctrl:1
	v_fmac_f32_e32 v11, v29, v58
	v_mul_f32_e32 v61, v46, v10
	v_fmac_f32_e32 v12, v30, v58
	v_fmac_f32_e32 v61, v47, v11
	v_fmac_f32_e32 v13, v31, v58
	v_fmac_f32_e32 v61, v48, v12
	v_fmac_f32_e32 v61, v49, v13
	ds_read_b128 v[24:27], v0 offset:3456
	ds_read_b128 v[42:45], v0 offset:4480
	ds_read_b128 v[66:69], v0 offset:5504
	ds_read_b32 v56, v1 offset:6432
	s_waitcnt lgkmcnt(8)
	v_mul_f32_e32 v10, v74, v10
	v_add_f32_dpp v61, v61, v61 quad_perm:[1,0,3,2] row_mask:0xf bank_mask:0xf bound_ctrl:1
	v_mul_f32_e32 v11, v75, v11
	v_mul_f32_e32 v12, v76, v12
	v_add_f32_dpp v61, v61, v61 quad_perm:[2,3,0,1] row_mask:0xf bank_mask:0xf bound_ctrl:1
	v_mul_f32_e32 v13, v77, v13
	v_fmac_f32_e32 v10, v32, v60
	v_add_f32_dpp v16, v61, v61 row_half_mirror row_mask:0xf bank_mask:0xa bound_ctrl:1
	v_fmac_f32_e32 v11, v33, v60
	v_mul_f32_e32 v118, v50, v10
	v_fmac_f32_e32 v12, v34, v60
	v_fmac_f32_e32 v118, v51, v11
	v_fmac_f32_e32 v13, v35, v60
	v_fmac_f32_e32 v118, v52, v12
	v_fmac_f32_e32 v118, v53, v13
	ds_read_b128 v[28:31], v0 offset:3584
	ds_read_b128 v[46:49], v0 offset:4608
	ds_read_b128 v[70:73], v0 offset:5632
	ds_read_b32 v58, v1 offset:6464
	s_nop 1
	v_add_f32_dpp v118, v118, v118 quad_perm:[1,0,3,2] row_mask:0xf bank_mask:0xf bound_ctrl:1
	s_nop 1
	v_add_f32_dpp v118, v118, v118 quad_perm:[2,3,0,1] row_mask:0xf bank_mask:0xf bound_ctrl:1
	s_nop 1
	v_add_f32_dpp v17, v118, v118 row_half_mirror row_mask:0xf bank_mask:0xa bound_ctrl:1
	v_mov_b32_e32 v118, 0
	v_cndmask_b32_e64 v18, v14, v15, s[6:7]
	v_cndmask_b32_e64 v18, v18, v16, s[8:9]
	v_cndmask_b32_e64 v18, v18, v17, s[10:11]
	v_cvt_pk_bf16_f32 v19, v18, v18
	ds_write_b16 v121, v19 offset:6656
	s_waitcnt lgkmcnt(9)
	v_mul_f32_e32 v10, v62, v10
	v_add_f32_dpp v118, v118, v118 quad_perm:[1,0,3,2] row_mask:0xf bank_mask:0xf bound_ctrl:1
	v_mul_f32_e32 v11, v63, v11
	v_mul_f32_e32 v12, v64, v12
	v_add_f32_dpp v118, v118, v118 quad_perm:[2,3,0,1] row_mask:0xf bank_mask:0xf bound_ctrl:1
	v_mul_f32_e32 v13, v65, v13
	v_fmac_f32_e32 v10, v20, v54
	v_add_f32_dpp v17, v118, v118 row_half_mirror row_mask:0xf bank_mask:0xa bound_ctrl:1
	v_fmac_f32_e32 v11, v21, v54
	v_mul_f32_e32 v61, v38, v10
	v_fmac_f32_e32 v12, v22, v54
	v_fmac_f32_e32 v61, v39, v11
	v_fmac_f32_e32 v13, v23, v54
	v_fmac_f32_e32 v61, v40, v12
	v_fmac_f32_e32 v61, v41, v13
	ds_read_b128 v[32:35], v0 offset:3712
	ds_read_b128 v[50:53], v0 offset:4736
	ds_read_b128 v[74:77], v0 offset:5760
	ds_read_b32 v60, v1 offset:6496
	s_waitcnt vmcnt(11)
	v_lshlrev_b32_e32 v110, 16, v94
	v_and_b32_e32 v111, 0xffff0000, v94
	v_lshlrev_b32_e32 v112, 16, v95
	v_and_b32_e32 v113, 0xffff0000, v95
	s_waitcnt lgkmcnt(9)
	v_mul_f32_e32 v10, v66, v10
	v_add_f32_dpp v61, v61, v61 quad_perm:[1,0,3,2] row_mask:0xf bank_mask:0xf bound_ctrl:1
	v_mul_f32_e32 v11, v67, v11
	v_mul_f32_e32 v12, v68, v12
	v_add_f32_dpp v61, v61, v61 quad_perm:[2,3,0,1] row_mask:0xf bank_mask:0xf bound_ctrl:1
	v_mul_f32_e32 v13, v69, v13
	v_fmac_f32_e32 v10, v24, v56
	v_add_f32_dpp v14, v61, v61 row_half_mirror row_mask:0xf bank_mask:0x5 bound_ctrl:1
	v_fmac_f32_e32 v11, v25, v56
	v_mul_f32_e32 v118, v42, v10
	v_fmac_f32_e32 v12, v26, v56
	v_fmac_f32_e32 v118, v43, v11
	v_fmac_f32_e32 v13, v27, v56
	v_fmac_f32_e32 v118, v44, v12
	v_fmac_f32_e32 v118, v45, v13
	ds_read_b128 v[20:23], v0 offset:3840
	ds_read_b128 v[38:41], v0 offset:4864
	ds_read_b128 v[62:65], v0 offset:5888
	ds_read_b32 v54, v1 offset:6528
	ds_write_b128 v2, v[110:113] offset:0
	v_lshlrev_b32_e32 v114, 16, v96
	v_and_b32_e32 v115, 0xffff0000, v96
	v_lshlrev_b32_e32 v116, 16, v97
	v_and_b32_e32 v117, 0xffff0000, v97
	s_waitcnt lgkmcnt(10)
	v_mul_f32_e32 v10, v70, v10
	v_add_f32_dpp v118, v118, v118 quad_perm:[1,0,3,2] row_mask:0xf bank_mask:0xf bound_ctrl:1
	v_mul_f32_e32 v11, v71, v11
	v_mul_f32_e32 v12, v72, v12
	v_add_f32_dpp v118, v118, v118 quad_perm:[2,3,0,1] row_mask:0xf bank_mask:0xf bound_ctrl:1
	v_mul_f32_e32 v13, v73, v13
	v_fmac_f32_e32 v10, v28, v58
	v_add_f32_dpp v15, v118, v118 row_half_mirror row_mask:0xf bank_mask:0x5 bound_ctrl:1
	v_fmac_f32_e32 v11, v29, v58
	v_mul_f32_e32 v61, v46, v10
	v_fmac_f32_e32 v12, v30, v58
	v_fmac_f32_e32 v61, v47, v11
	v_fmac_f32_e32 v13, v31, v58
	v_fmac_f32_e32 v61, v48, v12
	v_fmac_f32_e32 v61, v49, v13
	ds_read_b128 v[24:27], v0 offset:3968
	ds_read_b128 v[42:45], v0 offset:4992
	ds_read_b128 v[66:69], v0 offset:6016
	ds_read_b32 v56, v1 offset:6560
	ds_write_b128 v2, v[114:117] offset:16
	s_waitcnt vmcnt(10)
	ds_write_b128 v119, v[98:101] offset:2048
	s_waitcnt vmcnt(9)
	v_lshlrev_b32_e32 v57, 16, v57
	s_waitcnt lgkmcnt(11)
	v_mul_f32_e32 v10, v74, v10
	v_add_f32_dpp v61, v61, v61 quad_perm:[1,0,3,2] row_mask:0xf bank_mask:0xf bound_ctrl:1
	v_mul_f32_e32 v11, v75, v11
	v_mul_f32_e32 v12, v76, v12
	v_add_f32_dpp v61, v61, v61 quad_perm:[2,3,0,1] row_mask:0xf bank_mask:0xf bound_ctrl:1
	v_mul_f32_e32 v13, v77, v13
	v_fmac_f32_e32 v10, v32, v60
	v_add_f32_dpp v16, v61, v61 row_half_mirror row_mask:0xf bank_mask:0x5 bound_ctrl:1
	v_fmac_f32_e32 v11, v33, v60
	v_mul_f32_e32 v118, v50, v10
	v_fmac_f32_e32 v12, v34, v60
	v_fmac_f32_e32 v118, v51, v11
	v_fmac_f32_e32 v13, v35, v60
	v_fmac_f32_e32 v118, v52, v12
	v_fmac_f32_e32 v118, v53, v13
	ds_read_b128 v[28:31], v0 offset:4096
	ds_read_b128 v[46:49], v0 offset:5120
	ds_read_b128 v[70:73], v0 offset:6144
	ds_read_b32 v58, v1 offset:6592
	s_nop 0
	ds_write_b32 v4, v57 offset:3072
	s_waitcnt lgkmcnt(12)
	v_mul_f32_e32 v10, v62, v10
	v_add_f32_dpp v118, v118, v118 quad_perm:[1,0,3,2] row_mask:0xf bank_mask:0xf bound_ctrl:1
	v_mul_f32_e32 v11, v63, v11
	v_mul_f32_e32 v12, v64, v12
	v_add_f32_dpp v118, v118, v118 quad_perm:[2,3,0,1] row_mask:0xf bank_mask:0xf bound_ctrl:1
	v_mul_f32_e32 v13, v65, v13
	v_fmac_f32_e32 v10, v20, v54
	v_add_f32_dpp v17, v118, v118 row_half_mirror row_mask:0xf bank_mask:0x5 bound_ctrl:1
	v_fmac_f32_e32 v11, v21, v54
	v_mul_f32_e32 v61, v38, v10
	v_fmac_f32_e32 v12, v22, v54
	v_fmac_f32_e32 v61, v39, v11
	v_fmac_f32_e32 v13, v23, v54
	v_fmac_f32_e32 v61, v40, v12
	v_fmac_f32_e32 v61, v41, v13
	ds_read_b128 v[32:35], v0 offset:4224
	ds_read_b128 v[50:53], v0 offset:5248
	ds_read_b128 v[74:77], v0 offset:6272
	ds_read_b32 v60, v1 offset:6624
	global_load_dwordx4 v[94:97], v5, s[94:95]
	global_load_dwordx4 v[98:101], v8, s[94:95]
	global_load_ushort v57, v6, s[94:95]
	v_add_u32_e32 v5, v5, v9
	v_add_u32_e32 v8, 0x3180, v8
	v_add_u32_e32 v6, 0x10000, v6
	s_waitcnt lgkmcnt(11)
	v_mul_f32_e32 v10, v66, v10
	v_add_f32_dpp v61, v61, v61 quad_perm:[1,0,3,2] row_mask:0xf bank_mask:0xf bound_ctrl:1
	v_mul_f32_e32 v11, v67, v11
	v_mul_f32_e32 v12, v68, v12
	v_add_f32_dpp v61, v61, v61 quad_perm:[2,3,0,1] row_mask:0xf bank_mask:0xf bound_ctrl:1
	v_mul_f32_e32 v13, v69, v13
	v_fmac_f32_e32 v10, v24, v56
	v_add_f32_dpp v14, v61, v61 row_half_mirror row_mask:0xf bank_mask:0xa bound_ctrl:1
	v_fmac_f32_e32 v11, v25, v56
	v_mul_f32_e32 v118, v42, v10
	v_fmac_f32_e32 v12, v26, v56
	v_fmac_f32_e32 v118, v43, v11
	v_fmac_f32_e32 v13, v27, v56
	v_fmac_f32_e32 v118, v44, v12
	v_fmac_f32_e32 v118, v45, v13
	ds_read_b128 v[20:23], v0 offset:0
	ds_read_b128 v[38:41], v0 offset:1024
	ds_read_b128 v[62:65], v0 offset:2048
	ds_read_b32 v54, v1 offset:3072
	s_waitcnt lgkmcnt(9)
	v_mul_f32_e32 v10, v70, v10
	v_add_f32_dpp v118, v118, v118 quad_perm:[1,0,3,2] row_mask:0xf bank_mask:0xf bound_ctrl:1
	v_mul_f32_e32 v11, v71, v11
	v_mul_f32_e32 v12, v72, v12
	v_add_f32_dpp v118, v118, v118 quad_perm:[2,3,0,1] row_mask:0xf bank_mask:0xf bound_ctrl:1
	v_mul_f32_e32 v13, v73, v13
	v_fmac_f32_e32 v10, v28, v58
	v_add_f32_dpp v15, v118, v118 row_half_mirror row_mask:0xf bank_mask:0xa bound_ctrl:1
	v_fmac_f32_e32 v11, v29, v58
	v_mul_f32_e32 v61, v46, v10
	v_fmac_f32_e32 v12, v30, v58
	v_fmac_f32_e32 v61, v47, v11
	v_fmac_f32_e32 v13, v31, v58
	v_fmac_f32_e32 v61, v48, v12
	v_fmac_f32_e32 v61, v49, v13
	ds_read_b128 v[24:27], v0 offset:128
	ds_read_b128 v[42:45], v0 offset:1152
	ds_read_b128 v[66:69], v0 offset:2176
	ds_read_b32 v56, v1 offset:3104
	s_waitcnt lgkmcnt(8)
	v_mul_f32_e32 v10, v74, v10
	v_add_f32_dpp v61, v61, v61 quad_perm:[1,0,3,2] row_mask:0xf bank_mask:0xf bound_ctrl:1
	v_mul_f32_e32 v11, v75, v11
	v_mul_f32_e32 v12, v76, v12
	v_add_f32_dpp v61, v61, v61 quad_perm:[2,3,0,1] row_mask:0xf bank_mask:0xf bound_ctrl:1
	v_mul_f32_e32 v13, v77, v13
	v_fmac_f32_e32 v10, v32, v60
	v_add_f32_dpp v16, v61, v61 row_half_mirror row_mask:0xf bank_mask:0xa bound_ctrl:1
	v_fmac_f32_e32 v11, v33, v60
	v_mul_f32_e32 v118, v50, v10
	v_fmac_f32_e32 v12, v34, v60
	v_fmac_f32_e32 v118, v51, v11
	v_fmac_f32_e32 v13, v35, v60
	v_fmac_f32_e32 v118, v52, v12
	v_fmac_f32_e32 v118, v53, v13
	ds_read_b128 v[28:31], v0 offset:256
	ds_read_b128 v[46:49], v0 offset:1280
	ds_read_b128 v[70:73], v0 offset:2304
	ds_read_b32 v58, v1 offset:3136
	s_nop 1
	v_add_f32_dpp v118, v118, v118 quad_perm:[1,0,3,2] row_mask:0xf bank_mask:0xf bound_ctrl:1
	s_nop 1
	v_add_f32_dpp v118, v118, v118 quad_perm:[2,3,0,1] row_mask:0xf bank_mask:0xf bound_ctrl:1
	s_nop 1
	v_add_f32_dpp v17, v118, v118 row_half_mirror row_mask:0xf bank_mask:0xa bound_ctrl:1
	v_mov_b32_e32 v118, 0
	v_cndmask_b32_e64 v18, v14, v15, s[6:7]
	v_cndmask_b32_e64 v18, v18, v16, s[8:9]
	v_cndmask_b32_e64 v18, v18, v17, s[10:11]
	v_cvt_pk_bf16_f32 v19, v18, v18
	ds_write_b16 v121, v19 offset:6784
	s_waitcnt lgkmcnt(9)
	v_mul_f32_e32 v10, v62, v10
	v_add_f32_dpp v118, v118, v118 quad_perm:[1,0,3,2] row_mask:0xf bank_mask:0xf bound_ctrl:1
	v_mul_f32_e32 v11, v63, v11
	v_mul_f32_e32 v12, v64, v12
	v_add_f32_dpp v118, v118, v118 quad_perm:[2,3,0,1] row_mask:0xf bank_mask:0xf bound_ctrl:1
	v_mul_f32_e32 v13, v65, v13
	v_fmac_f32_e32 v10, v20, v54
	v_add_f32_dpp v17, v118, v118 row_half_mirror row_mask:0xf bank_mask:0xa bound_ctrl:1
	v_fmac_f32_e32 v11, v21, v54
	v_mul_f32_e32 v61, v38, v10
	v_fmac_f32_e32 v12, v22, v54
	v_fmac_f32_e32 v61, v39, v11
	v_fmac_f32_e32 v13, v23, v54
	v_fmac_f32_e32 v61, v40, v12
	v_fmac_f32_e32 v61, v41, v13
	ds_read_b128 v[32:35], v0 offset:384
	ds_read_b128 v[50:53], v0 offset:1408
	ds_read_b128 v[74:77], v0 offset:2432
	ds_read_b32 v60, v1 offset:3168
	s_waitcnt vmcnt(11)
	v_lshlrev_b32_e32 v110, 16, v102
	v_and_b32_e32 v111, 0xffff0000, v102
	v_lshlrev_b32_e32 v112, 16, v103
	v_and_b32_e32 v113, 0xffff0000, v103
	s_waitcnt lgkmcnt(9)
	v_mul_f32_e32 v10, v66, v10
	v_add_f32_dpp v61, v61, v61 quad_perm:[1,0,3,2] row_mask:0xf bank_mask:0xf bound_ctrl:1
	v_mul_f32_e32 v11, v67, v11
	v_mul_f32_e32 v12, v68, v12
	v_add_f32_dpp v61, v61, v61 quad_perm:[2,3,0,1] row_mask:0xf bank_mask:0xf bound_ctrl:1
	v_mul_f32_e32 v13, v69, v13
	v_fmac_f32_e32 v10, v24, v56
	v_add_f32_dpp v14, v61, v61 row_half_mirror row_mask:0xf bank_mask:0x5 bound_ctrl:1
	v_fmac_f32_e32 v11, v25, v56
	v_mul_f32_e32 v118, v42, v10
	v_fmac_f32_e32 v12, v26, v56
	v_fmac_f32_e32 v118, v43, v11
	v_fmac_f32_e32 v13, v27, v56
	v_fmac_f32_e32 v118, v44, v12
	v_fmac_f32_e32 v118, v45, v13
	ds_read_b128 v[20:23], v0 offset:512
	ds_read_b128 v[38:41], v0 offset:1536
	ds_read_b128 v[62:65], v0 offset:2560
	ds_read_b32 v54, v1 offset:3200
	ds_write_b128 v2, v[110:113] offset:3328
	v_lshlrev_b32_e32 v114, 16, v104
	v_and_b32_e32 v115, 0xffff0000, v104
	v_lshlrev_b32_e32 v116, 16, v105
	v_and_b32_e32 v117, 0xffff0000, v105
	s_waitcnt lgkmcnt(10)
	v_mul_f32_e32 v10, v70, v10
	v_add_f32_dpp v118, v118, v118 quad_perm:[1,0,3,2] row_mask:0xf bank_mask:0xf bound_ctrl:1
	v_mul_f32_e32 v11, v71, v11
	v_mul_f32_e32 v12, v72, v12
	v_add_f32_dpp v118, v118, v118 quad_perm:[2,3,0,1] row_mask:0xf bank_mask:0xf bound_ctrl:1
	v_mul_f32_e32 v13, v73, v13
	v_fmac_f32_e32 v10, v28, v58
	v_add_f32_dpp v15, v118, v118 row_half_mirror row_mask:0xf bank_mask:0x5 bound_ctrl:1
	v_fmac_f32_e32 v11, v29, v58
	v_mul_f32_e32 v61, v46, v10
	v_fmac_f32_e32 v12, v30, v58
	v_fmac_f32_e32 v61, v47, v11
	v_fmac_f32_e32 v13, v31, v58
	v_fmac_f32_e32 v61, v48, v12
	v_fmac_f32_e32 v61, v49, v13
	ds_read_b128 v[24:27], v0 offset:640
	ds_read_b128 v[42:45], v0 offset:1664
	ds_read_b128 v[66:69], v0 offset:2688
	ds_read_b32 v56, v1 offset:3232
	ds_write_b128 v2, v[114:117] offset:3344
	s_waitcnt vmcnt(10)
	ds_write_b128 v119, v[106:109] offset:5376
	s_waitcnt vmcnt(9)
	v_lshlrev_b32_e32 v59, 16, v59
	s_waitcnt lgkmcnt(11)
	v_mul_f32_e32 v10, v74, v10
	v_add_f32_dpp v61, v61, v61 quad_perm:[1,0,3,2] row_mask:0xf bank_mask:0xf bound_ctrl:1
	v_mul_f32_e32 v11, v75, v11
	v_mul_f32_e32 v12, v76, v12
	v_add_f32_dpp v61, v61, v61 quad_perm:[2,3,0,1] row_mask:0xf bank_mask:0xf bound_ctrl:1
	v_mul_f32_e32 v13, v77, v13
	v_fmac_f32_e32 v10, v32, v60
	v_add_f32_dpp v16, v61, v61 row_half_mirror row_mask:0xf bank_mask:0x5 bound_ctrl:1
	v_fmac_f32_e32 v11, v33, v60
	v_mul_f32_e32 v118, v50, v10
	v_fmac_f32_e32 v12, v34, v60
	v_fmac_f32_e32 v118, v51, v11
	v_fmac_f32_e32 v13, v35, v60
	v_fmac_f32_e32 v118, v52, v12
	v_fmac_f32_e32 v118, v53, v13
	ds_read_b128 v[28:31], v0 offset:768
	ds_read_b128 v[46:49], v0 offset:1792
	ds_read_b128 v[70:73], v0 offset:2816
	ds_read_b32 v58, v1 offset:3264
	s_nop 0
	ds_write_b32 v4, v59 offset:6400
	s_waitcnt lgkmcnt(12)
	v_mul_f32_e32 v10, v62, v10
	v_add_f32_dpp v118, v118, v118 quad_perm:[1,0,3,2] row_mask:0xf bank_mask:0xf bound_ctrl:1
	v_mul_f32_e32 v11, v63, v11
	v_mul_f32_e32 v12, v64, v12
	v_add_f32_dpp v118, v118, v118 quad_perm:[2,3,0,1] row_mask:0xf bank_mask:0xf bound_ctrl:1
	v_mul_f32_e32 v13, v65, v13
	v_fmac_f32_e32 v10, v20, v54
	v_add_f32_dpp v17, v118, v118 row_half_mirror row_mask:0xf bank_mask:0x5 bound_ctrl:1
	v_fmac_f32_e32 v11, v21, v54
	v_mul_f32_e32 v61, v38, v10
	v_fmac_f32_e32 v12, v22, v54
	v_fmac_f32_e32 v61, v39, v11
	v_fmac_f32_e32 v13, v23, v54
	v_fmac_f32_e32 v61, v40, v12
	v_fmac_f32_e32 v61, v41, v13
	ds_read_b128 v[32:35], v0 offset:896
	ds_read_b128 v[50:53], v0 offset:1920
	ds_read_b128 v[74:77], v0 offset:2944
	ds_read_b32 v60, v1 offset:3296
	global_load_dwordx4 v[102:105], v5, s[94:95]
	global_load_dwordx4 v[106:109], v8, s[94:95]
	global_load_ushort v59, v6, s[94:95]
	v_add_u32_e32 v5, v5, v9
	v_add_u32_e32 v8, 0x3180, v8
	v_add_u32_e32 v6, 0x10000, v6
	s_waitcnt lgkmcnt(11)
	v_mul_f32_e32 v10, v66, v10
	v_add_f32_dpp v61, v61, v61 quad_perm:[1,0,3,2] row_mask:0xf bank_mask:0xf bound_ctrl:1
	v_mul_f32_e32 v11, v67, v11
	v_mul_f32_e32 v12, v68, v12
	v_add_f32_dpp v61, v61, v61 quad_perm:[2,3,0,1] row_mask:0xf bank_mask:0xf bound_ctrl:1
	v_mul_f32_e32 v13, v69, v13
	v_fmac_f32_e32 v10, v24, v56
	v_add_f32_dpp v14, v61, v61 row_half_mirror row_mask:0xf bank_mask:0xa bound_ctrl:1
	v_fmac_f32_e32 v11, v25, v56
	v_mul_f32_e32 v118, v42, v10
	v_fmac_f32_e32 v12, v26, v56
	v_fmac_f32_e32 v118, v43, v11
	v_fmac_f32_e32 v13, v27, v56
	v_fmac_f32_e32 v118, v44, v12
	v_fmac_f32_e32 v118, v45, v13
	ds_read_b128 v[20:23], v0 offset:3328
	ds_read_b128 v[38:41], v0 offset:4352
	ds_read_b128 v[62:65], v0 offset:5376
	ds_read_b32 v54, v1 offset:6400
	s_waitcnt lgkmcnt(9)
	v_mul_f32_e32 v10, v70, v10
	v_add_f32_dpp v118, v118, v118 quad_perm:[1,0,3,2] row_mask:0xf bank_mask:0xf bound_ctrl:1
	v_mul_f32_e32 v11, v71, v11
	v_mul_f32_e32 v12, v72, v12
	v_add_f32_dpp v118, v118, v118 quad_perm:[2,3,0,1] row_mask:0xf bank_mask:0xf bound_ctrl:1
	v_mul_f32_e32 v13, v73, v13
	v_fmac_f32_e32 v10, v28, v58
	v_add_f32_dpp v15, v118, v118 row_half_mirror row_mask:0xf bank_mask:0xa bound_ctrl:1
	v_fmac_f32_e32 v11, v29, v58
	v_mul_f32_e32 v61, v46, v10
	v_fmac_f32_e32 v12, v30, v58
	v_fmac_f32_e32 v61, v47, v11
	v_fmac_f32_e32 v13, v31, v58
	v_fmac_f32_e32 v61, v48, v12
	v_fmac_f32_e32 v61, v49, v13
	ds_read_b128 v[24:27], v0 offset:3456
	ds_read_b128 v[42:45], v0 offset:4480
	ds_read_b128 v[66:69], v0 offset:5504
	ds_read_b32 v56, v1 offset:6432
	s_waitcnt lgkmcnt(8)
	v_mul_f32_e32 v10, v74, v10
	v_add_f32_dpp v61, v61, v61 quad_perm:[1,0,3,2] row_mask:0xf bank_mask:0xf bound_ctrl:1
	v_mul_f32_e32 v11, v75, v11
	v_mul_f32_e32 v12, v76, v12
	v_add_f32_dpp v61, v61, v61 quad_perm:[2,3,0,1] row_mask:0xf bank_mask:0xf bound_ctrl:1
	v_mul_f32_e32 v13, v77, v13
	v_fmac_f32_e32 v10, v32, v60
	v_add_f32_dpp v16, v61, v61 row_half_mirror row_mask:0xf bank_mask:0xa bound_ctrl:1
	v_fmac_f32_e32 v11, v33, v60
	v_mul_f32_e32 v118, v50, v10
	v_fmac_f32_e32 v12, v34, v60
	v_fmac_f32_e32 v118, v51, v11
	v_fmac_f32_e32 v13, v35, v60
	v_fmac_f32_e32 v118, v52, v12
	v_fmac_f32_e32 v118, v53, v13
	ds_read_b128 v[28:31], v0 offset:3584
	ds_read_b128 v[46:49], v0 offset:4608
	ds_read_b128 v[70:73], v0 offset:5632
	ds_read_b32 v58, v1 offset:6464
	s_nop 1
	v_add_f32_dpp v118, v118, v118 quad_perm:[1,0,3,2] row_mask:0xf bank_mask:0xf bound_ctrl:1
	s_nop 1
	v_add_f32_dpp v118, v118, v118 quad_perm:[2,3,0,1] row_mask:0xf bank_mask:0xf bound_ctrl:1
	s_nop 1
	v_add_f32_dpp v17, v118, v118 row_half_mirror row_mask:0xf bank_mask:0xa bound_ctrl:1
	v_mov_b32_e32 v118, 0
	v_cndmask_b32_e64 v18, v14, v15, s[6:7]
	v_cndmask_b32_e64 v18, v18, v16, s[8:9]
	v_cndmask_b32_e64 v18, v18, v17, s[10:11]
	v_cvt_pk_bf16_f32 v19, v18, v18
	ds_write_b16 v121, v19 offset:6912
	s_waitcnt lgkmcnt(9)
	v_mul_f32_e32 v10, v62, v10
	v_add_f32_dpp v118, v118, v118 quad_perm:[1,0,3,2] row_mask:0xf bank_mask:0xf bound_ctrl:1
	v_mul_f32_e32 v11, v63, v11
	v_mul_f32_e32 v12, v64, v12
	v_add_f32_dpp v118, v118, v118 quad_perm:[2,3,0,1] row_mask:0xf bank_mask:0xf bound_ctrl:1
	v_mul_f32_e32 v13, v65, v13
	v_fmac_f32_e32 v10, v20, v54
	v_add_f32_dpp v17, v118, v118 row_half_mirror row_mask:0xf bank_mask:0xa bound_ctrl:1
	v_fmac_f32_e32 v11, v21, v54
	v_mul_f32_e32 v61, v38, v10
	v_fmac_f32_e32 v12, v22, v54
	v_fmac_f32_e32 v61, v39, v11
	v_fmac_f32_e32 v13, v23, v54
	v_fmac_f32_e32 v61, v40, v12
	v_fmac_f32_e32 v61, v41, v13
	ds_read_b128 v[32:35], v0 offset:3712
	ds_read_b128 v[50:53], v0 offset:4736
	ds_read_b128 v[74:77], v0 offset:5760
	ds_read_b32 v60, v1 offset:6496
	s_waitcnt vmcnt(11)
	v_lshlrev_b32_e32 v110, 16, v78
	v_and_b32_e32 v111, 0xffff0000, v78
	v_lshlrev_b32_e32 v112, 16, v79
	v_and_b32_e32 v113, 0xffff0000, v79
	s_waitcnt lgkmcnt(9)
	v_mul_f32_e32 v10, v66, v10
	v_add_f32_dpp v61, v61, v61 quad_perm:[1,0,3,2] row_mask:0xf bank_mask:0xf bound_ctrl:1
	v_mul_f32_e32 v11, v67, v11
	v_mul_f32_e32 v12, v68, v12
	v_add_f32_dpp v61, v61, v61 quad_perm:[2,3,0,1] row_mask:0xf bank_mask:0xf bound_ctrl:1
	v_mul_f32_e32 v13, v69, v13
	v_fmac_f32_e32 v10, v24, v56
	v_add_f32_dpp v14, v61, v61 row_half_mirror row_mask:0xf bank_mask:0x5 bound_ctrl:1
	v_fmac_f32_e32 v11, v25, v56
	v_mul_f32_e32 v118, v42, v10
	v_fmac_f32_e32 v12, v26, v56
	v_fmac_f32_e32 v118, v43, v11
	v_fmac_f32_e32 v13, v27, v56
	v_fmac_f32_e32 v118, v44, v12
	v_fmac_f32_e32 v118, v45, v13
	ds_read_b128 v[20:23], v0 offset:3840
	ds_read_b128 v[38:41], v0 offset:4864
	ds_read_b128 v[62:65], v0 offset:5888
	ds_read_b32 v54, v1 offset:6528
	ds_write_b128 v2, v[110:113] offset:0
	v_lshlrev_b32_e32 v114, 16, v80
	v_and_b32_e32 v115, 0xffff0000, v80
	v_lshlrev_b32_e32 v116, 16, v81
	v_and_b32_e32 v117, 0xffff0000, v81
	s_waitcnt lgkmcnt(10)
	v_mul_f32_e32 v10, v70, v10
	v_add_f32_dpp v118, v118, v118 quad_perm:[1,0,3,2] row_mask:0xf bank_mask:0xf bound_ctrl:1
	v_mul_f32_e32 v11, v71, v11
	v_mul_f32_e32 v12, v72, v12
	v_add_f32_dpp v118, v118, v118 quad_perm:[2,3,0,1] row_mask:0xf bank_mask:0xf bound_ctrl:1
	v_mul_f32_e32 v13, v73, v13
	v_fmac_f32_e32 v10, v28, v58
	v_add_f32_dpp v15, v118, v118 row_half_mirror row_mask:0xf bank_mask:0x5 bound_ctrl:1
	v_fmac_f32_e32 v11, v29, v58
	v_mul_f32_e32 v61, v46, v10
	v_fmac_f32_e32 v12, v30, v58
	v_fmac_f32_e32 v61, v47, v11
	v_fmac_f32_e32 v13, v31, v58
	v_fmac_f32_e32 v61, v48, v12
	v_fmac_f32_e32 v61, v49, v13
	ds_read_b128 v[24:27], v0 offset:3968
	ds_read_b128 v[42:45], v0 offset:4992
	ds_read_b128 v[66:69], v0 offset:6016
	ds_read_b32 v56, v1 offset:6560
	ds_write_b128 v2, v[114:117] offset:16
	s_waitcnt vmcnt(10)
	ds_write_b128 v119, v[82:85] offset:2048
	s_waitcnt vmcnt(9)
	v_lshlrev_b32_e32 v36, 16, v36
	s_waitcnt lgkmcnt(11)
	v_mul_f32_e32 v10, v74, v10
	v_add_f32_dpp v61, v61, v61 quad_perm:[1,0,3,2] row_mask:0xf bank_mask:0xf bound_ctrl:1
	v_mul_f32_e32 v11, v75, v11
	v_mul_f32_e32 v12, v76, v12
	v_add_f32_dpp v61, v61, v61 quad_perm:[2,3,0,1] row_mask:0xf bank_mask:0xf bound_ctrl:1
	v_mul_f32_e32 v13, v77, v13
	v_fmac_f32_e32 v10, v32, v60
	v_add_f32_dpp v16, v61, v61 row_half_mirror row_mask:0xf bank_mask:0x5 bound_ctrl:1
	v_fmac_f32_e32 v11, v33, v60
	v_mul_f32_e32 v118, v50, v10
	v_fmac_f32_e32 v12, v34, v60
	v_fmac_f32_e32 v118, v51, v11
	v_fmac_f32_e32 v13, v35, v60
	v_fmac_f32_e32 v118, v52, v12
	v_fmac_f32_e32 v118, v53, v13
	ds_read_b128 v[28:31], v0 offset:4096
	ds_read_b128 v[46:49], v0 offset:5120
	ds_read_b128 v[70:73], v0 offset:6144
	ds_read_b32 v58, v1 offset:6592
	s_nop 0
	ds_write_b32 v4, v36 offset:3072
	s_waitcnt lgkmcnt(12)
	v_mul_f32_e32 v10, v62, v10
	v_add_f32_dpp v118, v118, v118 quad_perm:[1,0,3,2] row_mask:0xf bank_mask:0xf bound_ctrl:1
	v_mul_f32_e32 v11, v63, v11
	v_mul_f32_e32 v12, v64, v12
	v_add_f32_dpp v118, v118, v118 quad_perm:[2,3,0,1] row_mask:0xf bank_mask:0xf bound_ctrl:1
	v_mul_f32_e32 v13, v65, v13
	v_fmac_f32_e32 v10, v20, v54
	v_add_f32_dpp v17, v118, v118 row_half_mirror row_mask:0xf bank_mask:0x5 bound_ctrl:1
	v_fmac_f32_e32 v11, v21, v54
	v_mul_f32_e32 v61, v38, v10
	v_fmac_f32_e32 v12, v22, v54
	v_fmac_f32_e32 v61, v39, v11
	v_fmac_f32_e32 v13, v23, v54
	v_fmac_f32_e32 v61, v40, v12
	v_fmac_f32_e32 v61, v41, v13
	ds_read_b128 v[32:35], v0 offset:4224
	ds_read_b128 v[50:53], v0 offset:5248
	ds_read_b128 v[74:77], v0 offset:6272
	ds_read_b32 v60, v1 offset:6624
	global_load_dwordx4 v[78:81], v5, s[94:95]
	global_load_dwordx4 v[82:85], v8, s[94:95]
	global_load_ushort v36, v6, s[94:95]
	v_add_u32_e32 v5, v5, v9
	v_add_u32_e32 v8, 0x3180, v8
	v_add_u32_e32 v6, 0x10000, v6
	s_waitcnt lgkmcnt(11)
	v_mul_f32_e32 v10, v66, v10
	v_add_f32_dpp v61, v61, v61 quad_perm:[1,0,3,2] row_mask:0xf bank_mask:0xf bound_ctrl:1
	v_mul_f32_e32 v11, v67, v11
	v_mul_f32_e32 v12, v68, v12
	v_add_f32_dpp v61, v61, v61 quad_perm:[2,3,0,1] row_mask:0xf bank_mask:0xf bound_ctrl:1
	v_mul_f32_e32 v13, v69, v13
	v_fmac_f32_e32 v10, v24, v56
	v_add_f32_dpp v14, v61, v61 row_half_mirror row_mask:0xf bank_mask:0xa bound_ctrl:1
	v_fmac_f32_e32 v11, v25, v56
	v_mul_f32_e32 v118, v42, v10
	v_fmac_f32_e32 v12, v26, v56
	v_fmac_f32_e32 v118, v43, v11
	v_fmac_f32_e32 v13, v27, v56
	v_fmac_f32_e32 v118, v44, v12
	v_fmac_f32_e32 v118, v45, v13
	ds_read_b128 v[20:23], v0 offset:0
	ds_read_b128 v[38:41], v0 offset:1024
	ds_read_b128 v[62:65], v0 offset:2048
	ds_read_b32 v54, v1 offset:3072
	s_waitcnt lgkmcnt(9)
	v_mul_f32_e32 v10, v70, v10
	v_add_f32_dpp v118, v118, v118 quad_perm:[1,0,3,2] row_mask:0xf bank_mask:0xf bound_ctrl:1
	v_mul_f32_e32 v11, v71, v11
	v_mul_f32_e32 v12, v72, v12
	v_add_f32_dpp v118, v118, v118 quad_perm:[2,3,0,1] row_mask:0xf bank_mask:0xf bound_ctrl:1
	v_mul_f32_e32 v13, v73, v13
	v_fmac_f32_e32 v10, v28, v58
	v_add_f32_dpp v15, v118, v118 row_half_mirror row_mask:0xf bank_mask:0xa bound_ctrl:1
	v_fmac_f32_e32 v11, v29, v58
	v_mul_f32_e32 v61, v46, v10
	v_fmac_f32_e32 v12, v30, v58
	v_fmac_f32_e32 v61, v47, v11
	v_fmac_f32_e32 v13, v31, v58
	v_fmac_f32_e32 v61, v48, v12
	v_fmac_f32_e32 v61, v49, v13
	ds_read_b128 v[24:27], v0 offset:128
	ds_read_b128 v[42:45], v0 offset:1152
	ds_read_b128 v[66:69], v0 offset:2176
	ds_read_b32 v56, v1 offset:3104
	s_waitcnt lgkmcnt(8)
	v_mul_f32_e32 v10, v74, v10
	v_add_f32_dpp v61, v61, v61 quad_perm:[1,0,3,2] row_mask:0xf bank_mask:0xf bound_ctrl:1
	v_mul_f32_e32 v11, v75, v11
	v_mul_f32_e32 v12, v76, v12
	v_add_f32_dpp v61, v61, v61 quad_perm:[2,3,0,1] row_mask:0xf bank_mask:0xf bound_ctrl:1
	v_mul_f32_e32 v13, v77, v13
	v_fmac_f32_e32 v10, v32, v60
	v_add_f32_dpp v16, v61, v61 row_half_mirror row_mask:0xf bank_mask:0xa bound_ctrl:1
	v_fmac_f32_e32 v11, v33, v60
	v_mul_f32_e32 v118, v50, v10
	v_fmac_f32_e32 v12, v34, v60
	v_fmac_f32_e32 v118, v51, v11
	v_fmac_f32_e32 v13, v35, v60
	v_fmac_f32_e32 v118, v52, v12
	v_fmac_f32_e32 v118, v53, v13
	ds_read_b128 v[28:31], v0 offset:256
	ds_read_b128 v[46:49], v0 offset:1280
	ds_read_b128 v[70:73], v0 offset:2304
	ds_read_b32 v58, v1 offset:3136
	s_nop 1
	v_add_f32_dpp v118, v118, v118 quad_perm:[1,0,3,2] row_mask:0xf bank_mask:0xf bound_ctrl:1
	s_nop 1
	v_add_f32_dpp v118, v118, v118 quad_perm:[2,3,0,1] row_mask:0xf bank_mask:0xf bound_ctrl:1
	s_nop 1
	v_add_f32_dpp v17, v118, v118 row_half_mirror row_mask:0xf bank_mask:0xa bound_ctrl:1
	v_mov_b32_e32 v118, 0
	v_cndmask_b32_e64 v18, v14, v15, s[6:7]
	v_cndmask_b32_e64 v18, v18, v16, s[8:9]
	v_cndmask_b32_e64 v18, v18, v17, s[10:11]
	v_cvt_pk_bf16_f32 v19, v18, v18
	ds_write_b16 v121, v19 offset:7040
	v_add_u32_e32 v121, 0x200, v121
	s_and_b32 s24, s12, 15
	s_cmp_eq_u32 s24, 1
	s_cbranch_scc0 .Lls1_8_noflush
	ds_read_b128 v[124:127], v122 offset:6656
	s_waitcnt lgkmcnt(0)
	global_store_dwordx4 v7, v[124:127], s[94:95]
	v_add_u32_e32 v7, 0x20000, v7
	s_nop 0
	ds_read_b128 v[124:127], v122 offset:7680
	s_waitcnt lgkmcnt(0)
	global_store_dwordx4 v7, v[124:127], s[94:95]
	v_add_u32_e32 v7, 0x20000, v7
	s_nop 0
	ds_read_b128 v[124:127], v122 offset:8704
	s_waitcnt lgkmcnt(0)
	global_store_dwordx4 v7, v[124:127], s[94:95]
	v_add_u32_e32 v7, 0x20000, v7
	s_nop 0
	ds_read_b128 v[124:127], v122 offset:9728
	s_waitcnt lgkmcnt(0)
	global_store_dwordx4 v7, v[124:127], s[94:95]
	v_add_u32_e32 v7, 0x20000, v7
	s_nop 0
	ds_read_b128 v[124:127], v122 offset:10752
	s_waitcnt lgkmcnt(0)
	global_store_dwordx4 v7, v[124:127], s[94:95]
	v_add_u32_e32 v7, 0x20000, v7
	s_nop 0
	ds_read_b128 v[124:127], v122 offset:11776
	s_waitcnt lgkmcnt(0)
	global_store_dwordx4 v7, v[124:127], s[94:95]
	v_add_u32_e32 v7, 0x20000, v7
	s_nop 0
	ds_read_b128 v[124:127], v122 offset:12800
	s_waitcnt lgkmcnt(0)
	global_store_dwordx4 v7, v[124:127], s[94:95]
	v_add_u32_e32 v7, 0x20000, v7
	s_nop 0
	ds_read_b128 v[124:127], v122 offset:13824
	s_waitcnt lgkmcnt(0)
	global_store_dwordx4 v7, v[124:127], s[94:95]
	v_add_u32_e32 v7, 0x20000, v7
	s_nop 0
	v_subrev_u32_e32 v121, 0x2000, v121
.Lls1_8_noflush:
	s_sub_u32 s12, s12, 1
	s_cmp_lg_u32 s12, 0
	s_cbranch_scc1 .Lls1_8_loop
	global_store_dword v120, v10, s[26:27] offset:0
	global_store_dword v120, v11, s[26:27] offset:256
	global_store_dword v120, v12, s[26:27] offset:512
	global_store_dword v120, v13, s[26:27] offset:768
	s_waitcnt vmcnt(0) lgkmcnt(0)
	s_setprio 0
	s_branch .Lls_done
